# sc1 (write-through) on the 16-byte stores outside the bf16 GEMM epilogues (norms, conv, scan, GEMM<3> f32, mixers, prep): less dirty L2 to write back at phase barriers
# baseline (speedup 1.0000x reference)
.LBB0_17:
	v_ashrrev_i32_e32 v7, 31, v6
	v_lshlrev_b64 v[8:9], 12, v[6:7]
	v_lshl_add_u64 v[8:9], v[4:5], 0, v[8:9]
	global_load_dwordx4 v[16:19], v[8:9], off
	global_load_dwordx4 v[24:27], v[8:9], off offset:1024
	s_add_i32 s2, s2, s0
	v_add_u32_e32 v6, s1, v6
	s_cmpk_lt_i32 s2, 0x1000
	s_waitcnt vmcnt(1)
	v_mov_b32_e32 v30, v17
	v_mov_b32_e32 v28, v16
	s_waitcnt vmcnt(0)
	v_mov_b32_e32 v31, v25
	v_mov_b32_e32 v29, v24
	v_pk_mul_f32 v[30:31], v[30:31], v[30:31]
	v_mov_b32_e32 v32, v19
	v_pk_fma_f32 v[28:29], v[28:29], v[28:29], v[30:31]
	v_mov_b32_e32 v30, v18
	v_mov_b32_e32 v31, v26
	v_mov_b32_e32 v33, v27
	v_pk_fma_f32 v[28:29], v[30:31], v[30:31], v[28:29]
	s_nop 0
	v_pk_fma_f32 v[36:37], v[32:33], v[32:33], v[28:29]
	global_load_dwordx4 v[28:31], v[8:9], off offset:2048
	global_load_dwordx4 v[32:35], v[8:9], off offset:3072
	v_add_f32_e32 v7, v36, v37
	s_waitcnt vmcnt(1)
	v_mov_b32_e32 v40, v29
	s_waitcnt vmcnt(0)
	v_mov_b32_e32 v41, v33
	v_mov_b32_e32 v38, v28
	v_mov_b32_e32 v39, v32
	v_pk_mul_f32 v[40:41], v[40:41], v[40:41]
	v_mov_b32_e32 v42, v31
	v_pk_fma_f32 v[38:39], v[38:39], v[38:39], v[40:41]
	v_mov_b32_e32 v40, v30
	v_mov_b32_e32 v41, v34
	v_mov_b32_e32 v43, v35
	v_pk_fma_f32 v[38:39], v[40:41], v[40:41], v[38:39]
	s_nop 0
	v_pk_fma_f32 v[38:39], v[42:43], v[42:43], v[38:39]
	s_nop 0
	v_add_f32_e32 v7, v7, v38
	v_add_f32_e32 v7, v7, v39
	ds_bpermute_b32 v15, v0, v7
	s_waitcnt lgkmcnt(0)
	v_add_f32_e32 v7, v7, v15
	ds_bpermute_b32 v15, v10, v7
	s_waitcnt lgkmcnt(0)
	v_add_f32_e32 v7, v7, v15
	ds_bpermute_b32 v15, v11, v7
	s_waitcnt lgkmcnt(0)
	v_add_f32_e32 v7, v7, v15
	ds_bpermute_b32 v15, v12, v7
	s_waitcnt lgkmcnt(0)
	v_add_f32_e32 v7, v7, v15
	ds_bpermute_b32 v15, v13, v7
	s_waitcnt lgkmcnt(0)
	v_add_f32_e32 v7, v7, v15
	ds_bpermute_b32 v15, v14, v7
	s_waitcnt lgkmcnt(0)
	v_add_f32_e32 v7, v7, v15
	v_fmamk_f32 v7, v7, 0x3a800000, v178
	v_cmp_gt_f32_e32 vcc, s3, v7
	v_mul_f32_e32 v15, 0x4b800000, v7
	s_nop 0
	v_cndmask_b32_e32 v7, v7, v15, vcc
	v_rsq_f32_e32 v7, v7
	s_nop 0
	v_mul_f32_e32 v15, 0x45800000, v7
	v_cndmask_b32_e32 v36, v7, v15, vcc
	v_pk_mul_f32 v[16:17], v[16:17], v[36:37] op_sel_hi:[1,0]
	v_pk_mul_f32 v[18:19], v[18:19], v[36:37] op_sel_hi:[1,0]
	v_pk_mul_f32 v[16:17], v[44:45], v[16:17]
	v_pk_mul_f32 v[18:19], v[46:47], v[18:19]
	global_store_dwordx4 v[8:9], v[16:19], off sc1
	v_pk_mul_f32 v[20:21], v[24:25], v[36:37] op_sel_hi:[1,0]
	v_pk_mul_f32 v[22:23], v[26:27], v[36:37] op_sel_hi:[1,0]
	v_pk_mul_f32 v[60:61], v[48:49], v[20:21]
	v_pk_mul_f32 v[62:63], v[50:51], v[22:23]
	global_store_dwordx4 v[8:9], v[60:63], off offset:1024 sc1
	v_pk_mul_f32 v[20:21], v[28:29], v[36:37] op_sel_hi:[1,0]
	v_pk_mul_f32 v[22:23], v[30:31], v[36:37] op_sel_hi:[1,0]
	v_pk_mul_f32 v[16:17], v[20:21], v[52:53]
	v_pk_mul_f32 v[18:19], v[22:23], v[54:55]
	global_store_dwordx4 v[8:9], v[16:19], off offset:2048 sc1
	v_pk_mul_f32 v[20:21], v[32:33], v[36:37] op_sel_hi:[1,0]
	v_pk_mul_f32 v[22:23], v[34:35], v[36:37] op_sel_hi:[1,0]
	v_pk_mul_f32 v[60:61], v[20:21], v[56:57]
	v_pk_mul_f32 v[62:63], v[22:23], v[58:59]
	global_store_dwordx4 v[8:9], v[60:63], off offset:3072 sc1
	s_cbranch_scc1 .LBB0_17

.Lg24_loop:
	s_waitcnt lgkmcnt(4)
	v_mfma_f32_32x32x16_bf16 v[114:129], v[130:133], v[164:167], v[114:129]
	ds_read_b128 v[172:175], v204 offset:0
	s_waitcnt lgkmcnt(4)
	v_mfma_f32_32x32x16_bf16 v[98:113], v[130:133], v[168:171], v[98:113]
	ds_read_b128 v[192:195], v208 offset:0
	s_add_u32 m0, s14, 0x1a020
	s_add_u32 s12, s12, 0x40000
	s_addc_u32 s13, s13, 0
	global_load_lds_dwordx4 v155, s[12:13]
	s_waitcnt lgkmcnt(4)
	v_mfma_f32_32x32x16_bf16 v[82:97], v[134:137], v[164:167], v[82:97]
	ds_read_b128 v[200:203], v208 offset:4096
	v_mfma_f32_32x32x16_bf16 v[66:81], v[134:137], v[168:171], v[66:81]
	ds_read_b128 v[180:183], v204 offset:4096
	s_add_u32 m0, s14, 0x1c020
	s_add_u32 s12, s12, 0x40000
	s_addc_u32 s13, s13, 0
	global_load_lds_dwordx4 v155, s[12:13]
	s_waitcnt lgkmcnt(5)
	v_mfma_f32_32x32x16_bf16 v[50:65], v[156:159], v[164:167], v[50:65]
	ds_read_b128 v[184:187], v204 offset:8192
	v_mfma_f32_32x32x16_bf16 v[34:49], v[156:159], v[168:171], v[34:49]
	ds_read_b128 v[188:191], v204 offset:12288
	s_add_u32 m0, s14, 0x1e020
	s_add_u32 s12, s12, 0x40000
	s_addc_u32 s13, s13, 0
	global_load_lds_dwordx4 v155, s[12:13]
	s_add_u32 s4, s4, 0x80
	s_addc_u32 s5, s5, 0
	s_waitcnt lgkmcnt(6)
	v_mfma_f32_32x32x16_bf16 v[18:33], v[160:163], v[164:167], v[18:33]
	v_mfma_f32_32x32x16_bf16 v[2:17], v[160:163], v[168:171], v[2:17]
	s_waitcnt lgkmcnt(4)
	v_mfma_f32_32x32x16_bf16 v[114:129], v[172:175], v[192:195], v[114:129]
	ds_read_b128 v[130:133], v205 offset:0
	s_waitcnt lgkmcnt(4)
	v_mfma_f32_32x32x16_bf16 v[98:113], v[172:175], v[200:203], v[98:113]
	ds_read_b128 v[164:167], v209 offset:0
	s_waitcnt lgkmcnt(4)
	v_mfma_f32_32x32x16_bf16 v[82:97], v[180:183], v[192:195], v[82:97]
	ds_read_b128 v[168:171], v209 offset:4096
	v_mfma_f32_32x32x16_bf16 v[66:81], v[180:183], v[200:203], v[66:81]
	ds_read_b128 v[134:137], v205 offset:4096
	s_waitcnt lgkmcnt(5)
	v_mfma_f32_32x32x16_bf16 v[50:65], v[184:187], v[192:195], v[50:65]
	ds_read_b128 v[156:159], v205 offset:8192
	v_mfma_f32_32x32x16_bf16 v[34:49], v[184:187], v[200:203], v[34:49]
	ds_read_b128 v[160:163], v205 offset:12288
	s_waitcnt lgkmcnt(6)
	v_mfma_f32_32x32x16_bf16 v[18:33], v[188:191], v[192:195], v[18:33]
	v_mfma_f32_32x32x16_bf16 v[2:17], v[188:191], v[200:203], v[2:17]
	s_waitcnt lgkmcnt(4)
	v_mfma_f32_32x32x16_bf16 v[114:129], v[130:133], v[164:167], v[114:129]
	ds_read_b128 v[172:175], v206 offset:0
	ds_read_b128 v[192:195], v210 offset:0
	s_waitcnt lgkmcnt(5)
	v_mfma_f32_32x32x16_bf16 v[98:113], v[130:133], v[168:171], v[98:113]
	ds_read_b128 v[200:203], v210 offset:4096
	ds_read_b128 v[180:183], v206 offset:4096
	s_waitcnt lgkmcnt(6)
	v_mfma_f32_32x32x16_bf16 v[82:97], v[134:137], v[164:167], v[82:97]
	ds_read_b128 v[184:187], v206 offset:8192
	ds_read_b128 v[188:191], v206 offset:12288
	v_mfma_f32_32x32x16_bf16 v[66:81], v[134:137], v[168:171], v[66:81]
	s_waitcnt lgkmcnt(7)
	v_mfma_f32_32x32x16_bf16 v[50:65], v[156:159], v[164:167], v[50:65]
	v_mfma_f32_32x32x16_bf16 v[34:49], v[156:159], v[168:171], v[34:49]
	s_waitcnt lgkmcnt(6)
	v_mfma_f32_32x32x16_bf16 v[18:33], v[160:163], v[164:167], v[18:33]
	v_mfma_f32_32x32x16_bf16 v[2:17], v[160:163], v[168:171], v[2:17]
	s_waitcnt vmcnt(0) lgkmcnt(0)
	s_barrier
	v_mfma_f32_32x32x16_bf16 v[114:129], v[172:175], v[192:195], v[114:129]
	ds_read_b128 v[130:133], v177 offset:32768
	s_add_u32 m0, s14, 0x20
	s_add_u32 s12, s1, s4
	s_addc_u32 s13, s3, s5
	global_load_lds_dwordx4 v155, s[12:13]
	v_mfma_f32_32x32x16_bf16 v[98:113], v[172:175], v[200:203], v[98:113]
	ds_read_b128 v[164:167], v207 offset:32768
	s_add_u32 m0, s14, 0x2020
	s_add_u32 s12, s12, 0x40000
	s_addc_u32 s13, s13, 0
	global_load_lds_dwordx4 v155, s[12:13]
	v_mfma_f32_32x32x16_bf16 v[82:97], v[180:183], v[192:195], v[82:97]
	ds_read_b128 v[168:171], v207 offset:36864
	s_add_u32 m0, s14, 0x4020
	s_add_u32 s12, s12, 0x40000
	s_addc_u32 s13, s13, 0
	global_load_lds_dwordx4 v155, s[12:13]
	v_mfma_f32_32x32x16_bf16 v[66:81], v[180:183], v[200:203], v[66:81]
	ds_read_b128 v[134:137], v177 offset:36864
	s_add_u32 m0, s14, 0x6020
	s_add_u32 s12, s12, 0x40000
	s_addc_u32 s13, s13, 0
	global_load_lds_dwordx4 v155, s[12:13]
	v_mfma_f32_32x32x16_bf16 v[50:65], v[184:187], v[192:195], v[50:65]
	ds_read_b128 v[156:159], v177 offset:40960
	s_add_u32 m0, s14, 0x10020
	s_add_u32 s12, s9, s4
	s_addc_u32 s13, s10, s5
	global_load_lds_dwordx4 v155, s[12:13]
	v_mfma_f32_32x32x16_bf16 v[34:49], v[184:187], v[200:203], v[34:49]
	ds_read_b128 v[160:163], v177 offset:45056
	v_mfma_f32_32x32x16_bf16 v[18:33], v[188:191], v[192:195], v[18:33]
	v_mfma_f32_32x32x16_bf16 v[2:17], v[188:191], v[200:203], v[2:17]
	s_waitcnt lgkmcnt(4)
	v_mfma_f32_32x32x16_bf16 v[114:129], v[130:133], v[164:167], v[114:129]
	ds_read_b128 v[172:175], v204 offset:32768
	s_waitcnt lgkmcnt(4)
	v_mfma_f32_32x32x16_bf16 v[98:113], v[130:133], v[168:171], v[98:113]
	ds_read_b128 v[192:195], v208 offset:32768
	s_add_u32 m0, s14, 0x12020
	s_add_u32 s12, s12, 0x40000
	s_addc_u32 s13, s13, 0
	global_load_lds_dwordx4 v155, s[12:13]
	s_waitcnt lgkmcnt(4)
	v_mfma_f32_32x32x16_bf16 v[82:97], v[134:137], v[164:167], v[82:97]
	ds_read_b128 v[200:203], v208 offset:36864
	v_mfma_f32_32x32x16_bf16 v[66:81], v[134:137], v[168:171], v[66:81]
	ds_read_b128 v[180:183], v204 offset:36864
	s_add_u32 m0, s14, 0x14020
	s_add_u32 s12, s12, 0x40000
	s_addc_u32 s13, s13, 0
	global_load_lds_dwordx4 v155, s[12:13]
	s_waitcnt lgkmcnt(5)
	v_mfma_f32_32x32x16_bf16 v[50:65], v[156:159], v[164:167], v[50:65]
	ds_read_b128 v[184:187], v204 offset:40960
	v_mfma_f32_32x32x16_bf16 v[34:49], v[156:159], v[168:171], v[34:49]
	ds_read_b128 v[188:191], v204 offset:45056
	s_add_u32 m0, s14, 0x16020
	s_add_u32 s12, s12, 0x40000
	s_addc_u32 s13, s13, 0
	global_load_lds_dwordx4 v155, s[12:13]
	s_add_u32 s4, s4, 0x80
	s_addc_u32 s5, s5, 0
	s_waitcnt lgkmcnt(6)
	v_mfma_f32_32x32x16_bf16 v[18:33], v[160:163], v[164:167], v[18:33]
	v_mfma_f32_32x32x16_bf16 v[2:17], v[160:163], v[168:171], v[2:17]
	s_waitcnt lgkmcnt(4)
	v_mfma_f32_32x32x16_bf16 v[114:129], v[172:175], v[192:195], v[114:129]
	ds_read_b128 v[130:133], v205 offset:32768
	s_waitcnt lgkmcnt(4)
	v_mfma_f32_32x32x16_bf16 v[98:113], v[172:175], v[200:203], v[98:113]
	ds_read_b128 v[164:167], v209 offset:32768
	s_waitcnt lgkmcnt(4)
	v_mfma_f32_32x32x16_bf16 v[82:97], v[180:183], v[192:195], v[82:97]
	ds_read_b128 v[168:171], v209 offset:36864
	v_mfma_f32_32x32x16_bf16 v[66:81], v[180:183], v[200:203], v[66:81]
	ds_read_b128 v[134:137], v205 offset:36864
	s_waitcnt lgkmcnt(5)
	v_mfma_f32_32x32x16_bf16 v[50:65], v[184:187], v[192:195], v[50:65]
	ds_read_b128 v[156:159], v205 offset:40960
	v_mfma_f32_32x32x16_bf16 v[34:49], v[184:187], v[200:203], v[34:49]
	ds_read_b128 v[160:163], v205 offset:45056
	s_waitcnt lgkmcnt(6)
	v_mfma_f32_32x32x16_bf16 v[18:33], v[188:191], v[192:195], v[18:33]
	v_mfma_f32_32x32x16_bf16 v[2:17], v[188:191], v[200:203], v[2:17]
	s_waitcnt lgkmcnt(4)
	v_mfma_f32_32x32x16_bf16 v[114:129], v[130:133], v[164:167], v[114:129]
	ds_read_b128 v[172:175], v206 offset:32768
	ds_read_b128 v[192:195], v210 offset:32768
	s_waitcnt lgkmcnt(5)
	v_mfma_f32_32x32x16_bf16 v[98:113], v[130:133], v[168:171], v[98:113]
	ds_read_b128 v[200:203], v210 offset:36864
	ds_read_b128 v[180:183], v206 offset:36864
	s_waitcnt lgkmcnt(6)
	v_mfma_f32_32x32x16_bf16 v[82:97], v[134:137], v[164:167], v[82:97]
	ds_read_b128 v[184:187], v206 offset:40960
	ds_read_b128 v[188:191], v206 offset:45056
	v_mfma_f32_32x32x16_bf16 v[66:81], v[134:137], v[168:171], v[66:81]
	s_waitcnt lgkmcnt(7)
	v_mfma_f32_32x32x16_bf16 v[50:65], v[156:159], v[164:167], v[50:65]
	v_mfma_f32_32x32x16_bf16 v[34:49], v[156:159], v[168:171], v[34:49]
	s_waitcnt lgkmcnt(6)
	v_mfma_f32_32x32x16_bf16 v[18:33], v[160:163], v[164:167], v[18:33]
	v_mfma_f32_32x32x16_bf16 v[2:17], v[160:163], v[168:171], v[2:17]
	s_waitcnt vmcnt(0) lgkmcnt(0)
	s_barrier
	v_mfma_f32_32x32x16_bf16 v[114:129], v[172:175], v[192:195], v[114:129]
	ds_read_b128 v[130:133], v177 offset:0
	s_add_u32 m0, s14, 0x8020
	s_add_u32 s12, s1, s4
	s_addc_u32 s13, s3, s5
	global_load_lds_dwordx4 v155, s[12:13]
	v_mfma_f32_32x32x16_bf16 v[98:113], v[172:175], v[200:203], v[98:113]
	ds_read_b128 v[164:167], v207 offset:0
	s_add_u32 m0, s14, 0xa020
	s_add_u32 s12, s12, 0x40000
	s_addc_u32 s13, s13, 0
	global_load_lds_dwordx4 v155, s[12:13]
	v_mfma_f32_32x32x16_bf16 v[82:97], v[180:183], v[192:195], v[82:97]
	ds_read_b128 v[168:171], v207 offset:4096
	s_add_u32 m0, s14, 0xc020
	s_add_u32 s12, s12, 0x40000
	s_addc_u32 s13, s13, 0
	global_load_lds_dwordx4 v155, s[12:13]
	v_mfma_f32_32x32x16_bf16 v[66:81], v[180:183], v[200:203], v[66:81]
	ds_read_b128 v[134:137], v177 offset:4096
	s_add_u32 m0, s14, 0xe020
	s_add_u32 s12, s12, 0x40000
	s_addc_u32 s13, s13, 0
	global_load_lds_dwordx4 v155, s[12:13]
	v_mfma_f32_32x32x16_bf16 v[50:65], v[184:187], v[192:195], v[50:65]
	ds_read_b128 v[156:159], v177 offset:8192
	s_add_u32 m0, s14, 0x18020
	s_add_u32 s12, s9, s4
	s_addc_u32 s13, s10, s5
	global_load_lds_dwordx4 v155, s[12:13]
	v_mfma_f32_32x32x16_bf16 v[34:49], v[184:187], v[200:203], v[34:49]
	ds_read_b128 v[160:163], v177 offset:12288
	v_mfma_f32_32x32x16_bf16 v[18:33], v[188:191], v[192:195], v[18:33]
	v_mfma_f32_32x32x16_bf16 v[2:17], v[188:191], v[200:203], v[2:17]
	s_sub_u32 s11, s11, 1
	s_cmp_lg_u32 s11, 0
	s_cbranch_scc1 .Lg24_loop
	s_waitcnt lgkmcnt(4)
	v_mfma_f32_32x32x16_bf16 v[114:129], v[130:133], v[164:167], v[114:129]
	ds_read_b128 v[172:175], v204 offset:0
	s_waitcnt lgkmcnt(4)
	v_mfma_f32_32x32x16_bf16 v[98:113], v[130:133], v[168:171], v[98:113]
	ds_read_b128 v[192:195], v208 offset:0
	s_add_u32 m0, s14, 0x1a020
	s_add_u32 s12, s12, 0x40000
	s_addc_u32 s13, s13, 0
	global_load_lds_dwordx4 v155, s[12:13]
	s_waitcnt lgkmcnt(4)
	v_mfma_f32_32x32x16_bf16 v[82:97], v[134:137], v[164:167], v[82:97]
	ds_read_b128 v[200:203], v208 offset:4096
	v_mfma_f32_32x32x16_bf16 v[66:81], v[134:137], v[168:171], v[66:81]
	ds_read_b128 v[180:183], v204 offset:4096
	s_add_u32 m0, s14, 0x1c020
	s_add_u32 s12, s12, 0x40000
	s_addc_u32 s13, s13, 0
	global_load_lds_dwordx4 v155, s[12:13]
	s_waitcnt lgkmcnt(5)
	v_mfma_f32_32x32x16_bf16 v[50:65], v[156:159], v[164:167], v[50:65]
	ds_read_b128 v[184:187], v204 offset:8192
	v_mfma_f32_32x32x16_bf16 v[34:49], v[156:159], v[168:171], v[34:49]
	ds_read_b128 v[188:191], v204 offset:12288
	s_add_u32 m0, s14, 0x1e020
	s_add_u32 s12, s12, 0x40000
	s_addc_u32 s13, s13, 0
	global_load_lds_dwordx4 v155, s[12:13]
	s_add_u32 s4, s4, 0x80
	s_addc_u32 s5, s5, 0
	s_waitcnt lgkmcnt(6)
	v_mfma_f32_32x32x16_bf16 v[18:33], v[160:163], v[164:167], v[18:33]
	v_mfma_f32_32x32x16_bf16 v[2:17], v[160:163], v[168:171], v[2:17]
	s_waitcnt lgkmcnt(4)
	v_mfma_f32_32x32x16_bf16 v[114:129], v[172:175], v[192:195], v[114:129]
	ds_read_b128 v[130:133], v205 offset:0
	s_waitcnt lgkmcnt(4)
	v_mfma_f32_32x32x16_bf16 v[98:113], v[172:175], v[200:203], v[98:113]
	ds_read_b128 v[164:167], v209 offset:0
	s_waitcnt lgkmcnt(4)
	v_mfma_f32_32x32x16_bf16 v[82:97], v[180:183], v[192:195], v[82:97]
	ds_read_b128 v[168:171], v209 offset:4096
	v_mfma_f32_32x32x16_bf16 v[66:81], v[180:183], v[200:203], v[66:81]
	ds_read_b128 v[134:137], v205 offset:4096
	s_waitcnt lgkmcnt(5)
	v_mfma_f32_32x32x16_bf16 v[50:65], v[184:187], v[192:195], v[50:65]
	ds_read_b128 v[156:159], v205 offset:8192
	v_mfma_f32_32x32x16_bf16 v[34:49], v[184:187], v[200:203], v[34:49]
	ds_read_b128 v[160:163], v205 offset:12288
	s_waitcnt lgkmcnt(6)
	v_mfma_f32_32x32x16_bf16 v[18:33], v[188:191], v[192:195], v[18:33]
	v_mfma_f32_32x32x16_bf16 v[2:17], v[188:191], v[200:203], v[2:17]
	s_waitcnt lgkmcnt(4)
	v_mfma_f32_32x32x16_bf16 v[114:129], v[130:133], v[164:167], v[114:129]
	ds_read_b128 v[172:175], v206 offset:0
	ds_read_b128 v[192:195], v210 offset:0
	s_waitcnt lgkmcnt(5)
	v_mfma_f32_32x32x16_bf16 v[98:113], v[130:133], v[168:171], v[98:113]
	ds_read_b128 v[200:203], v210 offset:4096
	ds_read_b128 v[180:183], v206 offset:4096
	s_waitcnt lgkmcnt(6)
	v_mfma_f32_32x32x16_bf16 v[82:97], v[134:137], v[164:167], v[82:97]
	ds_read_b128 v[184:187], v206 offset:8192
	ds_read_b128 v[188:191], v206 offset:12288
	v_mfma_f32_32x32x16_bf16 v[66:81], v[134:137], v[168:171], v[66:81]
	s_waitcnt lgkmcnt(7)
	v_mfma_f32_32x32x16_bf16 v[50:65], v[156:159], v[164:167], v[50:65]
	v_mfma_f32_32x32x16_bf16 v[34:49], v[156:159], v[168:171], v[34:49]
	s_waitcnt lgkmcnt(6)
	v_mfma_f32_32x32x16_bf16 v[18:33], v[160:163], v[164:167], v[18:33]
	v_mfma_f32_32x32x16_bf16 v[2:17], v[160:163], v[168:171], v[2:17]
	s_waitcnt vmcnt(0) lgkmcnt(0)
	s_barrier
	v_mfma_f32_32x32x16_bf16 v[114:129], v[172:175], v[192:195], v[114:129]
	ds_read_b128 v[130:133], v177 offset:32768
	v_mfma_f32_32x32x16_bf16 v[98:113], v[172:175], v[200:203], v[98:113]
	ds_read_b128 v[164:167], v207 offset:32768
	v_mfma_f32_32x32x16_bf16 v[82:97], v[180:183], v[192:195], v[82:97]
	ds_read_b128 v[168:171], v207 offset:36864
	v_mfma_f32_32x32x16_bf16 v[66:81], v[180:183], v[200:203], v[66:81]
	ds_read_b128 v[134:137], v177 offset:36864
	v_mfma_f32_32x32x16_bf16 v[50:65], v[184:187], v[192:195], v[50:65]
	ds_read_b128 v[156:159], v177 offset:40960
	v_mfma_f32_32x32x16_bf16 v[34:49], v[184:187], v[200:203], v[34:49]
	ds_read_b128 v[160:163], v177 offset:45056
	v_mfma_f32_32x32x16_bf16 v[18:33], v[188:191], v[192:195], v[18:33]
	v_mfma_f32_32x32x16_bf16 v[2:17], v[188:191], v[200:203], v[2:17]
	s_waitcnt lgkmcnt(4)
	v_mfma_f32_32x32x16_bf16 v[114:129], v[130:133], v[164:167], v[114:129]
	ds_read_b128 v[172:175], v204 offset:32768
	s_waitcnt lgkmcnt(4)
	v_mfma_f32_32x32x16_bf16 v[98:113], v[130:133], v[168:171], v[98:113]
	ds_read_b128 v[192:195], v208 offset:32768
	s_waitcnt lgkmcnt(4)
	v_mfma_f32_32x32x16_bf16 v[82:97], v[134:137], v[164:167], v[82:97]
	ds_read_b128 v[200:203], v208 offset:36864
	v_mfma_f32_32x32x16_bf16 v[66:81], v[134:137], v[168:171], v[66:81]
	ds_read_b128 v[180:183], v204 offset:36864
	s_waitcnt lgkmcnt(5)
	v_mfma_f32_32x32x16_bf16 v[50:65], v[156:159], v[164:167], v[50:65]
	ds_read_b128 v[184:187], v204 offset:40960
	v_mfma_f32_32x32x16_bf16 v[34:49], v[156:159], v[168:171], v[34:49]
	ds_read_b128 v[188:191], v204 offset:45056
	s_waitcnt lgkmcnt(6)
	v_mfma_f32_32x32x16_bf16 v[18:33], v[160:163], v[164:167], v[18:33]
	v_mfma_f32_32x32x16_bf16 v[2:17], v[160:163], v[168:171], v[2:17]
	s_waitcnt lgkmcnt(4)
	v_mfma_f32_32x32x16_bf16 v[114:129], v[172:175], v[192:195], v[114:129]
	ds_read_b128 v[130:133], v205 offset:32768
	s_waitcnt lgkmcnt(4)
	v_mfma_f32_32x32x16_bf16 v[98:113], v[172:175], v[200:203], v[98:113]
	ds_read_b128 v[164:167], v209 offset:32768
	s_waitcnt lgkmcnt(4)
	v_mfma_f32_32x32x16_bf16 v[82:97], v[180:183], v[192:195], v[82:97]
	ds_read_b128 v[168:171], v209 offset:36864
	v_mfma_f32_32x32x16_bf16 v[66:81], v[180:183], v[200:203], v[66:81]
	ds_read_b128 v[134:137], v205 offset:36864
	s_waitcnt lgkmcnt(5)
	v_mfma_f32_32x32x16_bf16 v[50:65], v[184:187], v[192:195], v[50:65]
	ds_read_b128 v[156:159], v205 offset:40960
	v_mfma_f32_32x32x16_bf16 v[34:49], v[184:187], v[200:203], v[34:49]
	ds_read_b128 v[160:163], v205 offset:45056
	s_waitcnt lgkmcnt(6)
	v_mfma_f32_32x32x16_bf16 v[18:33], v[188:191], v[192:195], v[18:33]
	v_mfma_f32_32x32x16_bf16 v[2:17], v[188:191], v[200:203], v[2:17]
	s_waitcnt lgkmcnt(4)
	v_mfma_f32_32x32x16_bf16 v[114:129], v[130:133], v[164:167], v[114:129]
	ds_read_b128 v[172:175], v206 offset:32768
	ds_read_b128 v[192:195], v210 offset:32768
	s_waitcnt lgkmcnt(5)
	v_mfma_f32_32x32x16_bf16 v[98:113], v[130:133], v[168:171], v[98:113]
	ds_read_b128 v[200:203], v210 offset:36864
	ds_read_b128 v[180:183], v206 offset:36864
	s_waitcnt lgkmcnt(6)
	v_mfma_f32_32x32x16_bf16 v[82:97], v[134:137], v[164:167], v[82:97]
	ds_read_b128 v[184:187], v206 offset:40960
	ds_read_b128 v[188:191], v206 offset:45056
	v_mfma_f32_32x32x16_bf16 v[66:81], v[134:137], v[168:171], v[66:81]
	s_waitcnt lgkmcnt(7)
	v_mfma_f32_32x32x16_bf16 v[50:65], v[156:159], v[164:167], v[50:65]
	v_mfma_f32_32x32x16_bf16 v[34:49], v[156:159], v[168:171], v[34:49]
	s_waitcnt lgkmcnt(6)
	v_mfma_f32_32x32x16_bf16 v[18:33], v[160:163], v[164:167], v[18:33]
	v_mfma_f32_32x32x16_bf16 v[2:17], v[160:163], v[168:171], v[2:17]
	s_waitcnt vmcnt(0) lgkmcnt(0)
	s_barrier
	v_mfma_f32_32x32x16_bf16 v[114:129], v[172:175], v[192:195], v[114:129]
	v_mfma_f32_32x32x16_bf16 v[98:113], v[172:175], v[200:203], v[98:113]
	v_mfma_f32_32x32x16_bf16 v[82:97], v[180:183], v[192:195], v[82:97]
	v_mfma_f32_32x32x16_bf16 v[66:81], v[180:183], v[200:203], v[66:81]
	v_mfma_f32_32x32x16_bf16 v[50:65], v[184:187], v[192:195], v[50:65]
	v_mfma_f32_32x32x16_bf16 v[34:49], v[184:187], v[200:203], v[34:49]
	v_mfma_f32_32x32x16_bf16 v[18:33], v[188:191], v[192:195], v[18:33]
	v_mfma_f32_32x32x16_bf16 v[2:17], v[188:191], v[200:203], v[2:17]
	s_setprio 0
	v_add_u32_e32 v130, s0, v149
	v_ashrrev_i32_e32 v131, 31, v130
	v_lshrrev_b32_e32 v155, 18, v131
	v_add_u32_e32 v0, v130, v155
	v_ashrrev_i32_e32 v0, 14, v0
	v_mul_i32_i24_e32 v133, 0x4000, v0
	v_sub_u32_e32 v133, v130, v133
	v_add_u32_e32 v156, 0x100, v133
	v_mul_hi_i32_i24_e32 v137, 0x4100, v0
	v_mul_i32_i24_e32 v136, 0x4100, v0
	v_ashrrev_i32_e32 v157, 31, v156
	v_lshl_add_u64 v[136:137], v[136:137], 0, v[156:157]
	v_mov_b32_e32 v156, v179
	s_waitcnt vmcnt(0)
	s_barrier
	v_mul_i32_i24_e32 v134, 0xc00, v0
	v_readlane_b32 s40, v251, 2
	v_and_b32_e32 v0, 31, v156
	v_bfe_u32 v133, v156, 5, 1
	v_mul_u32_u24_e32 v133, 0x240, v133
	v_lshlrev_b32_e32 v0, 2, v0
	v_add3_u32 v0, v151, v133, v0
	ds_write2_b32 v0, v114, v115 offset1:36
	ds_write2_b32 v0, v116, v117 offset0:72 offset1:108
	v_add_u32_e32 v114, 0x400, v0
	v_or_b32_e32 v132, s2, v150
	ds_write2_b32 v114, v118, v119 offset0:32 offset1:68
	ds_write2_b32 v114, v120, v121 offset0:104 offset1:140
	v_add_u32_e32 v114, 0x800, v0
	v_add_u32_e32 v0, 0xc00, v0
	v_readlane_b32 s41, v251, 3
	v_readlane_b32 s42, v251, 4
	v_readlane_b32 s43, v251, 5
	v_readlane_b32 s44, v251, 6
	v_readlane_b32 s45, v251, 7
	v_readlane_b32 s46, v251, 8
	v_readlane_b32 s47, v251, 9
	v_readlane_b32 s48, v251, 10
	v_readlane_b32 s49, v251, 11
	v_readlane_b32 s50, v251, 12
	v_readlane_b32 s51, v251, 13
	v_readlane_b32 s0, v251, 26
	v_ashrrev_i32_e32 v135, 31, v134
	v_lshlrev_b64 v[136:137], 11, v[136:137]
	ds_write2_b32 v114, v122, v123 offset0:64 offset1:100
	ds_write2_b32 v114, v124, v125 offset0:136 offset1:172
	ds_write2_b32 v0, v126, v127 offset0:96 offset1:132
	ds_write2_b32 v0, v128, v129 offset0:168 offset1:204
	v_readlane_b32 s54, v251, 16
	v_readlane_b32 s55, v251, 17
	v_ashrrev_i32_e32 v133, 31, v132
	v_readlane_b32 s1, v251, 27
	v_readlane_b32 s36, v253, 47
	v_lshlrev_b32_e32 v0, 2, v156
	v_readlane_b32 s52, v251, 14
	v_readlane_b32 s53, v251, 15
	v_lshl_add_u64 v[114:115], v[134:135], 2, s[54:55]
	s_mov_b64 s[2:3], 0x1b0b000
	v_lshl_add_u64 v[118:119], s[0:1], 0, v[136:137]
	v_lshlrev_b64 v[116:117], 1, v[132:133]
	v_lshlrev_b64 v[122:123], 12, v[130:131]
	v_readlane_b32 s37, v253, 48
	v_and_b32_e32 v128, 28, v0
	v_lshl_add_u64 v[120:121], v[114:115], 0, s[2:3]
	v_lshlrev_b64 v[114:115], 2, v[132:133]
	v_lshl_add_u64 v[118:119], v[118:119], 0, v[116:117]
	v_lshl_add_u64 v[124:125], s[36:37], 0, v[122:123]
	v_lshl_add_u64 v[122:123], s[52:53], 0, v[122:123]
	v_lshlrev_b32_e32 v0, 2, v128
	v_lshlrev_b32_e32 v128, 1, v128
	v_mov_b32_e32 v129, v1
	v_bfe_u32 v133, v156, 3, 3
	v_lshl_add_u64 v[126:127], v[120:121], 0, v[114:115]
	v_lshl_add_u64 v[124:125], v[124:125], 0, v[114:115]
	v_lshl_add_u64 v[122:123], v[122:123], 0, v[114:115]
	v_lshl_add_u64 v[134:135], v[118:119], 0, v[128:129]
	v_mul_u32_u24_e32 v131, 0x90, v133
	v_lshlrev_b32_e32 v156, 11, v133
	v_mov_b32_e32 v157, v1
	s_waitcnt lgkmcnt(0)
	v_lshl_add_u64 v[126:127], v[126:127], 0, v[0:1]
	v_lshl_add_u64 v[136:137], v[124:125], 0, v[0:1]
	v_lshl_add_u64 v[128:129], v[122:123], 0, v[0:1]
	v_add3_u32 v131, v151, v0, v131
	v_lshlrev_b32_e32 v0, 12, v133
	v_lshl_add_u64 v[156:157], v[134:135], 0, v[156:157]
	v_lshl_add_u64 v[164:165], v[136:137], 0, v[0:1]
	global_load_dwordx4 v[180:183], v[126:127], off
	v_mov_b32_e32 v212, v133
	v_lshlrev_b32_e32 v184, 11, v212
	v_mov_b32_e32 v185, v1
	v_lshl_add_u64 v[184:185], v[134:135], 0, v[184:185]
	global_load_dwordx2 v[184:185], v[184:185], off
	v_lshlrev_b32_e32 v192, 12, v212
	v_mov_b32_e32 v193, v1
	v_lshl_add_u64 v[192:193], v[136:137], 0, v[192:193]
	global_load_dwordx4 v[192:195], v[192:193], off
	v_or_b32_e32 v212, 8, v133
	v_lshlrev_b32_e32 v186, 11, v212
	v_mov_b32_e32 v187, v1
	v_lshl_add_u64 v[186:187], v[134:135], 0, v[186:187]
	global_load_dwordx2 v[186:187], v[186:187], off
	v_lshlrev_b32_e32 v200, 12, v212
	v_mov_b32_e32 v201, v1
	v_lshl_add_u64 v[200:201], v[136:137], 0, v[200:201]
	global_load_dwordx4 v[200:203], v[200:201], off
	v_or_b32_e32 v212, 16, v133
	v_lshlrev_b32_e32 v188, 11, v212
	v_mov_b32_e32 v189, v1
	v_lshl_add_u64 v[188:189], v[134:135], 0, v[188:189]
	global_load_dwordx2 v[188:189], v[188:189], off
	v_lshlrev_b32_e32 v204, 12, v212
	v_mov_b32_e32 v205, v1
	v_lshl_add_u64 v[204:205], v[136:137], 0, v[204:205]
	global_load_dwordx4 v[204:207], v[204:205], off
	v_or_b32_e32 v212, 24, v133
	v_lshlrev_b32_e32 v190, 11, v212
	v_mov_b32_e32 v191, v1
	v_lshl_add_u64 v[190:191], v[134:135], 0, v[190:191]
	global_load_dwordx2 v[190:191], v[190:191], off
	v_lshlrev_b32_e32 v208, 12, v212
	v_mov_b32_e32 v209, v1
	v_lshl_add_u64 v[208:209], v[136:137], 0, v[208:209]
	global_load_dwordx4 v[208:211], v[208:209], off
	s_waitcnt vmcnt(6)
	v_mov_b32_e32 v168, v184
	v_mov_b32_e32 v169, v185
	ds_read_b128 v[156:159], v131
	v_mov_b32_e32 v160, v180
	v_mov_b32_e32 v161, v181
	v_mov_b32_e32 v162, v182
	v_mov_b32_e32 v163, v183
	s_nop 0
	v_mov_b32_e32 v164, v192
	v_mov_b32_e32 v165, v193
	v_mov_b32_e32 v166, v194
	v_mov_b32_e32 v167, v195
	v_lshl_add_u64 v[170:171], v[128:129], 0, v[0:1]
	v_readlane_b32 s38, v253, 49
	v_readlane_b32 s39, v253, 50
	v_readlane_b32 s42, v253, 53
	v_readlane_b32 s43, v253, 54
	v_readlane_b32 s44, v253, 55
	v_readlane_b32 s45, v253, 56
	v_readlane_b32 s46, v253, 57
	v_readlane_b32 s47, v253, 58
	v_readlane_b32 s48, v253, 59
	v_readlane_b32 s49, v253, 60
	v_readlane_b32 s51, v253, 62
	v_readlane_b32 s40, v253, 51
	v_readlane_b32 s41, v253, 52
	v_readlane_b32 s50, v253, 61
	v_and_b32_e32 v173, 0xffff0000, v168
	v_lshlrev_b32_e32 v172, 16, v168
	v_pk_add_f32 v[164:165], v[164:165], v[172:173]
	s_waitcnt lgkmcnt(0)
	v_pk_fma_f32 v[156:157], v[156:157], v[160:161], v[164:165]
	v_and_b32_e32 v161, 0xffff0000, v169
	v_lshlrev_b32_e32 v160, 16, v169
	v_pk_add_f32 v[160:161], v[166:167], v[160:161]
	s_nop 0
	v_pk_fma_f32 v[158:159], v[158:159], v[162:163], v[160:161]
	global_store_dwordx4 v[170:171], v[156:159], off sc1
	s_nop 1
	v_or_b32_e32 v156, 8, v133
	v_lshlrev_b32_e32 v0, 12, v156
	v_lshlrev_b32_e32 v156, 11, v156
	v_mov_b32_e32 v157, v1
	v_lshl_add_u64 v[156:157], v[134:135], 0, v[156:157]
	v_lshl_add_u64 v[164:165], v[136:137], 0, v[0:1]
	s_waitcnt vmcnt(5)
	v_mov_b32_e32 v168, v186
	v_mov_b32_e32 v169, v187
	ds_read_b128 v[156:159], v131 offset:1152
	v_mov_b32_e32 v160, v180
	v_mov_b32_e32 v161, v181
	v_mov_b32_e32 v162, v182
	v_mov_b32_e32 v163, v183
	s_nop 0
	v_mov_b32_e32 v164, v200
	v_mov_b32_e32 v165, v201
	v_mov_b32_e32 v166, v202
	v_mov_b32_e32 v167, v203
	v_lshl_add_u64 v[170:171], v[128:129], 0, v[0:1]
	v_or_b32_e32 v0, 16, v133
	v_and_b32_e32 v173, 0xffff0000, v168
	v_lshlrev_b32_e32 v172, 16, v168
	v_pk_add_f32 v[164:165], v[164:165], v[172:173]
	s_waitcnt lgkmcnt(0)
	v_pk_fma_f32 v[156:157], v[156:157], v[160:161], v[164:165]
	v_and_b32_e32 v161, 0xffff0000, v169
	v_lshlrev_b32_e32 v160, 16, v169
	v_pk_add_f32 v[160:161], v[166:167], v[160:161]
	s_nop 0
	v_pk_fma_f32 v[158:159], v[158:159], v[162:163], v[160:161]
	global_store_dwordx4 v[170:171], v[156:159], off sc1
	s_nop 1
	v_lshlrev_b32_e32 v158, 11, v0
	v_mov_b32_e32 v159, v1
	v_lshlrev_b32_e32 v156, 12, v0
	v_mov_b32_e32 v157, v1
	v_lshl_add_u64 v[158:159], v[134:135], 0, v[158:159]
	v_lshl_add_u64 v[164:165], v[136:137], 0, v[156:157]
	s_waitcnt vmcnt(4)
	v_mov_b32_e32 v168, v188
	v_mov_b32_e32 v169, v189
	v_lshl_add_u64 v[170:171], v[128:129], 0, v[156:157]
	ds_read_b128 v[156:159], v131 offset:2304
	v_mov_b32_e32 v160, v180
	v_mov_b32_e32 v161, v181
	v_mov_b32_e32 v162, v182
	v_mov_b32_e32 v163, v183
	s_nop 0
	v_mov_b32_e32 v164, v204
	v_mov_b32_e32 v165, v205
	v_mov_b32_e32 v166, v206
	v_mov_b32_e32 v167, v207
	v_or_b32_e32 v0, 24, v133
	v_and_b32_e32 v173, 0xffff0000, v168
	v_lshlrev_b32_e32 v172, 16, v168
	v_pk_add_f32 v[164:165], v[164:165], v[172:173]
	s_waitcnt lgkmcnt(0)
	v_pk_fma_f32 v[156:157], v[156:157], v[160:161], v[164:165]
	v_and_b32_e32 v161, 0xffff0000, v169
	v_lshlrev_b32_e32 v160, 16, v169
	v_pk_add_f32 v[160:161], v[166:167], v[160:161]
	s_nop 0
	v_pk_fma_f32 v[158:159], v[158:159], v[162:163], v[160:161]
	global_store_dwordx4 v[170:171], v[156:159], off sc1
	s_nop 1
	v_lshlrev_b32_e32 v156, 12, v0
	v_mov_b32_e32 v157, v1
	v_lshl_add_u64 v[158:159], v[136:137], 0, v[156:157]
	v_lshlrev_b32_e32 v136, 11, v0
	v_mov_b32_e32 v137, v1
	v_lshl_add_u64 v[134:135], v[134:135], 0, v[136:137]
	s_waitcnt vmcnt(3)
	v_mov_b32_e32 v160, v190
	v_mov_b32_e32 v161, v191
	v_lshl_add_u64 v[162:163], v[128:129], 0, v[156:157]
	ds_read_b128 v[134:137], v131 offset:3456
	v_mov_b32_e32 v126, v180
	v_mov_b32_e32 v127, v181
	v_mov_b32_e32 v128, v182
	v_mov_b32_e32 v129, v183
	s_nop 0
	v_mov_b32_e32 v156, v208
	v_mov_b32_e32 v157, v209
	v_mov_b32_e32 v158, v210
	v_mov_b32_e32 v159, v211
	v_and_b32_e32 v165, 0xffff0000, v160
	v_lshlrev_b32_e32 v164, 16, v160
	v_pk_add_f32 v[156:157], v[156:157], v[164:165]
	s_waitcnt lgkmcnt(0)
	v_pk_fma_f32 v[126:127], v[134:135], v[126:127], v[156:157]
	v_and_b32_e32 v135, 0xffff0000, v161
	v_lshlrev_b32_e32 v134, 16, v161
	v_pk_add_f32 v[134:135], v[158:159], v[134:135]
	s_nop 0
	v_pk_fma_f32 v[128:129], v[136:137], v[128:129], v[134:135]
	global_store_dwordx4 v[162:163], v[126:129], off sc1
	v_mov_b32_e32 v0, v179
	s_nop 0
	v_or_b32_e32 v126, 32, v132
	v_and_b32_e32 v127, 31, v0
	v_bfe_u32 v128, v0, 5, 1
	v_mul_u32_u24_e32 v128, 0x240, v128
	v_lshlrev_b32_e32 v127, 2, v127
	v_add3_u32 v127, v151, v128, v127
	ds_write2_b32 v127, v98, v99 offset1:36
	ds_write2_b32 v127, v100, v101 offset0:72 offset1:108
	v_add_u32_e32 v98, 0x400, v127
	ds_write2_b32 v98, v102, v103 offset0:32 offset1:68
	ds_write2_b32 v98, v104, v105 offset0:104 offset1:140
	v_add_u32_e32 v98, 0x800, v127
	ds_write2_b32 v98, v106, v107 offset0:64 offset1:100
	ds_write2_b32 v98, v108, v109 offset0:136 offset1:172
	v_add_u32_e32 v98, 0xc00, v127
	ds_write2_b32 v98, v110, v111 offset0:96 offset1:132
	ds_write2_b32 v98, v112, v113 offset0:168 offset1:204
	v_lshlrev_b32_e32 v98, 2, v0
	v_and_b32_e32 v102, 28, v98
	v_lshlrev_b32_e32 v108, 2, v102
	v_lshlrev_b32_e32 v102, 1, v102
	v_mov_b32_e32 v103, v1
	v_bfe_u32 v131, v0, 3, 3
	v_ashrrev_i32_e32 v127, 31, v126
	v_mov_b32_e32 v109, v1
	v_lshl_add_u64 v[104:105], v[118:119], 0, v[102:103]
	v_lshlrev_b32_e32 v110, 11, v131
	v_mov_b32_e32 v111, v1
	s_waitcnt lgkmcnt(0)
	v_lshl_add_u64 v[100:101], v[120:121], 0, v[108:109]
	v_lshlrev_b64 v[98:99], 2, v[126:127]
	v_mul_u32_u24_e32 v0, 0x90, v131
	v_lshl_add_u64 v[110:111], v[104:105], 0, v[110:111]
	v_lshl_add_u64 v[100:101], v[100:101], 0, v[98:99]
	v_lshl_add_u64 v[106:107], v[124:125], 0, v[108:109]
	v_lshl_add_u64 v[102:103], v[122:123], 0, v[108:109]
	v_add3_u32 v0, v151, v108, v0
	v_lshlrev_b32_e32 v108, 12, v131
	global_load_dwordx4 v[180:183], v[100:101], off
	v_mov_b32_e32 v212, v131
	v_lshlrev_b32_e32 v184, 11, v212
	v_mov_b32_e32 v185, v1
	v_lshl_add_u64 v[184:185], v[104:105], 0, v[184:185]
	global_load_dwordx2 v[184:185], v[184:185], off offset:64
	v_lshlrev_b32_e32 v192, 12, v212
	v_mov_b32_e32 v193, v1
	v_lshl_add_u64 v[192:193], v[106:107], 0, v[192:193]
	global_load_dwordx4 v[192:195], v[192:193], off offset:128
	v_or_b32_e32 v212, 8, v131
	v_lshlrev_b32_e32 v186, 11, v212
	v_mov_b32_e32 v187, v1
	v_lshl_add_u64 v[186:187], v[104:105], 0, v[186:187]
	global_load_dwordx2 v[186:187], v[186:187], off offset:64
	v_lshlrev_b32_e32 v200, 12, v212
	v_mov_b32_e32 v201, v1
	v_lshl_add_u64 v[200:201], v[106:107], 0, v[200:201]
	global_load_dwordx4 v[200:203], v[200:201], off offset:128
	v_or_b32_e32 v212, 16, v131
	v_lshlrev_b32_e32 v188, 11, v212
	v_mov_b32_e32 v189, v1
	v_lshl_add_u64 v[188:189], v[104:105], 0, v[188:189]
	global_load_dwordx2 v[188:189], v[188:189], off offset:64
	v_lshlrev_b32_e32 v204, 12, v212
	v_mov_b32_e32 v205, v1
	v_lshl_add_u64 v[204:205], v[106:107], 0, v[204:205]
	global_load_dwordx4 v[204:207], v[204:205], off offset:128
	v_or_b32_e32 v212, 24, v131
	v_lshlrev_b32_e32 v190, 11, v212
	v_mov_b32_e32 v191, v1
	v_lshl_add_u64 v[190:191], v[104:105], 0, v[190:191]
	global_load_dwordx2 v[190:191], v[190:191], off offset:64
	v_lshlrev_b32_e32 v208, 12, v212
	v_mov_b32_e32 v209, v1
	v_lshl_add_u64 v[208:209], v[106:107], 0, v[208:209]
	global_load_dwordx4 v[208:211], v[208:209], off offset:128
	s_waitcnt vmcnt(6)
	v_mov_b32_e32 v126, v184
	v_mov_b32_e32 v127, v185
	v_lshl_add_u64 v[112:113], v[106:107], 0, v[108:109]
	v_lshl_add_u64 v[128:129], v[102:103], 0, v[108:109]
	ds_read_b128 v[108:111], v0
	v_mov_b32_e32 v118, v180
	v_mov_b32_e32 v119, v181
	v_mov_b32_e32 v120, v182
	v_mov_b32_e32 v121, v183
	v_mov_b32_e32 v122, v192
	v_mov_b32_e32 v123, v193
	v_mov_b32_e32 v124, v194
	v_mov_b32_e32 v125, v195
	v_and_b32_e32 v113, 0xffff0000, v126
	v_lshlrev_b32_e32 v112, 16, v126
	v_pk_add_f32 v[112:113], v[122:123], v[112:113]
	s_waitcnt lgkmcnt(0)
	v_pk_fma_f32 v[108:109], v[108:109], v[118:119], v[112:113]
	v_and_b32_e32 v113, 0xffff0000, v127
	v_lshlrev_b32_e32 v112, 16, v127
	v_pk_add_f32 v[112:113], v[124:125], v[112:113]
	s_nop 0
	v_pk_fma_f32 v[110:111], v[110:111], v[120:121], v[112:113]
	global_store_dwordx4 v[128:129], v[108:111], off offset:128 sc1
	s_nop 1
	v_or_b32_e32 v110, 8, v131
	v_lshlrev_b32_e32 v108, 12, v110
	v_lshlrev_b32_e32 v110, 11, v110
	v_mov_b32_e32 v111, v1
	v_lshl_add_u64 v[110:111], v[104:105], 0, v[110:111]
	v_mov_b32_e32 v109, v1
	s_waitcnt vmcnt(5)
	v_mov_b32_e32 v126, v186
	v_mov_b32_e32 v127, v187
	v_lshl_add_u64 v[112:113], v[106:107], 0, v[108:109]
	v_lshl_add_u64 v[128:129], v[102:103], 0, v[108:109]
	ds_read_b128 v[108:111], v0 offset:1152
	v_mov_b32_e32 v118, v180
	v_mov_b32_e32 v119, v181
	v_mov_b32_e32 v120, v182
	v_mov_b32_e32 v121, v183
	v_mov_b32_e32 v122, v200
	v_mov_b32_e32 v123, v201
	v_mov_b32_e32 v124, v202
	v_mov_b32_e32 v125, v203
	v_and_b32_e32 v113, 0xffff0000, v126
	v_lshlrev_b32_e32 v112, 16, v126
	v_pk_add_f32 v[112:113], v[122:123], v[112:113]
	s_waitcnt lgkmcnt(0)
	v_pk_fma_f32 v[108:109], v[108:109], v[118:119], v[112:113]
	v_and_b32_e32 v113, 0xffff0000, v127
	v_lshlrev_b32_e32 v112, 16, v127
	v_pk_add_f32 v[112:113], v[124:125], v[112:113]
	s_nop 0
	v_pk_fma_f32 v[110:111], v[110:111], v[120:121], v[112:113]
	global_store_dwordx4 v[128:129], v[108:111], off offset:128 sc1
	s_nop 1
	v_or_b32_e32 v110, 16, v131
	v_lshlrev_b32_e32 v108, 12, v110
	v_lshlrev_b32_e32 v110, 11, v110
	v_mov_b32_e32 v111, v1
	v_lshl_add_u64 v[110:111], v[104:105], 0, v[110:111]
	v_mov_b32_e32 v109, v1
	s_waitcnt vmcnt(4)
	v_mov_b32_e32 v126, v188
	v_mov_b32_e32 v127, v189
	v_lshl_add_u64 v[112:113], v[106:107], 0, v[108:109]
	v_lshl_add_u64 v[128:129], v[102:103], 0, v[108:109]
	ds_read_b128 v[108:111], v0 offset:2304
	v_mov_b32_e32 v118, v180
	v_mov_b32_e32 v119, v181
	v_mov_b32_e32 v120, v182
	v_mov_b32_e32 v121, v183
	v_mov_b32_e32 v122, v204
	v_mov_b32_e32 v123, v205
	v_mov_b32_e32 v124, v206
	v_mov_b32_e32 v125, v207
	v_and_b32_e32 v113, 0xffff0000, v126
	v_lshlrev_b32_e32 v112, 16, v126
	v_pk_add_f32 v[112:113], v[122:123], v[112:113]
	s_waitcnt lgkmcnt(0)
	v_pk_fma_f32 v[108:109], v[108:109], v[118:119], v[112:113]
	v_and_b32_e32 v113, 0xffff0000, v127
	v_lshlrev_b32_e32 v112, 16, v127
	v_pk_add_f32 v[112:113], v[124:125], v[112:113]
	s_nop 0
	v_pk_fma_f32 v[110:111], v[110:111], v[120:121], v[112:113]
	v_or_b32_e32 v112, 24, v131
	global_store_dwordx4 v[128:129], v[108:111], off offset:128 sc1
	s_nop 1
	v_lshlrev_b32_e32 v108, 12, v112
	v_mov_b32_e32 v109, v1
	v_lshl_add_u64 v[110:111], v[106:107], 0, v[108:109]
	v_lshlrev_b32_e32 v106, 11, v112
	v_mov_b32_e32 v107, v1
	v_lshl_add_u64 v[104:105], v[104:105], 0, v[106:107]
	s_waitcnt vmcnt(3)
	v_mov_b32_e32 v118, v190
	v_mov_b32_e32 v119, v191
	v_lshl_add_u64 v[120:121], v[102:103], 0, v[108:109]
	ds_read_b128 v[102:105], v0 offset:3456
	v_mov_b32_e32 v106, v180
	v_mov_b32_e32 v107, v181
	v_mov_b32_e32 v108, v182
	v_mov_b32_e32 v109, v183
	s_nop 0
	v_mov_b32_e32 v110, v208
	v_mov_b32_e32 v111, v209
	v_mov_b32_e32 v112, v210
	v_mov_b32_e32 v113, v211
	v_and_b32_e32 v101, 0xffff0000, v118
	v_lshlrev_b32_e32 v100, 16, v118
	v_pk_add_f32 v[100:101], v[110:111], v[100:101]
	s_waitcnt lgkmcnt(0)
	v_pk_fma_f32 v[100:101], v[102:103], v[106:107], v[100:101]
	v_and_b32_e32 v103, 0xffff0000, v119
	v_lshlrev_b32_e32 v102, 16, v119
	v_pk_add_f32 v[102:103], v[112:113], v[102:103]
	s_nop 0
	v_pk_fma_f32 v[102:103], v[104:105], v[108:109], v[102:103]
	global_store_dwordx4 v[120:121], v[100:103], off offset:128 sc1
	s_nop 1
	v_or_b32_e32 v100, 32, v130
	v_add_u32_e32 v0, v100, v155
	v_ashrrev_i32_e32 v0, 14, v0
	v_mul_i32_i24_e32 v101, 0x4000, v0
	v_sub_u32_e32 v101, v100, v101
	v_add_u32_e32 v106, 0x100, v101
	v_mul_i32_i24_e32 v102, 0xc00, v0
	v_mul_hi_i32_i24_e32 v105, 0x4100, v0
	v_mul_i32_i24_e32 v104, 0x4100, v0
	v_ashrrev_i32_e32 v107, 31, v106
	v_mov_b32_e32 v0, v179
	v_lshl_add_u64 v[104:105], v[104:105], 0, v[106:107]
	v_ashrrev_i32_e32 v103, 31, v102
	v_and_b32_e32 v106, 31, v0
	v_bfe_u32 v107, v0, 5, 1
	v_mul_u32_u24_e32 v107, 0x240, v107
	v_lshlrev_b32_e32 v106, 2, v106
	v_add3_u32 v106, v151, v107, v106
	ds_write2_b32 v106, v82, v83 offset1:36
	ds_write2_b32 v106, v84, v85 offset0:72 offset1:108
	v_add_u32_e32 v82, 0x400, v106
	ds_write2_b32 v82, v86, v87 offset0:32 offset1:68
	ds_write2_b32 v82, v88, v89 offset0:104 offset1:140
	v_add_u32_e32 v82, 0x800, v106
	ds_write2_b32 v82, v90, v91 offset0:64 offset1:100
	ds_write2_b32 v82, v92, v93 offset0:136 offset1:172
	v_add_u32_e32 v82, 0xc00, v106
	v_lshlrev_b64 v[104:105], 11, v[104:105]
	v_ashrrev_i32_e32 v101, 31, v100
	ds_write2_b32 v82, v94, v95 offset0:96 offset1:132
	ds_write2_b32 v82, v96, v97 offset0:168 offset1:204
	v_lshl_add_u64 v[82:83], v[102:103], 2, s[54:55]
	v_lshlrev_b32_e32 v92, 2, v0
	v_lshl_add_u64 v[86:87], v[82:83], 0, s[2:3]
	v_lshl_add_u64 v[82:83], s[0:1], 0, v[104:105]
	v_lshlrev_b64 v[84:85], 12, v[100:101]
	v_and_b32_e32 v92, 28, v92
	v_lshl_add_u64 v[82:83], v[82:83], 0, v[116:117]
	v_lshl_add_u64 v[88:89], s[36:37], 0, v[84:85]
	v_lshl_add_u64 v[84:85], s[52:53], 0, v[84:85]
	v_lshlrev_b32_e32 v100, 2, v92
	v_lshlrev_b32_e32 v92, 1, v92
	v_mov_b32_e32 v93, v1
	v_bfe_u32 v122, v0, 3, 3
	v_lshl_add_u64 v[90:91], v[86:87], 0, v[114:115]
	v_lshl_add_u64 v[88:89], v[88:89], 0, v[114:115]
	v_lshl_add_u64 v[84:85], v[84:85], 0, v[114:115]
	v_mov_b32_e32 v101, v1
	v_lshl_add_u64 v[94:95], v[82:83], 0, v[92:93]
	v_mul_u32_u24_e32 v0, 0x90, v122
	v_lshlrev_b32_e32 v102, 11, v122
	v_mov_b32_e32 v103, v1
	s_waitcnt lgkmcnt(0)
	v_lshl_add_u64 v[90:91], v[90:91], 0, v[100:101]
	v_lshl_add_u64 v[96:97], v[88:89], 0, v[100:101]
	v_lshl_add_u64 v[92:93], v[84:85], 0, v[100:101]
	v_add3_u32 v0, v151, v100, v0
	v_lshlrev_b32_e32 v100, 12, v122
	v_lshl_add_u64 v[102:103], v[94:95], 0, v[102:103]
	v_lshl_add_u64 v[108:109], v[96:97], 0, v[100:101]
	global_load_dwordx4 v[180:183], v[90:91], off
	v_mov_b32_e32 v212, v122
	v_lshlrev_b32_e32 v184, 11, v212
	v_mov_b32_e32 v185, v1
	v_lshl_add_u64 v[184:185], v[94:95], 0, v[184:185]
	global_load_dwordx2 v[184:185], v[184:185], off
	v_lshlrev_b32_e32 v192, 12, v212
	v_mov_b32_e32 v193, v1
	v_lshl_add_u64 v[192:193], v[96:97], 0, v[192:193]
	global_load_dwordx4 v[192:195], v[192:193], off
	v_or_b32_e32 v212, 8, v122
	v_lshlrev_b32_e32 v186, 11, v212
	v_mov_b32_e32 v187, v1
	v_lshl_add_u64 v[186:187], v[94:95], 0, v[186:187]
	global_load_dwordx2 v[186:187], v[186:187], off
	v_lshlrev_b32_e32 v200, 12, v212
	v_mov_b32_e32 v201, v1
	v_lshl_add_u64 v[200:201], v[96:97], 0, v[200:201]
	global_load_dwordx4 v[200:203], v[200:201], off
	v_or_b32_e32 v212, 16, v122
	v_lshlrev_b32_e32 v188, 11, v212
	v_mov_b32_e32 v189, v1
	v_lshl_add_u64 v[188:189], v[94:95], 0, v[188:189]
	global_load_dwordx2 v[188:189], v[188:189], off
	v_lshlrev_b32_e32 v204, 12, v212
	v_mov_b32_e32 v205, v1
	v_lshl_add_u64 v[204:205], v[96:97], 0, v[204:205]
	global_load_dwordx4 v[204:207], v[204:205], off
	v_or_b32_e32 v212, 24, v122
	v_lshlrev_b32_e32 v190, 11, v212
	v_mov_b32_e32 v191, v1
	v_lshl_add_u64 v[190:191], v[94:95], 0, v[190:191]
	global_load_dwordx2 v[190:191], v[190:191], off
	v_lshlrev_b32_e32 v208, 12, v212
	v_mov_b32_e32 v209, v1
	v_lshl_add_u64 v[208:209], v[96:97], 0, v[208:209]
	global_load_dwordx4 v[208:211], v[208:209], off
	s_waitcnt vmcnt(6)
	v_mov_b32_e32 v112, v184
	v_mov_b32_e32 v113, v185
	v_lshl_add_u64 v[118:119], v[92:93], 0, v[100:101]
	ds_read_b128 v[100:103], v0
	v_mov_b32_e32 v104, v180
	v_mov_b32_e32 v105, v181
	v_mov_b32_e32 v106, v182
	v_mov_b32_e32 v107, v183
	s_nop 0
	v_mov_b32_e32 v108, v192
	v_mov_b32_e32 v109, v193
	v_mov_b32_e32 v110, v194
	v_mov_b32_e32 v111, v195
	v_and_b32_e32 v121, 0xffff0000, v112
	v_lshlrev_b32_e32 v120, 16, v112
	v_pk_add_f32 v[108:109], v[108:109], v[120:121]
	s_waitcnt lgkmcnt(0)
	v_pk_fma_f32 v[100:101], v[100:101], v[104:105], v[108:109]
	v_and_b32_e32 v105, 0xffff0000, v113
	v_lshlrev_b32_e32 v104, 16, v113
	v_pk_add_f32 v[104:105], v[110:111], v[104:105]
	s_nop 0
	v_pk_fma_f32 v[102:103], v[102:103], v[106:107], v[104:105]
	global_store_dwordx4 v[118:119], v[100:103], off sc1
	s_nop 1
	v_or_b32_e32 v102, 8, v122
	v_lshlrev_b32_e32 v100, 12, v102
	v_lshlrev_b32_e32 v102, 11, v102
	v_mov_b32_e32 v103, v1
	v_mov_b32_e32 v101, v1
	v_lshl_add_u64 v[102:103], v[94:95], 0, v[102:103]
	v_lshl_add_u64 v[108:109], v[96:97], 0, v[100:101]
	s_waitcnt vmcnt(5)
	v_mov_b32_e32 v112, v186
	v_mov_b32_e32 v113, v187
	v_lshl_add_u64 v[118:119], v[92:93], 0, v[100:101]
	ds_read_b128 v[100:103], v0 offset:1152
	v_mov_b32_e32 v104, v180
	v_mov_b32_e32 v105, v181
	v_mov_b32_e32 v106, v182
	v_mov_b32_e32 v107, v183
	s_nop 0
	v_mov_b32_e32 v108, v200
	v_mov_b32_e32 v109, v201
	v_mov_b32_e32 v110, v202
	v_mov_b32_e32 v111, v203
	v_and_b32_e32 v121, 0xffff0000, v112
	v_lshlrev_b32_e32 v120, 16, v112
	v_pk_add_f32 v[108:109], v[108:109], v[120:121]
	s_waitcnt lgkmcnt(0)
	v_pk_fma_f32 v[100:101], v[100:101], v[104:105], v[108:109]
	v_and_b32_e32 v105, 0xffff0000, v113
	v_lshlrev_b32_e32 v104, 16, v113
	v_pk_add_f32 v[104:105], v[110:111], v[104:105]
	s_nop 0
	v_pk_fma_f32 v[102:103], v[102:103], v[106:107], v[104:105]
	global_store_dwordx4 v[118:119], v[100:103], off sc1
	s_nop 1
	v_or_b32_e32 v102, 16, v122
	v_lshlrev_b32_e32 v100, 12, v102
	v_lshlrev_b32_e32 v102, 11, v102
	v_mov_b32_e32 v103, v1
	v_mov_b32_e32 v101, v1
	v_lshl_add_u64 v[102:103], v[94:95], 0, v[102:103]
	v_lshl_add_u64 v[108:109], v[96:97], 0, v[100:101]
	s_waitcnt vmcnt(4)
	v_mov_b32_e32 v112, v188
	v_mov_b32_e32 v113, v189
	v_lshl_add_u64 v[118:119], v[92:93], 0, v[100:101]
	ds_read_b128 v[100:103], v0 offset:2304
	v_mov_b32_e32 v104, v180
	v_mov_b32_e32 v105, v181
	v_mov_b32_e32 v106, v182
	v_mov_b32_e32 v107, v183
	s_nop 0
	v_mov_b32_e32 v108, v204
	v_mov_b32_e32 v109, v205
	v_mov_b32_e32 v110, v206
	v_mov_b32_e32 v111, v207
	v_and_b32_e32 v121, 0xffff0000, v112
	v_lshlrev_b32_e32 v120, 16, v112
	v_pk_add_f32 v[108:109], v[108:109], v[120:121]
	s_waitcnt lgkmcnt(0)
	v_pk_fma_f32 v[100:101], v[100:101], v[104:105], v[108:109]
	v_and_b32_e32 v105, 0xffff0000, v113
	v_lshlrev_b32_e32 v104, 16, v113
	v_pk_add_f32 v[104:105], v[110:111], v[104:105]
	s_nop 0
	v_pk_fma_f32 v[102:103], v[102:103], v[106:107], v[104:105]
	global_store_dwordx4 v[118:119], v[100:103], off sc1
	s_nop 1
	v_or_b32_e32 v102, 24, v122
	v_lshlrev_b32_e32 v100, 12, v102
	v_lshlrev_b32_e32 v102, 11, v102
	v_mov_b32_e32 v103, v1
	v_lshl_add_u64 v[94:95], v[94:95], 0, v[102:103]
	v_mov_b32_e32 v101, v1
	s_waitcnt vmcnt(3)
	v_mov_b32_e32 v108, v190
	v_mov_b32_e32 v109, v191
	v_lshl_add_u64 v[96:97], v[96:97], 0, v[100:101]
	v_lshl_add_u64 v[110:111], v[92:93], 0, v[100:101]
	ds_read_b128 v[92:95], v0 offset:3456
	v_mov_b32_e32 v100, v180
	v_mov_b32_e32 v101, v181
	v_mov_b32_e32 v102, v182
	v_mov_b32_e32 v103, v183
	v_mov_b32_e32 v104, v208
	v_mov_b32_e32 v105, v209
	v_mov_b32_e32 v106, v210
	v_mov_b32_e32 v107, v211
	v_and_b32_e32 v91, 0xffff0000, v108
	v_lshlrev_b32_e32 v90, 16, v108
	v_pk_add_f32 v[90:91], v[104:105], v[90:91]
	s_waitcnt lgkmcnt(0)
	v_pk_fma_f32 v[90:91], v[92:93], v[100:101], v[90:91]
	v_and_b32_e32 v93, 0xffff0000, v109
	v_lshlrev_b32_e32 v92, 16, v109
	v_pk_add_f32 v[92:93], v[106:107], v[92:93]
	s_nop 0
	v_pk_fma_f32 v[92:93], v[94:95], v[102:103], v[92:93]
	global_store_dwordx4 v[110:111], v[90:93], off sc1
	v_mov_b32_e32 v0, v179
	s_nop 0
	v_and_b32_e32 v90, 31, v0
	v_bfe_u32 v91, v0, 5, 1
	v_mul_u32_u24_e32 v91, 0x240, v91
	v_lshlrev_b32_e32 v90, 2, v90
	v_add3_u32 v90, v151, v91, v90
	ds_write2_b32 v90, v66, v67 offset1:36
	ds_write2_b32 v90, v68, v69 offset0:72 offset1:108
	v_add_u32_e32 v66, 0x400, v90
	ds_write2_b32 v66, v70, v71 offset0:32 offset1:68
	ds_write2_b32 v66, v72, v73 offset0:104 offset1:140
	v_add_u32_e32 v66, 0x800, v90
	ds_write2_b32 v66, v74, v75 offset0:64 offset1:100
	ds_write2_b32 v66, v76, v77 offset0:136 offset1:172
	v_add_u32_e32 v66, 0xc00, v90
	ds_write2_b32 v66, v78, v79 offset0:96 offset1:132
	ds_write2_b32 v66, v80, v81 offset0:168 offset1:204
	v_lshlrev_b32_e32 v66, 2, v0
	v_and_b32_e32 v68, 28, v66
	v_lshlrev_b32_e32 v74, 2, v68
	v_lshlrev_b32_e32 v68, 1, v68
	v_mov_b32_e32 v69, v1
	v_bfe_u32 v92, v0, 3, 3
	v_mov_b32_e32 v75, v1
	v_lshl_add_u64 v[70:71], v[82:83], 0, v[68:69]
	v_mul_u32_u24_e32 v0, 0x90, v92
	v_lshlrev_b32_e32 v76, 11, v92
	v_mov_b32_e32 v77, v1
	s_waitcnt lgkmcnt(0)
	v_lshl_add_u64 v[66:67], v[86:87], 0, v[74:75]
	v_lshl_add_u64 v[72:73], v[88:89], 0, v[74:75]
	v_lshl_add_u64 v[68:69], v[84:85], 0, v[74:75]
	v_add3_u32 v0, v151, v74, v0
	v_lshlrev_b32_e32 v74, 12, v92
	v_lshl_add_u64 v[76:77], v[70:71], 0, v[76:77]
	v_lshl_add_u64 v[66:67], v[66:67], 0, v[98:99]
	v_lshl_add_u64 v[82:83], v[72:73], 0, v[74:75]
	global_load_dwordx4 v[180:183], v[66:67], off
	v_mov_b32_e32 v212, v92
	v_lshlrev_b32_e32 v184, 11, v212
	v_mov_b32_e32 v185, v1
	v_lshl_add_u64 v[184:185], v[70:71], 0, v[184:185]
	global_load_dwordx2 v[184:185], v[184:185], off offset:64
	v_lshlrev_b32_e32 v192, 12, v212
	v_mov_b32_e32 v193, v1
	v_lshl_add_u64 v[192:193], v[72:73], 0, v[192:193]
	global_load_dwordx4 v[192:195], v[192:193], off offset:128
	v_or_b32_e32 v212, 8, v92
	v_lshlrev_b32_e32 v186, 11, v212
	v_mov_b32_e32 v187, v1
	v_lshl_add_u64 v[186:187], v[70:71], 0, v[186:187]
	global_load_dwordx2 v[186:187], v[186:187], off offset:64
	v_lshlrev_b32_e32 v200, 12, v212
	v_mov_b32_e32 v201, v1
	v_lshl_add_u64 v[200:201], v[72:73], 0, v[200:201]
	global_load_dwordx4 v[200:203], v[200:201], off offset:128
	v_or_b32_e32 v212, 16, v92
	v_lshlrev_b32_e32 v188, 11, v212
	v_mov_b32_e32 v189, v1
	v_lshl_add_u64 v[188:189], v[70:71], 0, v[188:189]
	global_load_dwordx2 v[188:189], v[188:189], off offset:64
	v_lshlrev_b32_e32 v204, 12, v212
	v_mov_b32_e32 v205, v1
	v_lshl_add_u64 v[204:205], v[72:73], 0, v[204:205]
	global_load_dwordx4 v[204:207], v[204:205], off offset:128
	v_or_b32_e32 v212, 24, v92
	v_lshlrev_b32_e32 v190, 11, v212
	v_mov_b32_e32 v191, v1
	v_lshl_add_u64 v[190:191], v[70:71], 0, v[190:191]
	global_load_dwordx2 v[190:191], v[190:191], off offset:64
	v_lshlrev_b32_e32 v208, 12, v212
	v_mov_b32_e32 v209, v1
	v_lshl_add_u64 v[208:209], v[72:73], 0, v[208:209]
	global_load_dwordx4 v[208:211], v[208:209], off offset:128
	s_waitcnt vmcnt(6)
	v_mov_b32_e32 v86, v184
	v_mov_b32_e32 v87, v185
	v_lshl_add_u64 v[88:89], v[68:69], 0, v[74:75]
	ds_read_b128 v[74:77], v0
	v_mov_b32_e32 v78, v180
	v_mov_b32_e32 v79, v181
	v_mov_b32_e32 v80, v182
	v_mov_b32_e32 v81, v183
	s_nop 0
	v_mov_b32_e32 v82, v192
	v_mov_b32_e32 v83, v193
	v_mov_b32_e32 v84, v194
	v_mov_b32_e32 v85, v195
	v_and_b32_e32 v91, 0xffff0000, v86
	v_lshlrev_b32_e32 v90, 16, v86
	v_pk_add_f32 v[82:83], v[82:83], v[90:91]
	s_waitcnt lgkmcnt(0)
	v_pk_fma_f32 v[74:75], v[74:75], v[78:79], v[82:83]
	v_and_b32_e32 v79, 0xffff0000, v87
	v_lshlrev_b32_e32 v78, 16, v87
	v_pk_add_f32 v[78:79], v[84:85], v[78:79]
	s_nop 0
	v_pk_fma_f32 v[76:77], v[76:77], v[80:81], v[78:79]
	global_store_dwordx4 v[88:89], v[74:77], off offset:128 sc1
	s_nop 1
	v_or_b32_e32 v76, 8, v92
	v_lshlrev_b32_e32 v74, 12, v76
	v_lshlrev_b32_e32 v76, 11, v76
	v_mov_b32_e32 v77, v1
	v_mov_b32_e32 v75, v1
	v_lshl_add_u64 v[76:77], v[70:71], 0, v[76:77]
	v_lshl_add_u64 v[82:83], v[72:73], 0, v[74:75]
	s_waitcnt vmcnt(5)
	v_mov_b32_e32 v86, v186
	v_mov_b32_e32 v87, v187
	v_lshl_add_u64 v[88:89], v[68:69], 0, v[74:75]
	ds_read_b128 v[74:77], v0 offset:1152
	v_mov_b32_e32 v78, v180
	v_mov_b32_e32 v79, v181
	v_mov_b32_e32 v80, v182
	v_mov_b32_e32 v81, v183
	s_nop 0
	v_mov_b32_e32 v82, v200
	v_mov_b32_e32 v83, v201
	v_mov_b32_e32 v84, v202
	v_mov_b32_e32 v85, v203
	v_and_b32_e32 v91, 0xffff0000, v86
	v_lshlrev_b32_e32 v90, 16, v86
	v_pk_add_f32 v[82:83], v[82:83], v[90:91]
	s_waitcnt lgkmcnt(0)
	v_pk_fma_f32 v[74:75], v[74:75], v[78:79], v[82:83]
	v_and_b32_e32 v79, 0xffff0000, v87
	v_lshlrev_b32_e32 v78, 16, v87
	v_pk_add_f32 v[78:79], v[84:85], v[78:79]
	s_nop 0
	v_pk_fma_f32 v[76:77], v[76:77], v[80:81], v[78:79]
	global_store_dwordx4 v[88:89], v[74:77], off offset:128 sc1
	s_nop 1
	v_or_b32_e32 v76, 16, v92
	v_lshlrev_b32_e32 v74, 12, v76
	v_lshlrev_b32_e32 v76, 11, v76
	v_mov_b32_e32 v77, v1
	v_mov_b32_e32 v75, v1
	v_lshl_add_u64 v[76:77], v[70:71], 0, v[76:77]
	v_lshl_add_u64 v[82:83], v[72:73], 0, v[74:75]
	s_waitcnt vmcnt(4)
	v_mov_b32_e32 v86, v188
	v_mov_b32_e32 v87, v189
	v_lshl_add_u64 v[88:89], v[68:69], 0, v[74:75]
	ds_read_b128 v[74:77], v0 offset:2304
	v_mov_b32_e32 v78, v180
	v_mov_b32_e32 v79, v181
	v_mov_b32_e32 v80, v182
	v_mov_b32_e32 v81, v183
	s_nop 0
	v_mov_b32_e32 v82, v204
	v_mov_b32_e32 v83, v205
	v_mov_b32_e32 v84, v206
	v_mov_b32_e32 v85, v207
	v_and_b32_e32 v91, 0xffff0000, v86
	v_lshlrev_b32_e32 v90, 16, v86
	v_pk_add_f32 v[82:83], v[82:83], v[90:91]
	s_waitcnt lgkmcnt(0)
	v_pk_fma_f32 v[74:75], v[74:75], v[78:79], v[82:83]
	v_and_b32_e32 v79, 0xffff0000, v87
	v_lshlrev_b32_e32 v78, 16, v87
	v_pk_add_f32 v[78:79], v[84:85], v[78:79]
	s_nop 0
	v_pk_fma_f32 v[76:77], v[76:77], v[80:81], v[78:79]
	v_or_b32_e32 v78, 24, v92
	global_store_dwordx4 v[88:89], v[74:77], off offset:128 sc1
	s_nop 1
	v_lshlrev_b32_e32 v74, 12, v78
	v_mov_b32_e32 v75, v1
	v_lshl_add_u64 v[76:77], v[72:73], 0, v[74:75]
	v_lshlrev_b32_e32 v72, 11, v78
	v_mov_b32_e32 v73, v1
	v_lshl_add_u64 v[70:71], v[70:71], 0, v[72:73]
	s_waitcnt vmcnt(3)
	v_mov_b32_e32 v80, v190
	v_mov_b32_e32 v81, v191
	v_lshl_add_u64 v[82:83], v[68:69], 0, v[74:75]
	ds_read_b128 v[68:71], v0 offset:3456
	v_mov_b32_e32 v72, v180
	v_mov_b32_e32 v73, v181
	v_mov_b32_e32 v74, v182
	v_mov_b32_e32 v75, v183
	s_nop 0
	v_mov_b32_e32 v76, v208
	v_mov_b32_e32 v77, v209
	v_mov_b32_e32 v78, v210
	v_mov_b32_e32 v79, v211
	v_and_b32_e32 v67, 0xffff0000, v80
	v_lshlrev_b32_e32 v66, 16, v80
	v_pk_add_f32 v[66:67], v[76:77], v[66:67]
	s_waitcnt lgkmcnt(0)
	v_pk_fma_f32 v[66:67], v[68:69], v[72:73], v[66:67]
	v_and_b32_e32 v69, 0xffff0000, v81
	v_lshlrev_b32_e32 v68, 16, v81
	v_pk_add_f32 v[68:69], v[78:79], v[68:69]
	s_nop 0
	v_pk_fma_f32 v[68:69], v[70:71], v[74:75], v[68:69]
	global_store_dwordx4 v[82:83], v[66:69], off offset:128 sc1
	s_nop 1
	v_or_b32_e32 v66, 64, v130
	v_add_u32_e32 v0, v66, v155
	v_ashrrev_i32_e32 v0, 14, v0
	v_mul_i32_i24_e32 v67, 0x4000, v0
	v_sub_u32_e32 v67, v66, v67
	v_add_u32_e32 v72, 0x100, v67
	v_mul_i32_i24_e32 v68, 0xc00, v0
	v_mul_hi_i32_i24_e32 v71, 0x4100, v0
	v_mul_i32_i24_e32 v70, 0x4100, v0
	v_ashrrev_i32_e32 v73, 31, v72
	v_mov_b32_e32 v0, v179
	v_lshl_add_u64 v[70:71], v[70:71], 0, v[72:73]
	v_ashrrev_i32_e32 v69, 31, v68
	v_and_b32_e32 v72, 31, v0
	v_bfe_u32 v73, v0, 5, 1
	v_mul_u32_u24_e32 v73, 0x240, v73
	v_lshlrev_b32_e32 v72, 2, v72
	v_add3_u32 v72, v151, v73, v72
	ds_write2_b32 v72, v50, v51 offset1:36
	ds_write2_b32 v72, v52, v53 offset0:72 offset1:108
	v_add_u32_e32 v50, 0x400, v72
	ds_write2_b32 v50, v54, v55 offset0:32 offset1:68
	ds_write2_b32 v50, v56, v57 offset0:104 offset1:140
	v_add_u32_e32 v50, 0x800, v72
	ds_write2_b32 v50, v58, v59 offset0:64 offset1:100
	ds_write2_b32 v50, v60, v61 offset0:136 offset1:172
	v_add_u32_e32 v50, 0xc00, v72
	v_lshlrev_b64 v[70:71], 11, v[70:71]
	v_ashrrev_i32_e32 v67, 31, v66
	ds_write2_b32 v50, v62, v63 offset0:96 offset1:132
	ds_write2_b32 v50, v64, v65 offset0:168 offset1:204
	v_lshl_add_u64 v[50:51], v[68:69], 2, s[54:55]
	v_lshlrev_b32_e32 v60, 2, v0
	v_lshl_add_u64 v[54:55], v[50:51], 0, s[2:3]
	v_lshl_add_u64 v[50:51], s[0:1], 0, v[70:71]
	v_lshlrev_b64 v[52:53], 12, v[66:67]
	v_and_b32_e32 v60, 28, v60
	v_lshl_add_u64 v[50:51], v[50:51], 0, v[116:117]
	v_lshl_add_u64 v[56:57], s[36:37], 0, v[52:53]
	v_lshl_add_u64 v[52:53], s[52:53], 0, v[52:53]
	v_lshlrev_b32_e32 v66, 2, v60
	v_lshlrev_b32_e32 v60, 1, v60
	v_mov_b32_e32 v61, v1
	v_bfe_u32 v84, v0, 3, 3
	v_lshl_add_u64 v[58:59], v[54:55], 0, v[114:115]
	v_lshl_add_u64 v[56:57], v[56:57], 0, v[114:115]
	v_lshl_add_u64 v[52:53], v[52:53], 0, v[114:115]
	v_mov_b32_e32 v67, v1
	v_lshl_add_u64 v[62:63], v[50:51], 0, v[60:61]
	v_mul_u32_u24_e32 v0, 0x90, v84
	v_lshlrev_b32_e32 v68, 11, v84
	v_mov_b32_e32 v69, v1
	s_waitcnt lgkmcnt(0)
	v_lshl_add_u64 v[58:59], v[58:59], 0, v[66:67]
	v_lshl_add_u64 v[64:65], v[56:57], 0, v[66:67]
	v_lshl_add_u64 v[60:61], v[52:53], 0, v[66:67]
	v_add3_u32 v0, v151, v66, v0
	v_lshlrev_b32_e32 v66, 12, v84
	v_lshl_add_u64 v[68:69], v[62:63], 0, v[68:69]
	v_lshl_add_u64 v[74:75], v[64:65], 0, v[66:67]
	global_load_dwordx4 v[180:183], v[58:59], off
	v_mov_b32_e32 v212, v84
	v_lshlrev_b32_e32 v184, 11, v212
	v_mov_b32_e32 v185, v1
	v_lshl_add_u64 v[184:185], v[62:63], 0, v[184:185]
	global_load_dwordx2 v[184:185], v[184:185], off
	v_lshlrev_b32_e32 v192, 12, v212
	v_mov_b32_e32 v193, v1
	v_lshl_add_u64 v[192:193], v[64:65], 0, v[192:193]
	global_load_dwordx4 v[192:195], v[192:193], off
	v_or_b32_e32 v212, 8, v84
	v_lshlrev_b32_e32 v186, 11, v212
	v_mov_b32_e32 v187, v1
	v_lshl_add_u64 v[186:187], v[62:63], 0, v[186:187]
	global_load_dwordx2 v[186:187], v[186:187], off
	v_lshlrev_b32_e32 v200, 12, v212
	v_mov_b32_e32 v201, v1
	v_lshl_add_u64 v[200:201], v[64:65], 0, v[200:201]
	global_load_dwordx4 v[200:203], v[200:201], off
	v_or_b32_e32 v212, 16, v84
	v_lshlrev_b32_e32 v188, 11, v212
	v_mov_b32_e32 v189, v1
	v_lshl_add_u64 v[188:189], v[62:63], 0, v[188:189]
	global_load_dwordx2 v[188:189], v[188:189], off
	v_lshlrev_b32_e32 v204, 12, v212
	v_mov_b32_e32 v205, v1
	v_lshl_add_u64 v[204:205], v[64:65], 0, v[204:205]
	global_load_dwordx4 v[204:207], v[204:205], off
	v_or_b32_e32 v212, 24, v84
	v_lshlrev_b32_e32 v190, 11, v212
	v_mov_b32_e32 v191, v1
	v_lshl_add_u64 v[190:191], v[62:63], 0, v[190:191]
	global_load_dwordx2 v[190:191], v[190:191], off
	v_lshlrev_b32_e32 v208, 12, v212
	v_mov_b32_e32 v209, v1
	v_lshl_add_u64 v[208:209], v[64:65], 0, v[208:209]
	global_load_dwordx4 v[208:211], v[208:209], off
	s_waitcnt vmcnt(6)
	v_mov_b32_e32 v78, v184
	v_mov_b32_e32 v79, v185
	v_lshl_add_u64 v[80:81], v[60:61], 0, v[66:67]
	ds_read_b128 v[66:69], v0
	v_mov_b32_e32 v70, v180
	v_mov_b32_e32 v71, v181
	v_mov_b32_e32 v72, v182
	v_mov_b32_e32 v73, v183
	s_nop 0
	v_mov_b32_e32 v74, v192
	v_mov_b32_e32 v75, v193
	v_mov_b32_e32 v76, v194
	v_mov_b32_e32 v77, v195
	v_and_b32_e32 v83, 0xffff0000, v78
	v_lshlrev_b32_e32 v82, 16, v78
	v_pk_add_f32 v[74:75], v[74:75], v[82:83]
	s_waitcnt lgkmcnt(0)
	v_pk_fma_f32 v[66:67], v[66:67], v[70:71], v[74:75]
	v_and_b32_e32 v71, 0xffff0000, v79
	v_lshlrev_b32_e32 v70, 16, v79
	v_pk_add_f32 v[70:71], v[76:77], v[70:71]
	s_nop 0
	v_pk_fma_f32 v[68:69], v[68:69], v[72:73], v[70:71]
	global_store_dwordx4 v[80:81], v[66:69], off sc1
	s_nop 1
	v_or_b32_e32 v68, 8, v84
	v_lshlrev_b32_e32 v66, 12, v68
	v_lshlrev_b32_e32 v68, 11, v68
	v_mov_b32_e32 v69, v1
	v_mov_b32_e32 v67, v1
	v_lshl_add_u64 v[68:69], v[62:63], 0, v[68:69]
	v_lshl_add_u64 v[74:75], v[64:65], 0, v[66:67]
	s_waitcnt vmcnt(5)
	v_mov_b32_e32 v78, v186
	v_mov_b32_e32 v79, v187
	v_lshl_add_u64 v[80:81], v[60:61], 0, v[66:67]
	ds_read_b128 v[66:69], v0 offset:1152
	v_mov_b32_e32 v70, v180
	v_mov_b32_e32 v71, v181
	v_mov_b32_e32 v72, v182
	v_mov_b32_e32 v73, v183
	s_nop 0
	v_mov_b32_e32 v74, v200
	v_mov_b32_e32 v75, v201
	v_mov_b32_e32 v76, v202
	v_mov_b32_e32 v77, v203
	v_and_b32_e32 v83, 0xffff0000, v78
	v_lshlrev_b32_e32 v82, 16, v78
	v_pk_add_f32 v[74:75], v[74:75], v[82:83]
	s_waitcnt lgkmcnt(0)
	v_pk_fma_f32 v[66:67], v[66:67], v[70:71], v[74:75]
	v_and_b32_e32 v71, 0xffff0000, v79
	v_lshlrev_b32_e32 v70, 16, v79
	v_pk_add_f32 v[70:71], v[76:77], v[70:71]
	s_nop 0
	v_pk_fma_f32 v[68:69], v[68:69], v[72:73], v[70:71]
	global_store_dwordx4 v[80:81], v[66:69], off sc1
	s_nop 1
	v_or_b32_e32 v68, 16, v84
	v_lshlrev_b32_e32 v66, 12, v68
	v_lshlrev_b32_e32 v68, 11, v68
	v_mov_b32_e32 v69, v1
	v_mov_b32_e32 v67, v1
	v_lshl_add_u64 v[68:69], v[62:63], 0, v[68:69]
	v_lshl_add_u64 v[74:75], v[64:65], 0, v[66:67]
	s_waitcnt vmcnt(4)
	v_mov_b32_e32 v78, v188
	v_mov_b32_e32 v79, v189
	v_lshl_add_u64 v[80:81], v[60:61], 0, v[66:67]
	ds_read_b128 v[66:69], v0 offset:2304
	v_mov_b32_e32 v70, v180
	v_mov_b32_e32 v71, v181
	v_mov_b32_e32 v72, v182
	v_mov_b32_e32 v73, v183
	s_nop 0
	v_mov_b32_e32 v74, v204
	v_mov_b32_e32 v75, v205
	v_mov_b32_e32 v76, v206
	v_mov_b32_e32 v77, v207
	v_and_b32_e32 v83, 0xffff0000, v78
	v_lshlrev_b32_e32 v82, 16, v78
	v_pk_add_f32 v[74:75], v[74:75], v[82:83]
	s_waitcnt lgkmcnt(0)
	v_pk_fma_f32 v[66:67], v[66:67], v[70:71], v[74:75]
	v_and_b32_e32 v71, 0xffff0000, v79
	v_lshlrev_b32_e32 v70, 16, v79
	v_pk_add_f32 v[70:71], v[76:77], v[70:71]
	s_nop 0
	v_pk_fma_f32 v[68:69], v[68:69], v[72:73], v[70:71]
	v_or_b32_e32 v70, 24, v84
	global_store_dwordx4 v[80:81], v[66:69], off sc1
	s_nop 1
	v_lshlrev_b32_e32 v66, 12, v70
	v_mov_b32_e32 v67, v1
	v_lshl_add_u64 v[68:69], v[64:65], 0, v[66:67]
	v_lshlrev_b32_e32 v64, 11, v70
	v_mov_b32_e32 v65, v1
	v_lshl_add_u64 v[62:63], v[62:63], 0, v[64:65]
	s_waitcnt vmcnt(3)
	v_mov_b32_e32 v72, v190
	v_mov_b32_e32 v73, v191
	v_lshl_add_u64 v[74:75], v[60:61], 0, v[66:67]
	ds_read_b128 v[60:63], v0 offset:3456
	v_mov_b32_e32 v64, v180
	v_mov_b32_e32 v65, v181
	v_mov_b32_e32 v66, v182
	v_mov_b32_e32 v67, v183
	s_nop 0
	v_mov_b32_e32 v68, v208
	v_mov_b32_e32 v69, v209
	v_mov_b32_e32 v70, v210
	v_mov_b32_e32 v71, v211
	v_and_b32_e32 v59, 0xffff0000, v72
	v_lshlrev_b32_e32 v58, 16, v72
	v_pk_add_f32 v[58:59], v[68:69], v[58:59]
	s_waitcnt lgkmcnt(0)
	v_pk_fma_f32 v[58:59], v[60:61], v[64:65], v[58:59]
	v_and_b32_e32 v61, 0xffff0000, v73
	v_lshlrev_b32_e32 v60, 16, v73
	v_pk_add_f32 v[60:61], v[70:71], v[60:61]
	s_nop 0
	v_pk_fma_f32 v[60:61], v[62:63], v[66:67], v[60:61]
	global_store_dwordx4 v[74:75], v[58:61], off sc1
	v_mov_b32_e32 v0, v179
	s_nop 0
	v_and_b32_e32 v58, 31, v0
	v_bfe_u32 v59, v0, 5, 1
	v_mul_u32_u24_e32 v59, 0x240, v59
	v_lshlrev_b32_e32 v58, 2, v58
	v_add3_u32 v58, v151, v59, v58
	ds_write2_b32 v58, v34, v35 offset1:36
	ds_write2_b32 v58, v36, v37 offset0:72 offset1:108
	v_add_u32_e32 v34, 0x400, v58
	ds_write2_b32 v34, v38, v39 offset0:32 offset1:68
	ds_write2_b32 v34, v40, v41 offset0:104 offset1:140
	v_add_u32_e32 v34, 0x800, v58
	ds_write2_b32 v34, v42, v43 offset0:64 offset1:100
	ds_write2_b32 v34, v44, v45 offset0:136 offset1:172
	v_add_u32_e32 v34, 0xc00, v58
	ds_write2_b32 v34, v46, v47 offset0:96 offset1:132
	ds_write2_b32 v34, v48, v49 offset0:168 offset1:204
	v_lshlrev_b32_e32 v34, 2, v0
	v_and_b32_e32 v36, 28, v34
	v_lshlrev_b32_e32 v42, 2, v36
	v_lshlrev_b32_e32 v36, 1, v36
	v_mov_b32_e32 v37, v1
	v_bfe_u32 v60, v0, 3, 3
	v_mov_b32_e32 v43, v1
	v_lshl_add_u64 v[38:39], v[50:51], 0, v[36:37]
	v_mul_u32_u24_e32 v0, 0x90, v60
	v_lshlrev_b32_e32 v44, 11, v60
	v_mov_b32_e32 v45, v1
	s_waitcnt lgkmcnt(0)
	v_lshl_add_u64 v[34:35], v[54:55], 0, v[42:43]
	v_lshl_add_u64 v[40:41], v[56:57], 0, v[42:43]
	v_lshl_add_u64 v[36:37], v[52:53], 0, v[42:43]
	v_add3_u32 v0, v151, v42, v0
	v_lshlrev_b32_e32 v42, 12, v60
	v_lshl_add_u64 v[44:45], v[38:39], 0, v[44:45]
	v_lshl_add_u64 v[34:35], v[34:35], 0, v[98:99]
	v_lshl_add_u64 v[50:51], v[40:41], 0, v[42:43]
	global_load_dwordx4 v[180:183], v[34:35], off
	v_mov_b32_e32 v212, v60
	v_lshlrev_b32_e32 v184, 11, v212
	v_mov_b32_e32 v185, v1
	v_lshl_add_u64 v[184:185], v[38:39], 0, v[184:185]
	global_load_dwordx2 v[184:185], v[184:185], off offset:64
	v_lshlrev_b32_e32 v192, 12, v212
	v_mov_b32_e32 v193, v1
	v_lshl_add_u64 v[192:193], v[40:41], 0, v[192:193]
	global_load_dwordx4 v[192:195], v[192:193], off offset:128
	v_or_b32_e32 v212, 8, v60
	v_lshlrev_b32_e32 v186, 11, v212
	v_mov_b32_e32 v187, v1
	v_lshl_add_u64 v[186:187], v[38:39], 0, v[186:187]
	global_load_dwordx2 v[186:187], v[186:187], off offset:64
	v_lshlrev_b32_e32 v200, 12, v212
	v_mov_b32_e32 v201, v1
	v_lshl_add_u64 v[200:201], v[40:41], 0, v[200:201]
	global_load_dwordx4 v[200:203], v[200:201], off offset:128
	v_or_b32_e32 v212, 16, v60
	v_lshlrev_b32_e32 v188, 11, v212
	v_mov_b32_e32 v189, v1
	v_lshl_add_u64 v[188:189], v[38:39], 0, v[188:189]
	global_load_dwordx2 v[188:189], v[188:189], off offset:64
	v_lshlrev_b32_e32 v204, 12, v212
	v_mov_b32_e32 v205, v1
	v_lshl_add_u64 v[204:205], v[40:41], 0, v[204:205]
	global_load_dwordx4 v[204:207], v[204:205], off offset:128
	v_or_b32_e32 v212, 24, v60
	v_lshlrev_b32_e32 v190, 11, v212
	v_mov_b32_e32 v191, v1
	v_lshl_add_u64 v[190:191], v[38:39], 0, v[190:191]
	global_load_dwordx2 v[190:191], v[190:191], off offset:64
	v_lshlrev_b32_e32 v208, 12, v212
	v_mov_b32_e32 v209, v1
	v_lshl_add_u64 v[208:209], v[40:41], 0, v[208:209]
	global_load_dwordx4 v[208:211], v[208:209], off offset:128
	s_waitcnt vmcnt(6)
	v_mov_b32_e32 v54, v184
	v_mov_b32_e32 v55, v185
	v_lshl_add_u64 v[56:57], v[36:37], 0, v[42:43]
	ds_read_b128 v[42:45], v0
	v_mov_b32_e32 v46, v180
	v_mov_b32_e32 v47, v181
	v_mov_b32_e32 v48, v182
	v_mov_b32_e32 v49, v183
	s_nop 0
	v_mov_b32_e32 v50, v192
	v_mov_b32_e32 v51, v193
	v_mov_b32_e32 v52, v194
	v_mov_b32_e32 v53, v195
	v_and_b32_e32 v59, 0xffff0000, v54
	v_lshlrev_b32_e32 v58, 16, v54
	v_pk_add_f32 v[50:51], v[50:51], v[58:59]
	s_waitcnt lgkmcnt(0)
	v_pk_fma_f32 v[42:43], v[42:43], v[46:47], v[50:51]
	v_and_b32_e32 v47, 0xffff0000, v55
	v_lshlrev_b32_e32 v46, 16, v55
	v_pk_add_f32 v[46:47], v[52:53], v[46:47]
	s_nop 0
	v_pk_fma_f32 v[44:45], v[44:45], v[48:49], v[46:47]
	global_store_dwordx4 v[56:57], v[42:45], off offset:128 sc1
	s_nop 1
	v_or_b32_e32 v44, 8, v60
	v_lshlrev_b32_e32 v42, 12, v44
	v_lshlrev_b32_e32 v44, 11, v44
	v_mov_b32_e32 v45, v1
	v_mov_b32_e32 v43, v1
	v_lshl_add_u64 v[44:45], v[38:39], 0, v[44:45]
	v_lshl_add_u64 v[50:51], v[40:41], 0, v[42:43]
	s_waitcnt vmcnt(5)
	v_mov_b32_e32 v54, v186
	v_mov_b32_e32 v55, v187
	v_lshl_add_u64 v[56:57], v[36:37], 0, v[42:43]
	ds_read_b128 v[42:45], v0 offset:1152
	v_mov_b32_e32 v46, v180
	v_mov_b32_e32 v47, v181
	v_mov_b32_e32 v48, v182
	v_mov_b32_e32 v49, v183
	s_nop 0
	v_mov_b32_e32 v50, v200
	v_mov_b32_e32 v51, v201
	v_mov_b32_e32 v52, v202
	v_mov_b32_e32 v53, v203
	v_and_b32_e32 v59, 0xffff0000, v54
	v_lshlrev_b32_e32 v58, 16, v54
	v_pk_add_f32 v[50:51], v[50:51], v[58:59]
	s_waitcnt lgkmcnt(0)
	v_pk_fma_f32 v[42:43], v[42:43], v[46:47], v[50:51]
	v_and_b32_e32 v47, 0xffff0000, v55
	v_lshlrev_b32_e32 v46, 16, v55
	v_pk_add_f32 v[46:47], v[52:53], v[46:47]
	s_nop 0
	v_pk_fma_f32 v[44:45], v[44:45], v[48:49], v[46:47]
	global_store_dwordx4 v[56:57], v[42:45], off offset:128 sc1
	s_nop 1
	v_or_b32_e32 v44, 16, v60
	v_lshlrev_b32_e32 v42, 12, v44
	v_lshlrev_b32_e32 v44, 11, v44
	v_mov_b32_e32 v45, v1
	v_mov_b32_e32 v43, v1
	v_lshl_add_u64 v[44:45], v[38:39], 0, v[44:45]
	v_lshl_add_u64 v[50:51], v[40:41], 0, v[42:43]
	s_waitcnt vmcnt(4)
	v_mov_b32_e32 v54, v188
	v_mov_b32_e32 v55, v189
	v_lshl_add_u64 v[56:57], v[36:37], 0, v[42:43]
	ds_read_b128 v[42:45], v0 offset:2304
	v_mov_b32_e32 v46, v180
	v_mov_b32_e32 v47, v181
	v_mov_b32_e32 v48, v182
	v_mov_b32_e32 v49, v183
	s_nop 0
	v_mov_b32_e32 v50, v204
	v_mov_b32_e32 v51, v205
	v_mov_b32_e32 v52, v206
	v_mov_b32_e32 v53, v207
	v_and_b32_e32 v59, 0xffff0000, v54
	v_lshlrev_b32_e32 v58, 16, v54
	v_pk_add_f32 v[50:51], v[50:51], v[58:59]
	s_waitcnt lgkmcnt(0)
	v_pk_fma_f32 v[42:43], v[42:43], v[46:47], v[50:51]
	v_and_b32_e32 v47, 0xffff0000, v55
	v_lshlrev_b32_e32 v46, 16, v55
	v_pk_add_f32 v[46:47], v[52:53], v[46:47]
	s_nop 0
	v_pk_fma_f32 v[44:45], v[44:45], v[48:49], v[46:47]
	v_or_b32_e32 v46, 24, v60
	global_store_dwordx4 v[56:57], v[42:45], off offset:128 sc1
	s_nop 1
	v_lshlrev_b32_e32 v42, 12, v46
	v_mov_b32_e32 v43, v1
	v_lshl_add_u64 v[44:45], v[40:41], 0, v[42:43]
	v_lshlrev_b32_e32 v40, 11, v46
	v_mov_b32_e32 v41, v1
	v_lshl_add_u64 v[38:39], v[38:39], 0, v[40:41]
	s_waitcnt vmcnt(3)
	v_mov_b32_e32 v48, v190
	v_mov_b32_e32 v49, v191
	v_lshl_add_u64 v[50:51], v[36:37], 0, v[42:43]
	ds_read_b128 v[36:39], v0 offset:3456
	v_mov_b32_e32 v40, v180
	v_mov_b32_e32 v41, v181
	v_mov_b32_e32 v42, v182
	v_mov_b32_e32 v43, v183
	s_nop 0
	v_mov_b32_e32 v44, v208
	v_mov_b32_e32 v45, v209
	v_mov_b32_e32 v46, v210
	v_mov_b32_e32 v47, v211
	v_and_b32_e32 v35, 0xffff0000, v48
	v_lshlrev_b32_e32 v34, 16, v48
	v_pk_add_f32 v[34:35], v[44:45], v[34:35]
	s_waitcnt lgkmcnt(0)
	v_pk_fma_f32 v[34:35], v[36:37], v[40:41], v[34:35]
	v_and_b32_e32 v37, 0xffff0000, v49
	v_lshlrev_b32_e32 v36, 16, v49
	v_pk_add_f32 v[36:37], v[46:47], v[36:37]
	s_nop 0
	v_pk_fma_f32 v[36:37], v[38:39], v[42:43], v[36:37]
	global_store_dwordx4 v[50:51], v[34:37], off offset:128 sc1
	s_nop 1
	v_or_b32_e32 v34, 0x60, v130
	v_add_u32_e32 v0, v34, v155
	v_ashrrev_i32_e32 v0, 14, v0
	v_mul_i32_i24_e32 v35, 0x4000, v0
	v_sub_u32_e32 v35, v34, v35
	v_add_u32_e32 v40, 0x100, v35
	v_mul_i32_i24_e32 v36, 0xc00, v0
	v_mul_hi_i32_i24_e32 v39, 0x4100, v0
	v_mul_i32_i24_e32 v38, 0x4100, v0
	v_ashrrev_i32_e32 v41, 31, v40
	v_mov_b32_e32 v0, v179
	v_lshl_add_u64 v[38:39], v[38:39], 0, v[40:41]
	v_ashrrev_i32_e32 v37, 31, v36
	v_and_b32_e32 v40, 31, v0
	v_bfe_u32 v41, v0, 5, 1
	v_mul_u32_u24_e32 v41, 0x240, v41
	v_lshlrev_b32_e32 v40, 2, v40
	v_add3_u32 v40, v151, v41, v40
	ds_write2_b32 v40, v18, v19 offset1:36
	ds_write2_b32 v40, v20, v21 offset0:72 offset1:108
	v_add_u32_e32 v18, 0x400, v40
	ds_write2_b32 v18, v22, v23 offset0:32 offset1:68
	ds_write2_b32 v18, v24, v25 offset0:104 offset1:140
	v_add_u32_e32 v18, 0x800, v40
	ds_write2_b32 v18, v26, v27 offset0:64 offset1:100
	ds_write2_b32 v18, v28, v29 offset0:136 offset1:172
	v_add_u32_e32 v18, 0xc00, v40
	v_lshlrev_b64 v[38:39], 11, v[38:39]
	v_ashrrev_i32_e32 v35, 31, v34
	ds_write2_b32 v18, v30, v31 offset0:96 offset1:132
	ds_write2_b32 v18, v32, v33 offset0:168 offset1:204
	v_lshl_add_u64 v[18:19], v[36:37], 2, s[54:55]
	v_lshlrev_b32_e32 v28, 2, v0
	v_lshl_add_u64 v[20:21], v[18:19], 0, s[2:3]
	v_lshl_add_u64 v[18:19], s[0:1], 0, v[38:39]
	v_lshlrev_b64 v[22:23], 12, v[34:35]
	v_and_b32_e32 v28, 28, v28
	v_lshl_add_u64 v[18:19], v[18:19], 0, v[116:117]
	v_lshl_add_u64 v[24:25], s[36:37], 0, v[22:23]
	v_lshl_add_u64 v[22:23], s[52:53], 0, v[22:23]
	v_lshlrev_b32_e32 v34, 2, v28
	v_lshlrev_b32_e32 v28, 1, v28
	v_mov_b32_e32 v29, v1
	v_bfe_u32 v52, v0, 3, 3
	v_lshl_add_u64 v[26:27], v[20:21], 0, v[114:115]
	v_lshl_add_u64 v[24:25], v[24:25], 0, v[114:115]
	v_lshl_add_u64 v[22:23], v[22:23], 0, v[114:115]
	v_mov_b32_e32 v35, v1
	v_lshl_add_u64 v[30:31], v[18:19], 0, v[28:29]
	v_mul_u32_u24_e32 v0, 0x90, v52
	v_lshlrev_b32_e32 v36, 11, v52
	v_mov_b32_e32 v37, v1
	s_waitcnt lgkmcnt(0)
	v_lshl_add_u64 v[26:27], v[26:27], 0, v[34:35]
	v_lshl_add_u64 v[32:33], v[24:25], 0, v[34:35]
	v_lshl_add_u64 v[28:29], v[22:23], 0, v[34:35]
	v_add3_u32 v0, v151, v34, v0
	v_lshlrev_b32_e32 v34, 12, v52
	v_lshl_add_u64 v[36:37], v[30:31], 0, v[36:37]
	v_lshl_add_u64 v[42:43], v[32:33], 0, v[34:35]
	global_load_dwordx4 v[180:183], v[26:27], off
	v_mov_b32_e32 v212, v52
	v_lshlrev_b32_e32 v184, 11, v212
	v_mov_b32_e32 v185, v1
	v_lshl_add_u64 v[184:185], v[30:31], 0, v[184:185]
	global_load_dwordx2 v[184:185], v[184:185], off
	v_lshlrev_b32_e32 v192, 12, v212
	v_mov_b32_e32 v193, v1
	v_lshl_add_u64 v[192:193], v[32:33], 0, v[192:193]
	global_load_dwordx4 v[192:195], v[192:193], off
	v_or_b32_e32 v212, 8, v52
	v_lshlrev_b32_e32 v186, 11, v212
	v_mov_b32_e32 v187, v1
	v_lshl_add_u64 v[186:187], v[30:31], 0, v[186:187]
	global_load_dwordx2 v[186:187], v[186:187], off
	v_lshlrev_b32_e32 v200, 12, v212
	v_mov_b32_e32 v201, v1
	v_lshl_add_u64 v[200:201], v[32:33], 0, v[200:201]
	global_load_dwordx4 v[200:203], v[200:201], off
	v_or_b32_e32 v212, 16, v52
	v_lshlrev_b32_e32 v188, 11, v212
	v_mov_b32_e32 v189, v1
	v_lshl_add_u64 v[188:189], v[30:31], 0, v[188:189]
	global_load_dwordx2 v[188:189], v[188:189], off
	v_lshlrev_b32_e32 v204, 12, v212
	v_mov_b32_e32 v205, v1
	v_lshl_add_u64 v[204:205], v[32:33], 0, v[204:205]
	global_load_dwordx4 v[204:207], v[204:205], off
	v_or_b32_e32 v212, 24, v52
	v_lshlrev_b32_e32 v190, 11, v212
	v_mov_b32_e32 v191, v1
	v_lshl_add_u64 v[190:191], v[30:31], 0, v[190:191]
	global_load_dwordx2 v[190:191], v[190:191], off
	v_lshlrev_b32_e32 v208, 12, v212
	v_mov_b32_e32 v209, v1
	v_lshl_add_u64 v[208:209], v[32:33], 0, v[208:209]
	global_load_dwordx4 v[208:211], v[208:209], off
	s_waitcnt vmcnt(6)
	v_mov_b32_e32 v46, v184
	v_mov_b32_e32 v47, v185
	v_lshl_add_u64 v[48:49], v[28:29], 0, v[34:35]
	ds_read_b128 v[34:37], v0
	v_mov_b32_e32 v38, v180
	v_mov_b32_e32 v39, v181
	v_mov_b32_e32 v40, v182
	v_mov_b32_e32 v41, v183
	s_nop 0
	v_mov_b32_e32 v42, v192
	v_mov_b32_e32 v43, v193
	v_mov_b32_e32 v44, v194
	v_mov_b32_e32 v45, v195
	v_and_b32_e32 v51, 0xffff0000, v46
	v_lshlrev_b32_e32 v50, 16, v46
	v_pk_add_f32 v[42:43], v[42:43], v[50:51]
	s_waitcnt lgkmcnt(0)
	v_pk_fma_f32 v[34:35], v[34:35], v[38:39], v[42:43]
	v_and_b32_e32 v39, 0xffff0000, v47
	v_lshlrev_b32_e32 v38, 16, v47
	v_pk_add_f32 v[38:39], v[44:45], v[38:39]
	s_nop 0
	v_pk_fma_f32 v[36:37], v[36:37], v[40:41], v[38:39]
	global_store_dwordx4 v[48:49], v[34:37], off sc1
	s_nop 1
	v_or_b32_e32 v36, 8, v52
	v_lshlrev_b32_e32 v34, 12, v36
	v_lshlrev_b32_e32 v36, 11, v36
	v_mov_b32_e32 v37, v1
	v_mov_b32_e32 v35, v1
	v_lshl_add_u64 v[36:37], v[30:31], 0, v[36:37]
	v_lshl_add_u64 v[42:43], v[32:33], 0, v[34:35]
	s_waitcnt vmcnt(5)
	v_mov_b32_e32 v46, v186
	v_mov_b32_e32 v47, v187
	v_lshl_add_u64 v[48:49], v[28:29], 0, v[34:35]
	ds_read_b128 v[34:37], v0 offset:1152
	v_mov_b32_e32 v38, v180
	v_mov_b32_e32 v39, v181
	v_mov_b32_e32 v40, v182
	v_mov_b32_e32 v41, v183
	s_nop 0
	v_mov_b32_e32 v42, v200
	v_mov_b32_e32 v43, v201
	v_mov_b32_e32 v44, v202
	v_mov_b32_e32 v45, v203
	v_and_b32_e32 v51, 0xffff0000, v46
	v_lshlrev_b32_e32 v50, 16, v46
	v_pk_add_f32 v[42:43], v[42:43], v[50:51]
	s_waitcnt lgkmcnt(0)
	v_pk_fma_f32 v[34:35], v[34:35], v[38:39], v[42:43]
	v_and_b32_e32 v39, 0xffff0000, v47
	v_lshlrev_b32_e32 v38, 16, v47
	v_pk_add_f32 v[38:39], v[44:45], v[38:39]
	s_nop 0
	v_pk_fma_f32 v[36:37], v[36:37], v[40:41], v[38:39]
	global_store_dwordx4 v[48:49], v[34:37], off sc1
	s_nop 1
	v_or_b32_e32 v36, 16, v52
	v_lshlrev_b32_e32 v34, 12, v36
	v_lshlrev_b32_e32 v36, 11, v36
	v_mov_b32_e32 v37, v1
	v_mov_b32_e32 v35, v1
	v_lshl_add_u64 v[36:37], v[30:31], 0, v[36:37]
	v_lshl_add_u64 v[42:43], v[32:33], 0, v[34:35]
	s_waitcnt vmcnt(4)
	v_mov_b32_e32 v46, v188
	v_mov_b32_e32 v47, v189
	v_lshl_add_u64 v[48:49], v[28:29], 0, v[34:35]
	ds_read_b128 v[34:37], v0 offset:2304
	v_mov_b32_e32 v38, v180
	v_mov_b32_e32 v39, v181
	v_mov_b32_e32 v40, v182
	v_mov_b32_e32 v41, v183
	s_nop 0
	v_mov_b32_e32 v42, v204
	v_mov_b32_e32 v43, v205
	v_mov_b32_e32 v44, v206
	v_mov_b32_e32 v45, v207
	v_and_b32_e32 v51, 0xffff0000, v46
	v_lshlrev_b32_e32 v50, 16, v46
	v_pk_add_f32 v[42:43], v[42:43], v[50:51]
	s_waitcnt lgkmcnt(0)
	v_pk_fma_f32 v[34:35], v[34:35], v[38:39], v[42:43]
	v_and_b32_e32 v39, 0xffff0000, v47
	v_lshlrev_b32_e32 v38, 16, v47
	v_pk_add_f32 v[38:39], v[44:45], v[38:39]
	s_nop 0
	v_pk_fma_f32 v[36:37], v[36:37], v[40:41], v[38:39]
	v_or_b32_e32 v38, 24, v52
	global_store_dwordx4 v[48:49], v[34:37], off sc1
	s_nop 1
	v_lshlrev_b32_e32 v34, 12, v38
	v_mov_b32_e32 v35, v1
	v_lshl_add_u64 v[36:37], v[32:33], 0, v[34:35]
	v_lshlrev_b32_e32 v32, 11, v38
	v_mov_b32_e32 v33, v1
	v_lshl_add_u64 v[30:31], v[30:31], 0, v[32:33]
	s_waitcnt vmcnt(3)
	v_mov_b32_e32 v40, v190
	v_mov_b32_e32 v41, v191
	v_lshl_add_u64 v[42:43], v[28:29], 0, v[34:35]
	ds_read_b128 v[28:31], v0 offset:3456
	v_mov_b32_e32 v32, v180
	v_mov_b32_e32 v33, v181
	v_mov_b32_e32 v34, v182
	v_mov_b32_e32 v35, v183
	s_nop 0
	v_mov_b32_e32 v36, v208
	v_mov_b32_e32 v37, v209
	v_mov_b32_e32 v38, v210
	v_mov_b32_e32 v39, v211
	v_and_b32_e32 v27, 0xffff0000, v40
	v_lshlrev_b32_e32 v26, 16, v40
	v_pk_add_f32 v[26:27], v[36:37], v[26:27]
	s_waitcnt lgkmcnt(0)
	v_pk_fma_f32 v[26:27], v[28:29], v[32:33], v[26:27]
	v_and_b32_e32 v29, 0xffff0000, v41
	v_lshlrev_b32_e32 v28, 16, v41
	v_pk_add_f32 v[28:29], v[38:39], v[28:29]
	s_nop 0
	v_pk_fma_f32 v[28:29], v[30:31], v[34:35], v[28:29]
	global_store_dwordx4 v[42:43], v[26:29], off sc1
	v_mov_b32_e32 v0, v179
	s_nop 0
	v_and_b32_e32 v26, 31, v0
	v_bfe_u32 v27, v0, 5, 1
	v_mul_u32_u24_e32 v27, 0x240, v27
	v_lshlrev_b32_e32 v26, 2, v26
	v_add3_u32 v26, v151, v27, v26
	ds_write2_b32 v26, v2, v3 offset1:36
	ds_write2_b32 v26, v4, v5 offset0:72 offset1:108
	v_add_u32_e32 v2, 0x400, v26
	ds_write2_b32 v2, v6, v7 offset0:32 offset1:68
	ds_write2_b32 v2, v8, v9 offset0:104 offset1:140
	v_add_u32_e32 v2, 0x800, v26
	ds_write2_b32 v2, v10, v11 offset0:64 offset1:100
	ds_write2_b32 v2, v12, v13 offset0:136 offset1:172
	v_add_u32_e32 v2, 0xc00, v26
	ds_write2_b32 v2, v14, v15 offset0:96 offset1:132
	ds_write2_b32 v2, v16, v17 offset0:168 offset1:204
	v_lshlrev_b32_e32 v2, 2, v0
	v_and_b32_e32 v4, 28, v2
	v_lshlrev_b32_e32 v10, 2, v4
	v_lshlrev_b32_e32 v4, 1, v4
	v_mov_b32_e32 v5, v1
	v_bfe_u32 v28, v0, 3, 3
	v_mov_b32_e32 v11, v1
	v_lshl_add_u64 v[6:7], v[18:19], 0, v[4:5]
	v_mul_u32_u24_e32 v0, 0x90, v28
	v_lshlrev_b32_e32 v12, 11, v28
	v_mov_b32_e32 v13, v1
	s_waitcnt lgkmcnt(0)
	v_lshl_add_u64 v[2:3], v[20:21], 0, v[10:11]
	v_lshl_add_u64 v[8:9], v[24:25], 0, v[10:11]
	v_lshl_add_u64 v[4:5], v[22:23], 0, v[10:11]
	v_add3_u32 v0, v151, v10, v0
	v_lshlrev_b32_e32 v10, 12, v28
	v_lshl_add_u64 v[12:13], v[6:7], 0, v[12:13]
	v_lshl_add_u64 v[2:3], v[2:3], 0, v[98:99]
	v_lshl_add_u64 v[18:19], v[8:9], 0, v[10:11]
	global_load_dwordx4 v[180:183], v[2:3], off
	v_mov_b32_e32 v212, v28
	v_lshlrev_b32_e32 v184, 11, v212
	v_mov_b32_e32 v185, v1
	v_lshl_add_u64 v[184:185], v[6:7], 0, v[184:185]
	global_load_dwordx2 v[184:185], v[184:185], off offset:64
	v_lshlrev_b32_e32 v192, 12, v212
	v_mov_b32_e32 v193, v1
	v_lshl_add_u64 v[192:193], v[8:9], 0, v[192:193]
	global_load_dwordx4 v[192:195], v[192:193], off offset:128
	v_or_b32_e32 v212, 8, v28
	v_lshlrev_b32_e32 v186, 11, v212
	v_mov_b32_e32 v187, v1
	v_lshl_add_u64 v[186:187], v[6:7], 0, v[186:187]
	global_load_dwordx2 v[186:187], v[186:187], off offset:64
	v_lshlrev_b32_e32 v200, 12, v212
	v_mov_b32_e32 v201, v1
	v_lshl_add_u64 v[200:201], v[8:9], 0, v[200:201]
	global_load_dwordx4 v[200:203], v[200:201], off offset:128
	v_or_b32_e32 v212, 16, v28
	v_lshlrev_b32_e32 v188, 11, v212
	v_mov_b32_e32 v189, v1
	v_lshl_add_u64 v[188:189], v[6:7], 0, v[188:189]
	global_load_dwordx2 v[188:189], v[188:189], off offset:64
	v_lshlrev_b32_e32 v204, 12, v212
	v_mov_b32_e32 v205, v1
	v_lshl_add_u64 v[204:205], v[8:9], 0, v[204:205]
	global_load_dwordx4 v[204:207], v[204:205], off offset:128
	v_or_b32_e32 v212, 24, v28
	v_lshlrev_b32_e32 v190, 11, v212
	v_mov_b32_e32 v191, v1
	v_lshl_add_u64 v[190:191], v[6:7], 0, v[190:191]
	global_load_dwordx2 v[190:191], v[190:191], off offset:64
	v_lshlrev_b32_e32 v208, 12, v212
	v_mov_b32_e32 v209, v1
	v_lshl_add_u64 v[208:209], v[8:9], 0, v[208:209]
	global_load_dwordx4 v[208:211], v[208:209], off offset:128
	s_waitcnt vmcnt(6)
	v_mov_b32_e32 v22, v184
	v_mov_b32_e32 v23, v185
	v_lshl_add_u64 v[24:25], v[4:5], 0, v[10:11]
	ds_read_b128 v[10:13], v0
	v_mov_b32_e32 v14, v180
	v_mov_b32_e32 v15, v181
	v_mov_b32_e32 v16, v182
	v_mov_b32_e32 v17, v183
	s_nop 0
	v_mov_b32_e32 v18, v192
	v_mov_b32_e32 v19, v193
	v_mov_b32_e32 v20, v194
	v_mov_b32_e32 v21, v195
	v_and_b32_e32 v27, 0xffff0000, v22
	v_lshlrev_b32_e32 v26, 16, v22
	v_pk_add_f32 v[18:19], v[18:19], v[26:27]
	s_waitcnt lgkmcnt(0)
	v_pk_fma_f32 v[10:11], v[10:11], v[14:15], v[18:19]
	v_and_b32_e32 v15, 0xffff0000, v23
	v_lshlrev_b32_e32 v14, 16, v23
	v_pk_add_f32 v[14:15], v[20:21], v[14:15]
	s_nop 0
	v_pk_fma_f32 v[12:13], v[12:13], v[16:17], v[14:15]
	global_store_dwordx4 v[24:25], v[10:13], off offset:128 sc1
	s_nop 1
	v_or_b32_e32 v12, 8, v28
	v_lshlrev_b32_e32 v10, 12, v12
	v_lshlrev_b32_e32 v12, 11, v12
	v_mov_b32_e32 v13, v1
	v_mov_b32_e32 v11, v1
	v_lshl_add_u64 v[12:13], v[6:7], 0, v[12:13]
	v_lshl_add_u64 v[18:19], v[8:9], 0, v[10:11]
	s_waitcnt vmcnt(5)
	v_mov_b32_e32 v22, v186
	v_mov_b32_e32 v23, v187
	v_lshl_add_u64 v[24:25], v[4:5], 0, v[10:11]
	ds_read_b128 v[10:13], v0 offset:1152
	v_mov_b32_e32 v14, v180
	v_mov_b32_e32 v15, v181
	v_mov_b32_e32 v16, v182
	v_mov_b32_e32 v17, v183
	s_nop 0
	v_mov_b32_e32 v18, v200
	v_mov_b32_e32 v19, v201
	v_mov_b32_e32 v20, v202
	v_mov_b32_e32 v21, v203
	v_and_b32_e32 v27, 0xffff0000, v22
	v_lshlrev_b32_e32 v26, 16, v22
	v_pk_add_f32 v[18:19], v[18:19], v[26:27]
	s_waitcnt lgkmcnt(0)
	v_pk_fma_f32 v[10:11], v[10:11], v[14:15], v[18:19]
	v_and_b32_e32 v15, 0xffff0000, v23
	v_lshlrev_b32_e32 v14, 16, v23
	v_pk_add_f32 v[14:15], v[20:21], v[14:15]
	s_nop 0
	v_pk_fma_f32 v[12:13], v[12:13], v[16:17], v[14:15]
	global_store_dwordx4 v[24:25], v[10:13], off offset:128 sc1
	s_nop 1
	v_or_b32_e32 v12, 16, v28
	v_lshlrev_b32_e32 v10, 12, v12
	v_lshlrev_b32_e32 v12, 11, v12
	v_mov_b32_e32 v13, v1
	v_mov_b32_e32 v11, v1
	v_lshl_add_u64 v[12:13], v[6:7], 0, v[12:13]
	v_lshl_add_u64 v[18:19], v[8:9], 0, v[10:11]
	s_waitcnt vmcnt(4)
	v_mov_b32_e32 v22, v188
	v_mov_b32_e32 v23, v189
	v_lshl_add_u64 v[24:25], v[4:5], 0, v[10:11]
	ds_read_b128 v[10:13], v0 offset:2304
	v_mov_b32_e32 v14, v180
	v_mov_b32_e32 v15, v181
	v_mov_b32_e32 v16, v182
	v_mov_b32_e32 v17, v183
	s_nop 0
	v_mov_b32_e32 v18, v204
	v_mov_b32_e32 v19, v205
	v_mov_b32_e32 v20, v206
	v_mov_b32_e32 v21, v207
	v_and_b32_e32 v27, 0xffff0000, v22
	v_lshlrev_b32_e32 v26, 16, v22
	v_pk_add_f32 v[18:19], v[18:19], v[26:27]
	s_waitcnt lgkmcnt(0)
	v_pk_fma_f32 v[10:11], v[10:11], v[14:15], v[18:19]
	v_and_b32_e32 v15, 0xffff0000, v23
	v_lshlrev_b32_e32 v14, 16, v23
	v_pk_add_f32 v[14:15], v[20:21], v[14:15]
	s_nop 0
	v_pk_fma_f32 v[12:13], v[12:13], v[16:17], v[14:15]
	v_or_b32_e32 v14, 24, v28
	global_store_dwordx4 v[24:25], v[10:13], off offset:128 sc1
	s_nop 1
	v_lshlrev_b32_e32 v10, 12, v14
	v_mov_b32_e32 v11, v1
	v_lshl_add_u64 v[12:13], v[8:9], 0, v[10:11]
	v_lshlrev_b32_e32 v8, 11, v14
	v_mov_b32_e32 v9, v1
	v_lshl_add_u64 v[6:7], v[6:7], 0, v[8:9]
	s_waitcnt vmcnt(3)
	v_mov_b32_e32 v16, v190
	v_mov_b32_e32 v17, v191
	v_lshl_add_u64 v[18:19], v[4:5], 0, v[10:11]
	ds_read_b128 v[4:7], v0 offset:3456
	v_mov_b32_e32 v8, v180
	v_mov_b32_e32 v9, v181
	v_mov_b32_e32 v10, v182
	v_mov_b32_e32 v11, v183
	s_nop 0
	v_mov_b32_e32 v12, v208
	v_mov_b32_e32 v13, v209
	v_mov_b32_e32 v14, v210
	v_mov_b32_e32 v15, v211
	v_and_b32_e32 v3, 0xffff0000, v16
	v_lshlrev_b32_e32 v2, 16, v16
	v_pk_add_f32 v[2:3], v[12:13], v[2:3]
	s_waitcnt lgkmcnt(0)
	v_pk_fma_f32 v[2:3], v[4:5], v[8:9], v[2:3]
	v_and_b32_e32 v5, 0xffff0000, v17
	v_lshlrev_b32_e32 v4, 16, v17
	v_pk_add_f32 v[4:5], v[14:15], v[4:5]
	s_nop 0
	v_pk_fma_f32 v[4:5], v[6:7], v[10:11], v[4:5]
	global_store_dwordx4 v[18:19], v[2:5], off offset:128 sc1
	s_add_i32 s7, s7, s6
	s_cmpk_gt_i32 s7, 0x1ff
	v_readlane_b32 s64, v254, 55
	v_readlane_b32 s38, v254, 57
	v_readlane_b32 s42, v254, 59
	s_cselect_b64 s[0:1], -1, 0
	v_readlane_b32 s65, v254, 56
	v_readlane_b32 s39, v254, 58
	v_readlane_b32 s43, v254, 60
	s_mov_b32 s51, s27
	s_movk_i32 s37, 0x1000
	s_movk_i32 s36, 0x1ff
	s_mov_b32 s47, 0x7f800000
	s_mov_b32 s49, 0x20000
	s_mov_b32 s46, 0x4081e0d3
	s_mov_b32 s48, 0xc09de9e6
	s_mov_b64 s[44:45], 0x800
	s_branch .LBB0_21

.LBB0_142:
	s_andn2_b64 vcc, exec, s[4:5]
	s_cbranch_vccnz .LBB0_144
	v_cvt_pk_bf16_f32 v76, v38, v39
	v_cvt_pk_bf16_f32 v77, v40, v41
	v_cvt_pk_bf16_f32 v78, v42, v43
	v_cvt_pk_bf16_f32 v79, v44, v45
	global_store_dwordx4 v[68:69], v[76:79], off sc1
.LBB0_144:
	s_waitcnt vmcnt(15)
	v_lshlrev_b32_e32 v68, 16, v30
	v_and_b32_e32 v69, 0xffff0000, v30
	v_lshlrev_b32_e32 v30, 16, v31
	v_and_b32_e32 v31, 0xffff0000, v31
	s_waitcnt vmcnt(7)
	v_pk_fma_f32 v[30:31], v[40:41], v[74:75], v[30:31] op_sel_hi:[1,0,1]
	v_lshlrev_b32_e32 v40, 16, v32
	v_and_b32_e32 v41, 0xffff0000, v32
	v_pk_fma_f32 v[40:41], v[42:43], v[74:75], v[40:41] op_sel_hi:[1,0,1]
	v_lshlrev_b32_e32 v32, 16, v33
	v_and_b32_e32 v33, 0xffff0000, v33
	v_cndmask_b32_e64 v42, 0, 1, s[6:7]
	v_pk_fma_f32 v[38:39], v[38:39], v[74:75], v[68:69] op_sel_hi:[1,0,1]
	v_cmp_ne_u32_e64 s[4:5], 1, v42
	s_andn2_b64 vcc, exec, s[6:7]
	v_pk_fma_f32 v[32:33], v[44:45], v[74:75], v[32:33] op_sel_hi:[1,0,1]
	s_cbranch_vccnz .LBB0_146
	v_cvt_pk_bf16_f32 v42, v38, v39
	v_cvt_pk_bf16_f32 v43, v30, v31
	v_cvt_pk_bf16_f32 v44, v40, v41
	v_cvt_pk_bf16_f32 v45, v32, v33
	global_store_dwordx4 v[64:65], v[42:45], off sc1
.LBB0_146:
	s_nop 1
	v_lshlrev_b32_e32 v42, 16, v26
	v_and_b32_e32 v43, 0xffff0000, v26
	v_lshlrev_b32_e32 v26, 16, v27
	v_and_b32_e32 v27, 0xffff0000, v27
	s_waitcnt vmcnt(6)
	v_pk_fma_f32 v[26:27], v[72:73], v[30:31], v[26:27] op_sel_hi:[0,1,1]
	v_lshlrev_b32_e32 v30, 16, v28
	v_and_b32_e32 v31, 0xffff0000, v28
	v_lshlrev_b32_e32 v28, 16, v29
	v_and_b32_e32 v29, 0xffff0000, v29
	v_pk_fma_f32 v[38:39], v[72:73], v[38:39], v[42:43] op_sel_hi:[0,1,1]
	v_pk_fma_f32 v[30:31], v[72:73], v[40:41], v[30:31] op_sel_hi:[0,1,1]
	s_and_b64 vcc, exec, s[4:5]
	v_pk_fma_f32 v[28:29], v[72:73], v[32:33], v[28:29] op_sel_hi:[0,1,1]
	s_cbranch_vccnz .LBB0_148
	v_cvt_pk_bf16_f32 v40, v38, v39
	v_cvt_pk_bf16_f32 v41, v26, v27
	v_cvt_pk_bf16_f32 v42, v30, v31
	v_cvt_pk_bf16_f32 v43, v28, v29
	global_store_dwordx4 v[62:63], v[40:43], off sc1
.LBB0_148:
	v_lshlrev_b32_e32 v32, 16, v22
	v_and_b32_e32 v33, 0xffff0000, v22
	v_lshlrev_b32_e32 v22, 16, v23
	v_and_b32_e32 v23, 0xffff0000, v23
	s_waitcnt vmcnt(5)
	v_pk_fma_f32 v[22:23], v[70:71], v[26:27], v[22:23] op_sel_hi:[0,1,1]
	v_lshlrev_b32_e32 v26, 16, v24
	v_and_b32_e32 v27, 0xffff0000, v24
	v_lshlrev_b32_e32 v24, 16, v25
	v_and_b32_e32 v25, 0xffff0000, v25
	v_pk_fma_f32 v[32:33], v[70:71], v[38:39], v[32:33] op_sel_hi:[0,1,1]
	v_pk_fma_f32 v[26:27], v[70:71], v[30:31], v[26:27] op_sel_hi:[0,1,1]
	s_and_b64 vcc, exec, s[4:5]
	v_pk_fma_f32 v[24:25], v[70:71], v[28:29], v[24:25] op_sel_hi:[0,1,1]
	s_cbranch_vccnz .LBB0_150
	v_cvt_pk_bf16_f32 v28, v32, v33
	v_cvt_pk_bf16_f32 v29, v22, v23
	v_cvt_pk_bf16_f32 v30, v26, v27
	v_cvt_pk_bf16_f32 v31, v24, v25
	global_store_dwordx4 v[58:59], v[28:31], off sc1
.LBB0_150:
	s_nop 1
	v_lshlrev_b32_e32 v28, 16, v18
	v_and_b32_e32 v29, 0xffff0000, v18
	v_lshlrev_b32_e32 v18, 16, v19
	v_and_b32_e32 v19, 0xffff0000, v19
	s_waitcnt vmcnt(4)
	v_pk_fma_f32 v[18:19], v[66:67], v[22:23], v[18:19] op_sel_hi:[0,1,1]
	v_lshlrev_b32_e32 v22, 16, v20
	v_and_b32_e32 v23, 0xffff0000, v20
	v_lshlrev_b32_e32 v20, 16, v21
	v_and_b32_e32 v21, 0xffff0000, v21
	v_pk_fma_f32 v[28:29], v[66:67], v[32:33], v[28:29] op_sel_hi:[0,1,1]
	v_pk_fma_f32 v[22:23], v[66:67], v[26:27], v[22:23] op_sel_hi:[0,1,1]
	s_and_b64 vcc, exec, s[4:5]
	v_pk_fma_f32 v[20:21], v[66:67], v[24:25], v[20:21] op_sel_hi:[0,1,1]
	s_cbranch_vccnz .LBB0_152
	v_cvt_pk_bf16_f32 v24, v28, v29
	v_cvt_pk_bf16_f32 v25, v18, v19
	v_cvt_pk_bf16_f32 v26, v22, v23
	v_cvt_pk_bf16_f32 v27, v20, v21
	global_store_dwordx4 v[56:57], v[24:27], off sc1
.LBB0_152:
	s_nop 1
	v_lshlrev_b32_e32 v24, 16, v14
	v_and_b32_e32 v25, 0xffff0000, v14
	v_lshlrev_b32_e32 v14, 16, v15
	v_and_b32_e32 v15, 0xffff0000, v15
	s_waitcnt vmcnt(3)
	v_pk_fma_f32 v[14:15], v[60:61], v[18:19], v[14:15] op_sel_hi:[0,1,1]
	v_lshlrev_b32_e32 v18, 16, v16
	v_and_b32_e32 v19, 0xffff0000, v16
	v_lshlrev_b32_e32 v16, 16, v17
	v_and_b32_e32 v17, 0xffff0000, v17
	v_pk_fma_f32 v[24:25], v[60:61], v[28:29], v[24:25] op_sel_hi:[0,1,1]
	v_pk_fma_f32 v[18:19], v[60:61], v[22:23], v[18:19] op_sel_hi:[0,1,1]
	s_and_b64 vcc, exec, s[4:5]
	v_pk_fma_f32 v[16:17], v[60:61], v[20:21], v[16:17] op_sel_hi:[0,1,1]
	s_cbranch_vccnz .LBB0_154
	v_cvt_pk_bf16_f32 v20, v24, v25
	v_cvt_pk_bf16_f32 v21, v14, v15
	v_cvt_pk_bf16_f32 v22, v18, v19
	v_cvt_pk_bf16_f32 v23, v16, v17
	global_store_dwordx4 v[52:53], v[20:23], off sc1
.LBB0_154:
	s_nop 1
	v_lshlrev_b32_e32 v20, 16, v10
	v_and_b32_e32 v21, 0xffff0000, v10
	v_lshlrev_b32_e32 v10, 16, v11
	v_and_b32_e32 v11, 0xffff0000, v11
	s_waitcnt vmcnt(2)
	v_pk_fma_f32 v[10:11], v[54:55], v[14:15], v[10:11] op_sel_hi:[0,1,1]
	v_lshlrev_b32_e32 v14, 16, v12
	v_and_b32_e32 v15, 0xffff0000, v12
	v_lshlrev_b32_e32 v12, 16, v13
	v_and_b32_e32 v13, 0xffff0000, v13
	v_pk_fma_f32 v[20:21], v[54:55], v[24:25], v[20:21] op_sel_hi:[0,1,1]
	v_pk_fma_f32 v[14:15], v[54:55], v[18:19], v[14:15] op_sel_hi:[0,1,1]
	s_and_b64 vcc, exec, s[4:5]
	v_pk_fma_f32 v[12:13], v[54:55], v[16:17], v[12:13] op_sel_hi:[0,1,1]
	s_cbranch_vccnz .LBB0_156
	v_cvt_pk_bf16_f32 v16, v20, v21
	v_cvt_pk_bf16_f32 v17, v10, v11
	v_cvt_pk_bf16_f32 v18, v14, v15
	v_cvt_pk_bf16_f32 v19, v12, v13
	global_store_dwordx4 v[48:49], v[16:19], off sc1
.LBB0_156:
	s_nop 1
	v_lshlrev_b32_e32 v16, 16, v6
	v_and_b32_e32 v17, 0xffff0000, v6
	v_lshlrev_b32_e32 v6, 16, v7
	v_and_b32_e32 v7, 0xffff0000, v7
	s_waitcnt vmcnt(1)
	v_pk_fma_f32 v[10:11], v[50:51], v[10:11], v[6:7] op_sel_hi:[0,1,1]
	v_lshlrev_b32_e32 v6, 16, v8
	v_and_b32_e32 v7, 0xffff0000, v8
	v_pk_fma_f32 v[14:15], v[50:51], v[14:15], v[6:7] op_sel_hi:[0,1,1]
	v_lshlrev_b32_e32 v6, 16, v9
	v_and_b32_e32 v7, 0xffff0000, v9
	v_pk_fma_f32 v[16:17], v[50:51], v[20:21], v[16:17] op_sel_hi:[0,1,1]
	s_and_b64 vcc, exec, s[4:5]
	v_pk_fma_f32 v[6:7], v[50:51], v[12:13], v[6:7] op_sel_hi:[0,1,1]
	s_cbranch_vccnz .LBB0_139
	v_cvt_pk_bf16_f32 v18, v16, v17
	v_cvt_pk_bf16_f32 v19, v10, v11
	v_cvt_pk_bf16_f32 v20, v14, v15
	v_cvt_pk_bf16_f32 v21, v6, v7
	global_store_dwordx4 v[46:47], v[18:21], off sc1
	s_branch .LBB0_139

.LBB0_284:
	s_or_b64 exec, exec, s[0:1]
	v_readlane_b32 s12, v254, 39
	v_lshlrev_b32_e32 v0, 2, v20
	v_readlane_b32 s24, v254, 51
	v_readlane_b32 s25, v254, 52
	s_mov_b64 s[0:1], 0x8000
	s_waitcnt vmcnt(63) expcnt(7) lgkmcnt(15)
	v_lshl_add_u64 v[14:15], s[24:25], 0, v[0:1]
	s_waitcnt vmcnt(3)
	v_lshl_add_u64 v[22:23], v[14:15], 0, s[0:1]
	s_movk_i32 s0, 0x4000
	v_add_co_u32_e32 v18, vcc, s0, v14
	s_mov_b32 s0, 0x8000
	s_nop 0
	v_addc_co_u32_e32 v19, vcc, 0, v15, vcc
	v_lshl_add_u64 v[16:17], v[14:15], 0, s[88:89]
	v_add_co_u32_e32 v14, vcc, s0, v14
	s_barrier
	s_nop 0
	v_addc_co_u32_e32 v15, vcc, 0, v15, vcc
	v_readlane_b32 s26, v254, 53
	v_readlane_b32 s27, v254, 54
	global_load_dwordx4 v[38:41], v[18:19], off
	global_load_dwordx4 v[34:37], v[14:15], off
	s_nop 0
	global_load_dwordx4 v[18:21], v[16:17], off offset:16
	s_nop 0
	global_load_dwordx4 v[14:17], v[22:23], off offset:16
	s_nop 0
	global_load_dwordx4 v[22:25], v0, s[24:25] offset:16
	global_load_dwordx4 v[26:29], v0, s[26:27] offset:16
	global_load_dwordx4 v[46:49], v0, s[24:25]
	global_load_dwordx4 v[42:45], v0, s[26:27]
	v_cndmask_b32_e64 v0, 0, 1, s[6:7]
	s_waitcnt vmcnt(8)
	v_lshlrev_b32_e32 v100, 16, v62
	v_and_b32_e32 v101, 0xffff0000, v62
	v_lshlrev_b32_e32 v94, 16, v70
	v_and_b32_e32 v95, 0xffff0000, v70
	v_lshlrev_b32_e32 v98, 16, v63
	v_and_b32_e32 v99, 0xffff0000, v63
	v_lshlrev_b32_e32 v92, 16, v71
	v_and_b32_e32 v93, 0xffff0000, v71
	v_lshlrev_b32_e32 v96, 16, v64
	v_and_b32_e32 v97, 0xffff0000, v64
	v_lshlrev_b32_e32 v70, 16, v72
	v_and_b32_e32 v71, 0xffff0000, v72
	v_lshlrev_b32_e32 v64, 16, v65
	v_and_b32_e32 v65, 0xffff0000, v65
	v_lshlrev_b32_e32 v62, 16, v73
	v_cmp_ne_u32_e64 s[0:1], 1, v0
	s_andn2_b64 vcc, exec, s[6:7]
	v_and_b32_e32 v63, 0xffff0000, v73
	v_readlane_b32 s13, v254, 40
	v_readlane_b32 s14, v254, 41
	v_readlane_b32 s15, v254, 42
	v_readlane_b32 s16, v254, 43
	v_readlane_b32 s17, v254, 44
	v_readlane_b32 s18, v254, 45
	v_readlane_b32 s19, v254, 46
	v_readlane_b32 s20, v254, 47
	v_readlane_b32 s21, v254, 48
	v_readlane_b32 s22, v254, 49
	v_readlane_b32 s23, v254, 50
	s_cbranch_vccnz .LBB0_286
	v_lshlrev_b32_e32 v72, 16, v50
	v_and_b32_e32 v73, 0xffff0000, v50
	s_waitcnt vmcnt(7)
	v_pk_mul_f32 v[104:105], v[38:39], v[100:101]
	v_ashrrev_i32_e32 v89, 31, v88
	s_waitcnt vmcnt(1)
	v_pk_fma_f32 v[72:73], v[46:47], v[72:73], v[104:105]
	s_nop 0
	v_pk_fma_f32 v[72:73], v[34:35], v[94:95], v[72:73]
	s_waitcnt vmcnt(0)
	v_pk_add_f32 v[72:73], v[42:43], v[72:73]
	s_nop 0
	v_mul_f32_e32 v0, 0xbfb8aa3b, v72
	v_exp_f32_e32 v0, v0
	s_nop 0
	v_add_f32_e32 v0, 1.0, v0
	v_rcp_f32_e32 v104, v0
	v_mul_f32_e32 v0, 0xbfb8aa3b, v73
	v_exp_f32_e32 v0, v0
	s_nop 0
	v_add_f32_e32 v0, 1.0, v0
	v_rcp_f32_e32 v105, v0
	s_nop 0
	v_pk_mul_f32 v[72:73], v[72:73], v[104:105]
	s_nop 0
	v_cvt_pk_bf16_f32 v50, v72, v73
	v_lshlrev_b32_e32 v72, 16, v51
	v_and_b32_e32 v73, 0xffff0000, v51
	v_pk_mul_f32 v[104:105], v[40:41], v[98:99]
	s_nop 0
	v_pk_fma_f32 v[72:73], v[48:49], v[72:73], v[104:105]
	s_nop 0
	v_pk_fma_f32 v[72:73], v[36:37], v[92:93], v[72:73]
	s_nop 0
	v_pk_add_f32 v[72:73], v[44:45], v[72:73]
	s_nop 0
	v_mul_f32_e32 v0, 0xbfb8aa3b, v72
	v_exp_f32_e32 v0, v0
	s_nop 0
	v_add_f32_e32 v0, 1.0, v0
	v_rcp_f32_e32 v104, v0
	v_mul_f32_e32 v0, 0xbfb8aa3b, v73
	v_exp_f32_e32 v0, v0
	s_nop 0
	v_add_f32_e32 v0, 1.0, v0
	v_rcp_f32_e32 v105, v0
	s_nop 0
	v_pk_mul_f32 v[72:73], v[72:73], v[104:105]
	s_nop 0
	v_cvt_pk_bf16_f32 v51, v72, v73
	v_lshlrev_b32_e32 v72, 16, v52
	v_and_b32_e32 v73, 0xffff0000, v52
	v_pk_mul_f32 v[104:105], v[18:19], v[96:97]
	s_nop 0
	v_pk_fma_f32 v[72:73], v[22:23], v[72:73], v[104:105]
	s_nop 0
	v_pk_fma_f32 v[72:73], v[14:15], v[70:71], v[72:73]
	s_nop 0
	v_pk_add_f32 v[72:73], v[26:27], v[72:73]
	s_nop 0
	v_mul_f32_e32 v0, 0xbfb8aa3b, v72
	v_exp_f32_e32 v0, v0
	s_nop 0
	v_add_f32_e32 v0, 1.0, v0
	v_rcp_f32_e32 v104, v0
	v_mul_f32_e32 v0, 0xbfb8aa3b, v73
	v_exp_f32_e32 v0, v0
	s_nop 0
	v_add_f32_e32 v0, 1.0, v0
	v_rcp_f32_e32 v105, v0
	s_nop 0
	v_pk_mul_f32 v[72:73], v[72:73], v[104:105]
	s_nop 0
	v_cvt_pk_bf16_f32 v52, v72, v73
	v_lshlrev_b32_e32 v72, 16, v53
	v_and_b32_e32 v73, 0xffff0000, v53
	v_pk_mul_f32 v[104:105], v[20:21], v[64:65]
	s_nop 0
	v_pk_fma_f32 v[72:73], v[24:25], v[72:73], v[104:105]
	s_nop 0
	v_pk_fma_f32 v[72:73], v[16:17], v[62:63], v[72:73]
	s_nop 0
	v_pk_add_f32 v[72:73], v[28:29], v[72:73]
	s_nop 0
	v_mul_f32_e32 v0, 0xbfb8aa3b, v72
	v_exp_f32_e32 v0, v0
	s_nop 0
	v_add_f32_e32 v0, 1.0, v0
	v_rcp_f32_e32 v104, v0
	v_mul_f32_e32 v0, 0xbfb8aa3b, v73
	v_exp_f32_e32 v0, v0
	s_nop 0
	v_add_f32_e32 v0, 1.0, v0
	v_rcp_f32_e32 v105, v0
	s_nop 0
	v_pk_mul_f32 v[72:73], v[72:73], v[104:105]
	s_nop 0
	v_cvt_pk_bf16_f32 v53, v72, v73
	v_lshlrev_b64 v[72:73], 13, v[88:89]
	v_lshl_add_u64 v[72:73], v[74:75], 0, v[72:73]
	global_store_dwordx4 v[72:73], v[50:53], off sc1
.LBB0_286:
	s_and_b64 vcc, exec, s[0:1]
	s_cbranch_vccnz .LBB0_182
	s_waitcnt vmcnt(7)
	v_pk_mul_f32 v[50:51], v[38:39], v[94:95]
	v_lshlrev_b32_e32 v88, 16, v66
	v_and_b32_e32 v89, 0xffff0000, v66
	s_waitcnt vmcnt(1)
	v_pk_fma_f32 v[50:51], v[46:47], v[100:101], v[50:51]
	v_lshlrev_b32_e32 v72, 16, v67
	v_pk_fma_f32 v[50:51], v[34:35], v[88:89], v[50:51]
	v_and_b32_e32 v73, 0xffff0000, v67
	s_waitcnt vmcnt(0)
	v_pk_add_f32 v[50:51], v[42:43], v[50:51]
	v_lshlrev_b32_e32 v66, 16, v68
	v_mul_f32_e32 v0, 0xbfb8aa3b, v50
	v_exp_f32_e32 v0, v0
	v_and_b32_e32 v67, 0xffff0000, v68
	v_lshlrev_b32_e32 v52, 16, v69
	v_and_b32_e32 v53, 0xffff0000, v69
	v_add_f32_e32 v0, 1.0, v0
	v_rcp_f32_e32 v68, v0
	v_mul_f32_e32 v0, 0xbfb8aa3b, v51
	v_exp_f32_e32 v0, v0
	v_ashrrev_i32_e32 v91, 31, v90
	v_ashrrev_i32_e32 v87, 31, v86
	v_ashrrev_i32_e32 v85, 31, v84
	v_add_f32_e32 v0, 1.0, v0
	v_rcp_f32_e32 v69, v0
	v_ashrrev_i32_e32 v83, 31, v82
	v_ashrrev_i32_e32 v81, 31, v80
	v_ashrrev_i32_e32 v79, 31, v78
	v_pk_mul_f32 v[50:51], v[50:51], v[68:69]
	v_ashrrev_i32_e32 v77, 31, v76
	v_cvt_pk_bf16_f32 v104, v50, v51
	v_pk_mul_f32 v[50:51], v[40:41], v[92:93]
	s_nop 0
	v_pk_fma_f32 v[50:51], v[48:49], v[98:99], v[50:51]
	s_nop 0
	v_pk_fma_f32 v[50:51], v[36:37], v[72:73], v[50:51]
	s_nop 0
	v_pk_add_f32 v[50:51], v[44:45], v[50:51]
	s_nop 0
	v_mul_f32_e32 v0, 0xbfb8aa3b, v50
	v_exp_f32_e32 v0, v0
	s_nop 0
	v_add_f32_e32 v0, 1.0, v0
	v_rcp_f32_e32 v68, v0
	v_mul_f32_e32 v0, 0xbfb8aa3b, v51
	v_exp_f32_e32 v0, v0
	s_nop 0
	v_add_f32_e32 v0, 1.0, v0
	v_rcp_f32_e32 v69, v0
	s_nop 0
	v_pk_mul_f32 v[50:51], v[50:51], v[68:69]
	s_nop 0
	v_cvt_pk_bf16_f32 v105, v50, v51
	v_pk_mul_f32 v[50:51], v[18:19], v[70:71]
	s_nop 0
	v_pk_fma_f32 v[50:51], v[22:23], v[96:97], v[50:51]
	s_nop 0
	v_pk_fma_f32 v[50:51], v[14:15], v[66:67], v[50:51]
	s_nop 0
	v_pk_add_f32 v[50:51], v[26:27], v[50:51]
	s_nop 0
	v_mul_f32_e32 v0, 0xbfb8aa3b, v50
	v_exp_f32_e32 v0, v0
	s_nop 0
	v_add_f32_e32 v0, 1.0, v0
	v_rcp_f32_e32 v68, v0
	v_mul_f32_e32 v0, 0xbfb8aa3b, v51
	v_exp_f32_e32 v0, v0
	s_nop 0
	v_add_f32_e32 v0, 1.0, v0
	v_rcp_f32_e32 v69, v0
	s_nop 0
	v_pk_mul_f32 v[50:51], v[50:51], v[68:69]
	s_nop 0
	v_cvt_pk_bf16_f32 v106, v50, v51
	v_pk_mul_f32 v[50:51], v[20:21], v[62:63]
	s_nop 0
	v_pk_fma_f32 v[50:51], v[24:25], v[64:65], v[50:51]
	s_nop 0
	v_pk_fma_f32 v[50:51], v[16:17], v[52:53], v[50:51]
	s_nop 0
	v_pk_add_f32 v[50:51], v[28:29], v[50:51]
	s_nop 0
	v_mul_f32_e32 v0, 0xbfb8aa3b, v50
	v_exp_f32_e32 v0, v0
	s_nop 0
	v_add_f32_e32 v0, 1.0, v0
	v_rcp_f32_e32 v64, v0
	v_mul_f32_e32 v0, 0xbfb8aa3b, v51
	v_exp_f32_e32 v0, v0
	s_nop 0
	v_add_f32_e32 v0, 1.0, v0
	v_rcp_f32_e32 v65, v0
	s_nop 0
	v_pk_mul_f32 v[50:51], v[50:51], v[64:65]
	s_nop 0
	v_cvt_pk_bf16_f32 v107, v50, v51
	v_lshlrev_b64 v[50:51], 13, v[90:91]
	v_lshl_add_u64 v[50:51], v[74:75], 0, v[50:51]
	global_store_dwordx4 v[50:51], v[104:107], off sc1
	v_lshlrev_b32_e32 v50, 16, v61
	v_and_b32_e32 v51, 0xffff0000, v61
	v_lshlrev_b32_e32 v64, 16, v60
	v_and_b32_e32 v65, 0xffff0000, v60
	v_lshlrev_b32_e32 v60, 16, v59
	v_and_b32_e32 v61, 0xffff0000, v59
	v_lshlrev_b32_e32 v90, 16, v58
	v_and_b32_e32 v91, 0xffff0000, v58
	v_pk_mul_f32 v[58:59], v[38:39], v[88:89]
	s_nop 0
	v_pk_fma_f32 v[58:59], v[46:47], v[94:95], v[58:59]
	s_nop 0
	v_pk_fma_f32 v[58:59], v[34:35], v[90:91], v[58:59]
	s_nop 0
	v_pk_add_f32 v[58:59], v[42:43], v[58:59]
	s_nop 0
	v_mul_f32_e32 v0, 0xbfb8aa3b, v58
	v_exp_f32_e32 v0, v0
	s_nop 0
	v_add_f32_e32 v0, 1.0, v0
	v_rcp_f32_e32 v68, v0
	v_mul_f32_e32 v0, 0xbfb8aa3b, v59
	v_exp_f32_e32 v0, v0
	s_nop 0
	v_add_f32_e32 v0, 1.0, v0
	v_rcp_f32_e32 v69, v0
	s_nop 0
	v_pk_mul_f32 v[58:59], v[58:59], v[68:69]
	s_nop 0
	v_cvt_pk_bf16_f32 v68, v58, v59
	v_pk_mul_f32 v[58:59], v[40:41], v[72:73]
	s_nop 0
	v_pk_fma_f32 v[58:59], v[48:49], v[92:93], v[58:59]
	s_nop 0
	v_pk_fma_f32 v[58:59], v[36:37], v[60:61], v[58:59]
	s_nop 0
	v_pk_add_f32 v[58:59], v[44:45], v[58:59]
	s_nop 0
	v_mul_f32_e32 v0, 0xbfb8aa3b, v58
	v_exp_f32_e32 v0, v0
	s_nop 0
	v_add_f32_e32 v0, 1.0, v0
	v_rcp_f32_e32 v92, v0
	v_mul_f32_e32 v0, 0xbfb8aa3b, v59
	v_exp_f32_e32 v0, v0
	s_nop 0
	v_add_f32_e32 v0, 1.0, v0
	v_rcp_f32_e32 v93, v0
	s_nop 0
	v_pk_mul_f32 v[58:59], v[58:59], v[92:93]
	s_nop 0
	v_cvt_pk_bf16_f32 v69, v58, v59
	v_pk_mul_f32 v[58:59], v[18:19], v[66:67]
	s_nop 0
	v_pk_fma_f32 v[58:59], v[22:23], v[70:71], v[58:59]
	s_nop 0
	v_pk_fma_f32 v[58:59], v[14:15], v[64:65], v[58:59]
	s_nop 0
	v_pk_add_f32 v[58:59], v[26:27], v[58:59]
	s_nop 0
	v_mul_f32_e32 v0, 0xbfb8aa3b, v58
	v_exp_f32_e32 v0, v0
	s_nop 0
	v_add_f32_e32 v0, 1.0, v0
	v_rcp_f32_e32 v70, v0
	v_mul_f32_e32 v0, 0xbfb8aa3b, v59
	v_exp_f32_e32 v0, v0
	s_nop 0
	v_add_f32_e32 v0, 1.0, v0
	v_rcp_f32_e32 v71, v0
	s_nop 0
	v_pk_mul_f32 v[58:59], v[58:59], v[70:71]
	s_nop 0
	v_cvt_pk_bf16_f32 v70, v58, v59
	v_pk_mul_f32 v[58:59], v[20:21], v[52:53]
	s_nop 0
	v_pk_fma_f32 v[58:59], v[24:25], v[62:63], v[58:59]
	s_nop 0
	v_pk_fma_f32 v[58:59], v[16:17], v[50:51], v[58:59]
	s_nop 0
	v_pk_add_f32 v[58:59], v[28:29], v[58:59]
	s_nop 0
	v_mul_f32_e32 v0, 0xbfb8aa3b, v58
	v_exp_f32_e32 v0, v0
	s_nop 0
	v_add_f32_e32 v0, 1.0, v0
	v_rcp_f32_e32 v62, v0
	v_mul_f32_e32 v0, 0xbfb8aa3b, v59
	v_exp_f32_e32 v0, v0
	s_nop 0
	v_add_f32_e32 v0, 1.0, v0
	v_rcp_f32_e32 v63, v0
	s_nop 0
	v_pk_mul_f32 v[58:59], v[58:59], v[62:63]
	s_nop 0
	v_cvt_pk_bf16_f32 v71, v58, v59
	v_lshlrev_b64 v[58:59], 13, v[86:87]
	v_lshl_add_u64 v[58:59], v[74:75], 0, v[58:59]
	global_store_dwordx4 v[58:59], v[68:71], off sc1
	v_pk_mul_f32 v[58:59], v[38:39], v[90:91]
	s_nop 0
	v_lshlrev_b32_e32 v70, 16, v54
	v_and_b32_e32 v71, 0xffff0000, v54
	v_pk_fma_f32 v[58:59], v[46:47], v[88:89], v[58:59]
	v_lshlrev_b32_e32 v68, 16, v55
	v_pk_fma_f32 v[58:59], v[34:35], v[70:71], v[58:59]
	v_and_b32_e32 v69, 0xffff0000, v55
	v_pk_add_f32 v[58:59], v[42:43], v[58:59]
	s_nop 0
	v_mul_f32_e32 v0, 0xbfb8aa3b, v58
	v_exp_f32_e32 v0, v0
	s_nop 0
	v_add_f32_e32 v0, 1.0, v0
	v_rcp_f32_e32 v62, v0
	v_mul_f32_e32 v0, 0xbfb8aa3b, v59
	v_exp_f32_e32 v0, v0
	s_nop 0
	v_add_f32_e32 v0, 1.0, v0
	v_rcp_f32_e32 v63, v0
	s_nop 0
	v_pk_mul_f32 v[58:59], v[58:59], v[62:63]
	s_nop 0
	v_cvt_pk_bf16_f32 v54, v58, v59
	v_pk_mul_f32 v[58:59], v[40:41], v[60:61]
	s_nop 0
	v_pk_fma_f32 v[58:59], v[48:49], v[72:73], v[58:59]
	s_nop 0
	v_pk_fma_f32 v[58:59], v[36:37], v[68:69], v[58:59]
	s_nop 0
	v_pk_add_f32 v[58:59], v[44:45], v[58:59]
	s_nop 0
	v_mul_f32_e32 v0, 0xbfb8aa3b, v58
	v_exp_f32_e32 v0, v0
	s_nop 0
	v_add_f32_e32 v0, 1.0, v0
	v_rcp_f32_e32 v62, v0
	v_mul_f32_e32 v0, 0xbfb8aa3b, v59
	v_exp_f32_e32 v0, v0
	s_nop 0
	v_add_f32_e32 v0, 1.0, v0
	v_rcp_f32_e32 v63, v0
	s_nop 0
	v_pk_mul_f32 v[58:59], v[58:59], v[62:63]
	s_nop 0
	v_cvt_pk_bf16_f32 v55, v58, v59
	v_pk_mul_f32 v[58:59], v[18:19], v[64:65]
	v_lshlrev_b32_e32 v62, 16, v56
	v_and_b32_e32 v63, 0xffff0000, v56
	v_pk_fma_f32 v[58:59], v[22:23], v[66:67], v[58:59]
	s_nop 0
	v_pk_fma_f32 v[58:59], v[14:15], v[62:63], v[58:59]
	s_nop 0
	v_pk_add_f32 v[58:59], v[26:27], v[58:59]
	s_nop 0
	v_mul_f32_e32 v0, 0xbfb8aa3b, v58
	v_exp_f32_e32 v0, v0
	s_nop 0
	v_add_f32_e32 v0, 1.0, v0
	v_rcp_f32_e32 v66, v0
	v_mul_f32_e32 v0, 0xbfb8aa3b, v59
	v_exp_f32_e32 v0, v0
	s_nop 0
	v_add_f32_e32 v0, 1.0, v0
	v_rcp_f32_e32 v67, v0
	s_nop 0
	v_pk_mul_f32 v[58:59], v[58:59], v[66:67]
	v_pk_mul_f32 v[66:67], v[20:21], v[50:51]
	v_cvt_pk_bf16_f32 v56, v58, v59
	v_lshlrev_b32_e32 v58, 16, v57
	v_and_b32_e32 v59, 0xffff0000, v57
	v_pk_fma_f32 v[52:53], v[24:25], v[52:53], v[66:67]
	s_nop 0
	v_pk_fma_f32 v[52:53], v[16:17], v[58:59], v[52:53]
	s_nop 0
	v_pk_add_f32 v[52:53], v[28:29], v[52:53]
	s_nop 0
	v_mul_f32_e32 v0, 0xbfb8aa3b, v52
	v_exp_f32_e32 v0, v0
	s_nop 0
	v_add_f32_e32 v0, 1.0, v0
	v_rcp_f32_e32 v66, v0
	v_mul_f32_e32 v0, 0xbfb8aa3b, v53
	v_exp_f32_e32 v0, v0
	s_nop 0
	v_add_f32_e32 v0, 1.0, v0
	v_rcp_f32_e32 v67, v0
	s_nop 0
	v_pk_mul_f32 v[52:53], v[52:53], v[66:67]
	s_nop 0
	v_cvt_pk_bf16_f32 v57, v52, v53
	v_lshlrev_b64 v[52:53], 13, v[84:85]
	v_lshl_add_u64 v[52:53], v[74:75], 0, v[52:53]
	global_store_dwordx4 v[52:53], v[54:57], off sc1
	v_pk_mul_f32 v[52:53], v[38:39], v[70:71]
	s_nop 0
	v_lshlrev_b32_e32 v56, 16, v30
	v_and_b32_e32 v57, 0xffff0000, v30
	v_pk_fma_f32 v[52:53], v[46:47], v[90:91], v[52:53]
	s_nop 0
	v_pk_fma_f32 v[52:53], v[34:35], v[56:57], v[52:53]
	s_nop 0
	v_pk_add_f32 v[52:53], v[42:43], v[52:53]
	s_nop 0
	v_mul_f32_e32 v0, 0xbfb8aa3b, v52
	v_exp_f32_e32 v0, v0
	s_nop 0
	v_add_f32_e32 v0, 1.0, v0
	v_rcp_f32_e32 v54, v0
	v_mul_f32_e32 v0, 0xbfb8aa3b, v53
	v_exp_f32_e32 v0, v0
	s_nop 0
	v_add_f32_e32 v0, 1.0, v0
	v_rcp_f32_e32 v55, v0
	s_nop 0
	v_pk_mul_f32 v[52:53], v[52:53], v[54:55]
	v_lshlrev_b32_e32 v54, 16, v31
	v_and_b32_e32 v55, 0xffff0000, v31
	v_pk_mul_f32 v[30:31], v[40:41], v[68:69]
	v_cvt_pk_bf16_f32 v84, v52, v53
	v_pk_fma_f32 v[30:31], v[48:49], v[60:61], v[30:31]
	s_nop 0
	v_pk_fma_f32 v[30:31], v[36:37], v[54:55], v[30:31]
	s_nop 0
	v_pk_add_f32 v[30:31], v[44:45], v[30:31]
	s_nop 0
	v_mul_f32_e32 v0, 0xbfb8aa3b, v30
	v_exp_f32_e32 v0, v0
	s_nop 0
	v_add_f32_e32 v0, 1.0, v0
	v_rcp_f32_e32 v52, v0
	v_mul_f32_e32 v0, 0xbfb8aa3b, v31
	v_exp_f32_e32 v0, v0
	s_nop 0
	v_add_f32_e32 v0, 1.0, v0
	v_rcp_f32_e32 v53, v0
	s_nop 0
	v_pk_mul_f32 v[30:31], v[30:31], v[52:53]
	s_nop 0
	v_cvt_pk_bf16_f32 v85, v30, v31
	v_pk_mul_f32 v[30:31], v[18:19], v[62:63]
	v_lshlrev_b32_e32 v52, 16, v32
	v_and_b32_e32 v53, 0xffff0000, v32
	v_pk_fma_f32 v[30:31], v[22:23], v[64:65], v[30:31]
	s_nop 0
	v_pk_fma_f32 v[30:31], v[14:15], v[52:53], v[30:31]
	s_nop 0
	v_pk_add_f32 v[30:31], v[26:27], v[30:31]
	s_nop 0
	v_mul_f32_e32 v0, 0xbfb8aa3b, v30
	v_exp_f32_e32 v0, v0
	s_nop 0
	v_add_f32_e32 v0, 1.0, v0
	v_rcp_f32_e32 v60, v0
	v_mul_f32_e32 v0, 0xbfb8aa3b, v31
	v_exp_f32_e32 v0, v0
	s_nop 0
	v_add_f32_e32 v0, 1.0, v0
	v_rcp_f32_e32 v61, v0
	s_nop 0
	v_pk_mul_f32 v[30:31], v[30:31], v[60:61]
	s_nop 0
	v_cvt_pk_bf16_f32 v86, v30, v31
	v_lshlrev_b32_e32 v30, 16, v33
	v_and_b32_e32 v31, 0xffff0000, v33
	v_pk_mul_f32 v[32:33], v[20:21], v[58:59]
	v_lshlrev_b32_e32 v60, 16, v10
	v_pk_fma_f32 v[32:33], v[24:25], v[50:51], v[32:33]
	v_and_b32_e32 v61, 0xffff0000, v10
	v_pk_fma_f32 v[32:33], v[16:17], v[30:31], v[32:33]
	s_nop 0
	v_pk_add_f32 v[32:33], v[28:29], v[32:33]
	s_nop 0
	v_mul_f32_e32 v0, 0xbfb8aa3b, v32
	v_exp_f32_e32 v0, v0
	s_nop 0
	v_add_f32_e32 v0, 1.0, v0
	v_rcp_f32_e32 v50, v0
	v_mul_f32_e32 v0, 0xbfb8aa3b, v33
	v_exp_f32_e32 v0, v0
	s_nop 0
	v_add_f32_e32 v0, 1.0, v0
	v_rcp_f32_e32 v51, v0
	s_nop 0
	v_pk_mul_f32 v[32:33], v[32:33], v[50:51]
	s_nop 0
	v_cvt_pk_bf16_f32 v87, v32, v33
	v_lshlrev_b64 v[32:33], 13, v[82:83]
	v_lshl_add_u64 v[32:33], v[74:75], 0, v[32:33]
	global_store_dwordx4 v[32:33], v[84:87], off sc1
	v_pk_mul_f32 v[32:33], v[38:39], v[56:57]
	s_nop 0
	v_pk_fma_f32 v[32:33], v[46:47], v[70:71], v[32:33]
	s_nop 0
	v_pk_fma_f32 v[32:33], v[34:35], v[60:61], v[32:33]
	s_nop 0
	v_pk_add_f32 v[32:33], v[42:43], v[32:33]
	s_nop 0
	v_mul_f32_e32 v0, 0xbfb8aa3b, v32
	v_exp_f32_e32 v0, v0
	s_nop 0
	v_add_f32_e32 v0, 1.0, v0
	v_rcp_f32_e32 v50, v0
	v_mul_f32_e32 v0, 0xbfb8aa3b, v33
	v_exp_f32_e32 v0, v0
	s_nop 0
	v_add_f32_e32 v0, 1.0, v0
	v_rcp_f32_e32 v51, v0
	s_nop 0
	v_pk_mul_f32 v[32:33], v[32:33], v[50:51]
	v_lshlrev_b32_e32 v50, 16, v11
	v_and_b32_e32 v51, 0xffff0000, v11
	v_pk_mul_f32 v[10:11], v[40:41], v[54:55]
	v_cvt_pk_bf16_f32 v64, v32, v33
	v_pk_fma_f32 v[10:11], v[48:49], v[68:69], v[10:11]
	s_nop 0
	v_pk_fma_f32 v[10:11], v[36:37], v[50:51], v[10:11]
	s_nop 0
	v_pk_add_f32 v[10:11], v[44:45], v[10:11]
	s_nop 0
	v_mul_f32_e32 v0, 0xbfb8aa3b, v10
	v_exp_f32_e32 v0, v0
	s_nop 0
	v_add_f32_e32 v0, 1.0, v0
	v_rcp_f32_e32 v32, v0
	v_mul_f32_e32 v0, 0xbfb8aa3b, v11
	v_exp_f32_e32 v0, v0
	s_nop 0
	v_add_f32_e32 v0, 1.0, v0
	v_rcp_f32_e32 v33, v0
	s_nop 0
	v_pk_mul_f32 v[10:11], v[10:11], v[32:33]
	s_nop 0
	v_cvt_pk_bf16_f32 v65, v10, v11
	v_pk_mul_f32 v[10:11], v[18:19], v[52:53]
	v_lshlrev_b32_e32 v32, 16, v12
	v_and_b32_e32 v33, 0xffff0000, v12
	v_pk_fma_f32 v[10:11], v[22:23], v[62:63], v[10:11]
	s_nop 0
	v_pk_fma_f32 v[10:11], v[14:15], v[32:33], v[10:11]
	s_nop 0
	v_pk_add_f32 v[10:11], v[26:27], v[10:11]
	s_nop 0
	v_mul_f32_e32 v0, 0xbfb8aa3b, v10
	v_exp_f32_e32 v0, v0
	s_nop 0
	v_add_f32_e32 v0, 1.0, v0
	v_rcp_f32_e32 v62, v0
	v_mul_f32_e32 v0, 0xbfb8aa3b, v11
	v_exp_f32_e32 v0, v0
	s_nop 0
	v_add_f32_e32 v0, 1.0, v0
	v_rcp_f32_e32 v63, v0
	s_nop 0
	v_pk_mul_f32 v[10:11], v[10:11], v[62:63]
	s_nop 0
	v_cvt_pk_bf16_f32 v66, v10, v11
	v_lshlrev_b32_e32 v10, 16, v13
	v_and_b32_e32 v11, 0xffff0000, v13
	v_pk_mul_f32 v[12:13], v[20:21], v[30:31]
	s_nop 0
	v_pk_fma_f32 v[12:13], v[24:25], v[58:59], v[12:13]
	s_nop 0
	v_pk_fma_f32 v[12:13], v[16:17], v[10:11], v[12:13]
	s_nop 0
	v_pk_add_f32 v[12:13], v[28:29], v[12:13]
	s_nop 0
	v_mul_f32_e32 v0, 0xbfb8aa3b, v12
	v_exp_f32_e32 v0, v0
	s_nop 0
	v_add_f32_e32 v0, 1.0, v0
	v_rcp_f32_e32 v58, v0
	v_mul_f32_e32 v0, 0xbfb8aa3b, v13
	v_exp_f32_e32 v0, v0
	s_nop 0
	v_add_f32_e32 v0, 1.0, v0
	v_rcp_f32_e32 v59, v0
	s_nop 0
	v_pk_mul_f32 v[12:13], v[12:13], v[58:59]
	s_nop 0
	v_cvt_pk_bf16_f32 v67, v12, v13
	v_lshlrev_b64 v[12:13], 13, v[80:81]
	v_lshl_add_u64 v[12:13], v[74:75], 0, v[12:13]
	v_pk_mul_f32 v[58:59], v[38:39], v[60:61]
	global_store_dwordx4 v[12:13], v[64:67], off sc1
	v_lshlrev_b32_e32 v12, 16, v6
	v_and_b32_e32 v13, 0xffff0000, v6
	v_pk_fma_f32 v[56:57], v[46:47], v[56:57], v[58:59]
	s_nop 0
	v_pk_fma_f32 v[56:57], v[34:35], v[12:13], v[56:57]
	s_nop 0
	v_pk_add_f32 v[56:57], v[42:43], v[56:57]
	s_nop 0
	v_mul_f32_e32 v0, 0xbfb8aa3b, v56
	v_exp_f32_e32 v0, v0
	s_nop 0
	v_add_f32_e32 v0, 1.0, v0
	v_rcp_f32_e32 v58, v0
	v_mul_f32_e32 v0, 0xbfb8aa3b, v57
	v_exp_f32_e32 v0, v0
	s_nop 0
	v_add_f32_e32 v0, 1.0, v0
	v_rcp_f32_e32 v59, v0
	s_nop 0
	v_pk_mul_f32 v[56:57], v[56:57], v[58:59]
	v_pk_mul_f32 v[58:59], v[40:41], v[50:51]
	v_cvt_pk_bf16_f32 v6, v56, v57
	v_lshlrev_b32_e32 v56, 16, v7
	v_and_b32_e32 v57, 0xffff0000, v7
	v_pk_fma_f32 v[54:55], v[48:49], v[54:55], v[58:59]
	s_nop 0
	v_pk_fma_f32 v[54:55], v[36:37], v[56:57], v[54:55]
	s_nop 0
	v_pk_add_f32 v[54:55], v[44:45], v[54:55]
	s_nop 0
	v_mul_f32_e32 v0, 0xbfb8aa3b, v54
	v_exp_f32_e32 v0, v0
	s_nop 0
	v_add_f32_e32 v0, 1.0, v0
	v_rcp_f32_e32 v58, v0
	v_mul_f32_e32 v0, 0xbfb8aa3b, v55
	v_exp_f32_e32 v0, v0
	s_nop 0
	v_add_f32_e32 v0, 1.0, v0
	v_rcp_f32_e32 v59, v0
	s_nop 0
	v_pk_mul_f32 v[54:55], v[54:55], v[58:59]
	v_pk_mul_f32 v[58:59], v[18:19], v[32:33]
	v_cvt_pk_bf16_f32 v7, v54, v55
	v_lshlrev_b32_e32 v54, 16, v8
	v_and_b32_e32 v55, 0xffff0000, v8
	v_pk_fma_f32 v[52:53], v[22:23], v[52:53], v[58:59]
	s_nop 0
	v_pk_fma_f32 v[52:53], v[14:15], v[54:55], v[52:53]
	s_nop 0
	v_pk_add_f32 v[52:53], v[26:27], v[52:53]
	s_nop 0
	v_mul_f32_e32 v0, 0xbfb8aa3b, v52
	v_exp_f32_e32 v0, v0
	s_nop 0
	v_add_f32_e32 v0, 1.0, v0
	v_rcp_f32_e32 v58, v0
	v_mul_f32_e32 v0, 0xbfb8aa3b, v53
	v_exp_f32_e32 v0, v0
	s_nop 0
	v_add_f32_e32 v0, 1.0, v0
	v_rcp_f32_e32 v59, v0
	s_nop 0
	v_pk_mul_f32 v[52:53], v[52:53], v[58:59]
	v_pk_mul_f32 v[58:59], v[20:21], v[10:11]
	v_cvt_pk_bf16_f32 v8, v52, v53
	v_lshlrev_b32_e32 v52, 16, v9
	v_and_b32_e32 v53, 0xffff0000, v9
	v_pk_fma_f32 v[30:31], v[24:25], v[30:31], v[58:59]
	s_nop 0
	v_pk_fma_f32 v[30:31], v[16:17], v[52:53], v[30:31]
	s_nop 0
	v_pk_add_f32 v[30:31], v[28:29], v[30:31]
	s_nop 0
	v_mul_f32_e32 v0, 0xbfb8aa3b, v30
	v_exp_f32_e32 v0, v0
	s_nop 0
	v_add_f32_e32 v0, 1.0, v0
	v_rcp_f32_e32 v58, v0
	v_mul_f32_e32 v0, 0xbfb8aa3b, v31
	v_exp_f32_e32 v0, v0
	s_nop 0
	v_add_f32_e32 v0, 1.0, v0
	v_rcp_f32_e32 v59, v0
	s_nop 0
	v_pk_mul_f32 v[30:31], v[30:31], v[58:59]
	s_nop 0
	v_cvt_pk_bf16_f32 v9, v30, v31
	v_lshlrev_b64 v[30:31], 13, v[78:79]
	v_lshl_add_u64 v[30:31], v[74:75], 0, v[30:31]
	global_store_dwordx4 v[30:31], v[6:9], off sc1
	s_nop 1
	v_pk_mul_f32 v[6:7], v[38:39], v[12:13]
	v_lshlrev_b32_e32 v8, 16, v2
	v_pk_fma_f32 v[6:7], v[46:47], v[60:61], v[6:7]
	v_and_b32_e32 v9, 0xffff0000, v2
	v_pk_fma_f32 v[6:7], v[34:35], v[8:9], v[6:7]
	s_nop 0
	v_pk_add_f32 v[6:7], v[42:43], v[6:7]
	s_nop 0
	v_mul_f32_e32 v0, 0xbfb8aa3b, v6
	v_exp_f32_e32 v0, v0
	s_nop 0
	v_add_f32_e32 v0, 1.0, v0
	v_rcp_f32_e32 v8, v0
	v_mul_f32_e32 v0, 0xbfb8aa3b, v7
	v_exp_f32_e32 v0, v0
	s_nop 0
	v_add_f32_e32 v0, 1.0, v0
	v_rcp_f32_e32 v9, v0
	s_nop 0
	v_pk_mul_f32 v[6:7], v[6:7], v[8:9]
	s_nop 0
	v_cvt_pk_bf16_f32 v2, v6, v7
	v_pk_mul_f32 v[6:7], v[40:41], v[56:57]
	v_lshlrev_b32_e32 v8, 16, v3
	v_pk_fma_f32 v[6:7], v[48:49], v[50:51], v[6:7]
	v_and_b32_e32 v9, 0xffff0000, v3
	v_pk_fma_f32 v[6:7], v[36:37], v[8:9], v[6:7]
	s_nop 0
	v_pk_add_f32 v[6:7], v[44:45], v[6:7]
	s_nop 0
	v_mul_f32_e32 v0, 0xbfb8aa3b, v6
	v_exp_f32_e32 v0, v0
	s_nop 0
	v_add_f32_e32 v0, 1.0, v0
	v_rcp_f32_e32 v8, v0
	v_mul_f32_e32 v0, 0xbfb8aa3b, v7
	v_exp_f32_e32 v0, v0
	s_nop 0
	v_add_f32_e32 v0, 1.0, v0
	v_rcp_f32_e32 v9, v0
	s_nop 0
	v_pk_mul_f32 v[6:7], v[6:7], v[8:9]
	s_nop 0
	v_cvt_pk_bf16_f32 v3, v6, v7
	v_pk_mul_f32 v[6:7], v[18:19], v[54:55]
	v_lshlrev_b32_e32 v8, 16, v4
	v_pk_fma_f32 v[6:7], v[22:23], v[32:33], v[6:7]
	v_and_b32_e32 v9, 0xffff0000, v4
	v_pk_fma_f32 v[6:7], v[14:15], v[8:9], v[6:7]
	s_nop 0
	v_pk_add_f32 v[6:7], v[26:27], v[6:7]
	s_nop 0
	v_mul_f32_e32 v0, 0xbfb8aa3b, v6
	v_exp_f32_e32 v0, v0
	s_nop 0
	v_add_f32_e32 v0, 1.0, v0
	v_rcp_f32_e32 v8, v0
	v_mul_f32_e32 v0, 0xbfb8aa3b, v7
	v_exp_f32_e32 v0, v0
	s_nop 0
	v_add_f32_e32 v0, 1.0, v0
	v_rcp_f32_e32 v9, v0
	s_nop 0
	v_pk_mul_f32 v[6:7], v[6:7], v[8:9]
	s_nop 0
	v_cvt_pk_bf16_f32 v4, v6, v7
	v_pk_mul_f32 v[6:7], v[20:21], v[52:53]
	v_lshlrev_b32_e32 v8, 16, v5
	v_pk_fma_f32 v[6:7], v[24:25], v[10:11], v[6:7]
	v_and_b32_e32 v9, 0xffff0000, v5
	v_pk_fma_f32 v[6:7], v[16:17], v[8:9], v[6:7]
	s_nop 0
	v_pk_add_f32 v[6:7], v[28:29], v[6:7]
	s_nop 0
	v_mul_f32_e32 v0, 0xbfb8aa3b, v6
	v_exp_f32_e32 v0, v0
	s_nop 0
	v_add_f32_e32 v0, 1.0, v0
	v_rcp_f32_e32 v8, v0
	v_mul_f32_e32 v0, 0xbfb8aa3b, v7
	v_exp_f32_e32 v0, v0
	s_nop 0
	v_add_f32_e32 v0, 1.0, v0
	v_rcp_f32_e32 v9, v0
	s_nop 0
	v_pk_mul_f32 v[6:7], v[6:7], v[8:9]
	s_nop 0
	v_cvt_pk_bf16_f32 v5, v6, v7
	v_lshlrev_b64 v[6:7], 13, v[76:77]
	v_lshl_add_u64 v[6:7], v[74:75], 0, v[6:7]
	global_store_dwordx4 v[6:7], v[2:5], off sc1
	s_branch .LBB0_182

.LBB0_917:
	s_ashr_i32 s4, s3, 3
	s_mul_hi_i32 s5, s4, 0x7e07e07f
	s_lshr_b32 s6, s5, 31
	s_ashr_i32 s5, s5, 7
	s_add_i32 s5, s5, s6
	s_mulk_i32 s5, 0x104
	s_sub_i32 s6, s4, s5
	s_mul_hi_i32 s4, s3, 0x7e07e07f
	s_lshr_b32 s5, s4, 31
	s_ashr_i32 s4, s4, 10
	s_and_b32 s50, s2, 0x1c0
	s_add_i32 s7, s4, s5
	v_lshl_add_u64 v[4:5], s[50:51], 0, v[2:3]
	v_mov_b32_e32 v9, 0x600
	v_mad_i64_i32 v[4:5], s[4:5], s7, v9, v[4:5]
	v_mov_b64_e32 v[10:11], s[38:39]
	v_mad_u64_u32 v[10:11], s[4:5], v4, s8, v[10:11]
	s_lshl_b32 s4, s6, 6
	v_mad_i32_i24 v11, v5, s8, v11
	s_ashr_i32 s5, s4, 31
	v_lshl_add_u64 v[4:5], s[4:5], 1, v[10:11]
	v_lshl_add_u64 v[4:5], v[4:5], 0, v[0:1]
	s_waitcnt vmcnt(63) expcnt(7) lgkmcnt(15)
	s_barrier
	global_load_dwordx4 v[10:13], v[4:5], off
	s_mul_hi_i32 s6, s7, 0x4100
	s_mulk_i32 s7, 0x4100
	s_add_u32 s4, s4, s7
	s_addc_u32 s5, s5, s6
	s_lshl_b32 s50, s50, 1
	s_add_i32 s3, s3, s0
	s_add_i32 s2, s2, s1
	s_cmpk_gt_i32 s3, 0x103f
	s_waitcnt vmcnt(0)
	v_lshlrev_b32_e32 v4, 16, v10
	v_and_b32_e32 v5, 0xffff0000, v10
	ds_write2_b32 v6, v4, v5 offset1:1
	v_lshlrev_b32_e32 v4, 16, v11
	v_and_b32_e32 v5, 0xffff0000, v11
	ds_write2_b32 v6, v4, v5 offset0:2 offset1:3
	v_lshlrev_b32_e32 v4, 16, v12
	v_and_b32_e32 v5, 0xffff0000, v12
	ds_write2_b32 v6, v4, v5 offset0:4 offset1:5
	v_lshlrev_b32_e32 v4, 16, v13
	v_and_b32_e32 v5, 0xffff0000, v13
	ds_write2_b32 v6, v4, v5 offset0:6 offset1:7
	v_lshl_add_u64 v[4:5], s[4:5], 0, v[2:3]
	v_lshlrev_b64 v[10:11], 10, v[4:5]
	v_lshl_add_u64 v[10:11], s[42:43], 0, v[10:11]
	v_lshl_add_u64 v[10:11], v[10:11], 0, s[50:51]
	v_lshl_add_u64 v[10:11], v[10:11], 0, v[0:1]
	s_waitcnt lgkmcnt(0)
	s_barrier
	global_load_dwordx4 v[10:13], v[10:11], off
	ds_read2_b32 v[14:15], v7 offset1:130
	ds_read2_b32 v[16:17], v8 offset0:65 offset1:195
	v_lshlrev_b64 v[4:5], 11, v[4:5]
	v_lshl_add_u64 v[4:5], s[64:65], 0, v[4:5]
	v_lshl_add_u64 v[4:5], v[4:5], 0, s[50:51]
	v_lshl_add_u64 v[4:5], v[4:5], 0, v[0:1]
	s_waitcnt vmcnt(0)
	v_lshlrev_b32_e32 v18, 16, v10
	v_mul_f32_e32 v9, 0xbfb8aa3b, v18
	v_exp_f32_e32 v9, v9
	v_and_b32_e32 v19, 0xffff0000, v10
	v_add_f32_e32 v9, 1.0, v9
	v_rcp_f32_e32 v20, v9
	v_mul_f32_e32 v9, 0xbfb8aa3b, v19
	v_exp_f32_e32 v9, v9
	s_nop 0
	v_add_f32_e32 v9, 1.0, v9
	v_rcp_f32_e32 v21, v9
	s_nop 0
	v_pk_mul_f32 v[18:19], v[20:21], v[18:19]
	s_waitcnt lgkmcnt(1)
	v_mov_b32_e32 v20, v14
	s_waitcnt lgkmcnt(0)
	v_mov_b32_e32 v21, v16
	v_pk_mul_f32 v[18:19], v[20:21], v[18:19]
	v_mov_b32_e32 v16, v15
	v_cvt_pk_bf16_f32 v10, v18, v19
	v_lshlrev_b32_e32 v18, 16, v11
	v_mul_f32_e32 v9, 0xbfb8aa3b, v18
	v_exp_f32_e32 v9, v9
	v_and_b32_e32 v19, 0xffff0000, v11
	v_add_f32_e32 v9, 1.0, v9
	v_rcp_f32_e32 v20, v9
	v_mul_f32_e32 v9, 0xbfb8aa3b, v19
	v_exp_f32_e32 v9, v9
	s_nop 0
	v_add_f32_e32 v9, 1.0, v9
	v_rcp_f32_e32 v21, v9
	v_add_u32_e32 v9, 0x400, v7
	v_pk_mul_f32 v[18:19], v[20:21], v[18:19]
	s_nop 0
	v_pk_mul_f32 v[14:15], v[16:17], v[18:19]
	v_lshlrev_b32_e32 v18, 16, v12
	v_cvt_pk_bf16_f32 v11, v14, v15
	ds_read2_b32 v[14:15], v9 offset0:4 offset1:134
	v_add_u32_e32 v9, 0x400, v8
	ds_read2_b32 v[16:17], v9 offset0:69 offset1:199
	v_mul_f32_e32 v9, 0xbfb8aa3b, v18
	v_exp_f32_e32 v9, v9
	v_and_b32_e32 v19, 0xffff0000, v12
	v_add_f32_e32 v9, 1.0, v9
	v_rcp_f32_e32 v20, v9
	v_mul_f32_e32 v9, 0xbfb8aa3b, v19
	v_exp_f32_e32 v9, v9
	s_nop 0
	v_add_f32_e32 v9, 1.0, v9
	v_rcp_f32_e32 v21, v9
	s_nop 0
	v_pk_mul_f32 v[18:19], v[20:21], v[18:19]
	s_waitcnt lgkmcnt(1)
	v_mov_b32_e32 v20, v14
	s_waitcnt lgkmcnt(0)
	v_mov_b32_e32 v21, v16
	v_pk_mul_f32 v[18:19], v[20:21], v[18:19]
	v_mov_b32_e32 v16, v15
	v_cvt_pk_bf16_f32 v12, v18, v19
	v_lshlrev_b32_e32 v18, 16, v13
	v_mul_f32_e32 v9, 0xbfb8aa3b, v18
	v_exp_f32_e32 v9, v9
	v_and_b32_e32 v19, 0xffff0000, v13
	v_add_f32_e32 v9, 1.0, v9
	v_rcp_f32_e32 v20, v9
	v_mul_f32_e32 v9, 0xbfb8aa3b, v19
	v_exp_f32_e32 v9, v9
	s_nop 0
	v_add_f32_e32 v9, 1.0, v9
	v_rcp_f32_e32 v21, v9
	s_nop 0
	v_pk_mul_f32 v[18:19], v[20:21], v[18:19]
	s_nop 0
	v_pk_mul_f32 v[14:15], v[16:17], v[18:19]
	s_nop 0
	v_cvt_pk_bf16_f32 v13, v14, v15
	global_store_dwordx4 v[4:5], v[10:13], off sc1
	s_cbranch_scc0 .LBB0_917

.LBB0_990:
	s_or_b64 exec, exec, s[0:1]
	s_waitcnt vmcnt(1)
	v_and_b32_e32 v21, 0xffff0000, v6
	v_lshlrev_b32_e32 v8, 16, v6
	v_fma_f32 v6, v12, v18, v15
	v_and_b32_e32 v9, 0xffff0000, v7
	v_lshlrev_b32_e32 v7, 16, v7
	v_fmac_f32_e32 v6, v13, v8
	v_fma_f32 v8, v12, v8, v15
	v_fma_f32 v22, v12, v21, v15
	v_fmac_f32_e32 v8, v13, v21
	v_fmac_f32_e32 v22, v13, v7
	v_fma_f32 v24, v12, v7, v15
	v_fmac_f32_e32 v8, v14, v7
	v_fmac_f32_e32 v22, v14, v9
	v_fmac_f32_e32 v24, v13, v9
	s_waitcnt vmcnt(0)
	v_lshlrev_b32_e32 v9, 16, v10
	v_fma_f32 v7, v12, v20, v15
	v_and_b32_e32 v18, 0xffff0000, v10
	v_fmac_f32_e32 v7, v13, v9
	v_fma_f32 v9, v12, v9, v15
	v_readlane_b32 s64, v251, 2
	v_fmac_f32_e32 v24, v14, v17
	v_and_b32_e32 v17, 0xffff0000, v11
	v_lshlrev_b32_e32 v11, 16, v11
	v_fmac_f32_e32 v9, v13, v18
	v_fma_f32 v23, v12, v18, v15
	v_readlane_b32 s78, v251, 16
	v_readlane_b32 s79, v251, 17
	v_fmac_f32_e32 v9, v14, v11
	v_fmac_f32_e32 v23, v13, v11
	v_fma_f32 v25, v12, v11, v15
	v_lshl_add_u64 v[10:11], s[78:79], 0, v[4:5]
	s_mov_b32 s0, 0x16a20000
	v_add_co_u32_e32 v10, vcc, s0, v10
	s_mov_b64 s[0:1], 0x1000
	v_fmac_f32_e32 v6, v14, v21
	v_fmac_f32_e32 v7, v14, v18
	v_fmac_f32_e32 v25, v13, v17
	v_addc_co_u32_e32 v11, vcc, 0, v11, vcc
	v_lshl_add_u64 v[2:3], v[2:3], 0, s[0:1]
	s_movk_i32 s0, 0x37ff
	v_fmac_f32_e32 v23, v14, v17
	v_fmac_f32_e32 v25, v14, v19
	global_store_dwordx4 v[10:11], v[6:9], off sc1
	global_store_dwordx4 v[10:11], v[22:25], off offset:16 sc1
	ds_write_b128 v16, v[6:9]
	ds_write_b128 v16, v[22:25] offset:16
	v_add_u32_e32 v6, 0x800, v0
	v_cmp_lt_i32_e32 vcc, s0, v0
	v_add_u32_e32 v16, 0x4000, v16
	v_lshl_add_u64 v[4:5], v[4:5], 0, s[88:89]
	s_or_b64 s[24:25], vcc, s[24:25]
	v_mov_b32_e32 v0, v6
	v_readlane_b32 s65, v251, 3
	v_readlane_b32 s66, v251, 4
	v_readlane_b32 s67, v251, 5
	v_readlane_b32 s68, v251, 6
	v_readlane_b32 s69, v251, 7
	v_readlane_b32 s70, v251, 8
	v_readlane_b32 s71, v251, 9
	v_readlane_b32 s72, v251, 10
	v_readlane_b32 s73, v251, 11
	v_readlane_b32 s74, v251, 12
	v_readlane_b32 s75, v251, 13
	v_readlane_b32 s76, v251, 14
	v_readlane_b32 s77, v251, 15
	s_andn2_b64 exec, exec, s[24:25]
	s_cbranch_execz .LBB0_999

.LBB0_1042:
	v_add_u32_e32 v0, 1, v10
	ds_read_b128 v[12:15], v7
	ds_read_b128 v[16:19], v7 offset:16
	v_cvt_f32_i32_e32 v8, v0
	v_cvt_f32_i32_e32 v9, v10
	s_mov_b64 s[2:3], 0x20000
	s_waitcnt lgkmcnt(1)
	global_store_dwordx4 v[2:3], v[12:15], off sc1
	s_waitcnt lgkmcnt(0)
	global_store_dwordx4 v[2:3], v[16:19], off offset:16 sc1
	v_pk_mul_f32 v[8:9], v[8:9], s[38:39] op_sel_hi:[1,0]
	v_lshl_add_u64 v[4:5], v[2:3], 0, s[2:3]
	v_and_b32_e32 v13, 0x7fffffff, v9
	v_and_b32_e32 v12, 0x7fffffff, v8
	v_pk_mul_f32 v[14:15], v[12:13], 0.5 op_sel_hi:[1,0]
	v_cmp_gt_f32_e64 s[2:3], |v9|, 1.0
	v_fract_f32_e32 v0, v15
	v_add_f32_e32 v0, v0, v0
	v_cmp_neq_f32_e32 vcc, s24, v15
	v_xor_b32_e32 v13, v13, v9
	v_xor_b32_e32 v12, v12, v8
	v_cndmask_b32_e32 v0, 0, v0, vcc
	v_cndmask_b32_e64 v0, |v9|, v0, s[2:3]
	v_add_f32_e32 v6, v0, v0
	v_rndne_f32_e32 v6, v6
	v_fmac_f32_e32 v0, -0.5, v6
	v_mul_f32_e32 v11, v0, v0
	v_fmamk_f32 v15, v11, 0x3e75aa41, v197
	v_fmaak_f32 v15, v11, v15, 0x40234736
	v_fmaak_f32 v15, v11, v15, 0xc0a55e0e
	v_mul_f32_e32 v16, v0, v11
	v_mul_f32_e32 v15, v16, v15
	v_cvt_i32_f32_e32 v6, v6
	v_fmac_f32_e32 v15, 0x40490fdb, v0
	v_fmamk_f32 v0, v11, 0x3d4be544, v198
	v_fmaak_f32 v0, v11, v0, 0xbfaad1da
	v_fmaak_f32 v0, v11, v0, 0x4081e0d3
	v_fmaak_f32 v0, v11, v0, 0xc09de9e6
	v_fma_f32 v0, v11, v0, 1.0
	v_lshlrev_b32_e32 v11, 30, v6
	v_and_b32_e32 v6, 1, v6
	v_cmp_eq_u32_e32 vcc, 0, v6
	v_and_b32_e32 v16, 0x80000000, v11
	v_cmp_gt_f32_e64 s[2:3], |v8|, 1.0
	v_cndmask_b32_e32 v6, v0, v15, vcc
	v_xor_b32_e32 v6, v13, v6
	v_xor_b32_e32 v13, 0x80000000, v15
	v_cndmask_b32_e32 v0, v13, v0, vcc
	v_xor_b32_e32 v6, v6, v16
	v_bitop3_b32 v0, v0, v11, s30 bitop3:0x78
	v_cmp_class_f32_e64 vcc, v9, s26
	v_fract_f32_e32 v9, v14
	v_add_f32_e32 v9, v9, v9
	v_cndmask_b32_e32 v0, v218, v0, vcc
	v_cndmask_b32_e64 v6, v217, -v6, vcc
	v_cmp_neq_f32_e32 vcc, s24, v14
	s_nop 1
	v_cndmask_b32_e32 v9, 0, v9, vcc
	v_cndmask_b32_e64 v9, |v8|, v9, s[2:3]
	v_add_f32_e32 v11, v9, v9
	v_rndne_f32_e32 v11, v11
	v_fmac_f32_e32 v9, -0.5, v11
	v_mul_f32_e32 v13, v9, v9
	v_fmamk_f32 v14, v13, 0x3e75aa41, v197
	v_fmaak_f32 v14, v13, v14, 0x40234736
	v_fmaak_f32 v14, v13, v14, 0xc0a55e0e
	v_mul_f32_e32 v15, v9, v13
	v_mul_f32_e32 v14, v15, v14
	v_cvt_i32_f32_e32 v11, v11
	v_fmac_f32_e32 v14, 0x40490fdb, v9
	v_fmamk_f32 v9, v13, 0x3d4be544, v198
	v_fmaak_f32 v9, v13, v9, 0xbfaad1da
	v_fmaak_f32 v9, v13, v9, 0x4081e0d3
	v_fmaak_f32 v9, v13, v9, 0xc09de9e6
	v_fma_f32 v9, v13, v9, 1.0
	v_lshlrev_b32_e32 v13, 30, v11
	v_and_b32_e32 v11, 1, v11
	v_cmp_eq_u32_e32 vcc, 0, v11
	v_and_b32_e32 v15, 0x80000000, v13
	s_nop 0
	v_cndmask_b32_e32 v11, v9, v14, vcc
	v_xor_b32_e32 v11, v12, v11
	v_xor_b32_e32 v12, 0x80000000, v14
	v_cndmask_b32_e32 v9, v12, v9, vcc
	v_xor_b32_e32 v11, v11, v15
	v_bitop3_b32 v9, v9, v13, s30 bitop3:0x78
	v_cmp_class_f32_e64 vcc, v8, s26
	s_nop 1
	v_cndmask_b32_e32 v8, v218, v9, vcc
	v_cndmask_b32_e64 v12, v217, -v11, vcc
	v_or_b32_e32 v9, 2, v10
	v_or_b32_e32 v11, 3, v10
	v_cvt_f32_i32_e32 v15, v9
	v_cvt_f32_i32_e32 v14, v11
	v_pk_mul_f32 v[18:19], v[14:15], s[38:39] op_sel_hi:[1,0]
	s_nop 0
	v_and_b32_e32 v21, 0x7fffffff, v19
	v_and_b32_e32 v20, 0x7fffffff, v18
	v_pk_mul_f32 v[22:23], v[20:21], 0.5 op_sel_hi:[1,0]
	v_cmp_gt_f32_e64 s[2:3], |v19|, 1.0
	v_fract_f32_e32 v9, v23
	v_add_f32_e32 v9, v9, v9
	v_cmp_neq_f32_e32 vcc, s24, v23
	v_xor_b32_e32 v16, v21, v19
	s_nop 0
	v_cndmask_b32_e32 v9, 0, v9, vcc
	v_cndmask_b32_e64 v9, |v19|, v9, s[2:3]
	v_add_f32_e32 v11, v9, v9
	v_rndne_f32_e32 v11, v11
	v_fmac_f32_e32 v9, -0.5, v11
	v_mul_f32_e32 v13, v9, v9
	v_fmamk_f32 v14, v13, 0x3e75aa41, v197
	v_fmaak_f32 v14, v13, v14, 0x40234736
	v_fmaak_f32 v14, v13, v14, 0xc0a55e0e
	v_mul_f32_e32 v15, v9, v13
	v_mul_f32_e32 v14, v15, v14
	v_cvt_i32_f32_e32 v11, v11
	v_fmac_f32_e32 v14, 0x40490fdb, v9
	v_fmamk_f32 v9, v13, 0x3d4be544, v198
	v_fmaak_f32 v9, v13, v9, 0xbfaad1da
	v_fmaak_f32 v9, v13, v9, 0x4081e0d3
	v_fmaak_f32 v9, v13, v9, 0xc09de9e6
	v_fma_f32 v9, v13, v9, 1.0
	v_lshlrev_b32_e32 v13, 30, v11
	v_and_b32_e32 v11, 1, v11
	v_cmp_eq_u32_e32 vcc, 0, v11
	v_and_b32_e32 v15, 0x80000000, v13
	v_cmp_gt_f32_e64 s[2:3], |v18|, 1.0
	v_cndmask_b32_e32 v11, v9, v14, vcc
	v_xor_b32_e32 v14, 0x80000000, v14
	v_cndmask_b32_e32 v9, v14, v9, vcc
	v_xor_b32_e32 v11, v16, v11
	v_bitop3_b32 v9, v9, v13, s30 bitop3:0x78
	v_cmp_class_f32_e64 vcc, v19, s26
	v_xor_b32_e32 v11, v11, v15
	v_xor_b32_e32 v19, v20, v18
	v_cndmask_b32_e32 v14, v218, v9, vcc
	v_fract_f32_e32 v9, v22
	v_cndmask_b32_e64 v16, v217, -v11, vcc
	v_add_f32_e32 v9, v9, v9
	v_cmp_neq_f32_e32 vcc, s24, v22
	s_nop 1
	v_cndmask_b32_e32 v9, 0, v9, vcc
	v_cndmask_b32_e64 v9, |v18|, v9, s[2:3]
	v_add_f32_e32 v11, v9, v9
	v_rndne_f32_e32 v11, v11
	v_fmac_f32_e32 v9, -0.5, v11
	v_mul_f32_e32 v13, v9, v9
	v_fmamk_f32 v15, v13, 0x3e75aa41, v197
	v_fmaak_f32 v15, v13, v15, 0x40234736
	v_fmaak_f32 v15, v13, v15, 0xc0a55e0e
	v_mul_f32_e32 v17, v9, v13
	v_mul_f32_e32 v15, v17, v15
	v_cvt_i32_f32_e32 v11, v11
	v_fmac_f32_e32 v15, 0x40490fdb, v9
	v_fmamk_f32 v9, v13, 0x3d4be544, v198
	v_fmaak_f32 v9, v13, v9, 0xbfaad1da
	v_fmaak_f32 v9, v13, v9, 0x4081e0d3
	v_fmaak_f32 v9, v13, v9, 0xc09de9e6
	v_fma_f32 v9, v13, v9, 1.0
	v_lshlrev_b32_e32 v13, 30, v11
	v_and_b32_e32 v11, 1, v11
	v_cmp_eq_u32_e32 vcc, 0, v11
	v_and_b32_e32 v17, 0x80000000, v13
	s_nop 0
	v_cndmask_b32_e32 v11, v9, v15, vcc
	v_xor_b32_e32 v15, 0x80000000, v15
	v_xor_b32_e32 v11, v19, v11
	v_cndmask_b32_e32 v9, v15, v9, vcc
	v_xor_b32_e32 v11, v11, v17
	v_bitop3_b32 v9, v9, v13, s30 bitop3:0x78
	v_cmp_class_f32_e64 vcc, v18, s26
	s_nop 1
	v_cndmask_b32_e32 v18, v218, v9, vcc
	v_cndmask_b32_e64 v20, v217, -v11, vcc
	v_add_co_u32_e32 v22, vcc, s9, v2
	s_nop 1
	v_addc_co_u32_e32 v23, vcc, 0, v3, vcc
	global_load_dwordx4 v[22:25], v[22:23], off
	s_nop 0
	global_load_dwordx4 v[26:29], v[4:5], off offset:16
	v_cmp_lt_i32_e32 vcc, s25, v10
	v_lshl_add_u64 v[2:3], v[2:3], 0, s[88:89]
	s_or_b64 s[0:1], vcc, s[0:1]
	s_waitcnt vmcnt(1)
	v_pk_mul_f32 v[4:5], v[22:23], v[6:7] op_sel:[1,0] op_sel_hi:[0,0]
	v_pk_mul_f32 v[12:13], v[24:25], v[12:13] op_sel:[1,0] op_sel_hi:[0,0]
	v_pk_fma_f32 v[30:31], v[22:23], v[0:1], v[4:5] neg_lo:[0,0,1] neg_hi:[0,0,1]
	v_pk_fma_f32 v[4:5], v[22:23], v[0:1], v[4:5] op_sel_hi:[1,0,1]
	v_pk_fma_f32 v[32:33], v[24:25], v[8:9], v[12:13] neg_lo:[0,0,1] neg_hi:[0,0,1]
	v_pk_fma_f32 v[8:9], v[24:25], v[8:9], v[12:13] op_sel_hi:[1,0,1]
	v_mov_b32_e32 v31, v5
	v_mov_b32_e32 v33, v9
	s_waitcnt vmcnt(0)
	v_pk_mul_f32 v[4:5], v[26:27], v[16:17] op_sel:[1,0] op_sel_hi:[0,0]
	v_pk_mul_f32 v[8:9], v[28:29], v[20:21] op_sel:[1,0] op_sel_hi:[0,0]
	v_pk_fma_f32 v[12:13], v[26:27], v[14:15], v[4:5] neg_lo:[0,0,1] neg_hi:[0,0,1]
	v_pk_fma_f32 v[4:5], v[26:27], v[14:15], v[4:5] op_sel_hi:[1,0,1]
	v_pk_fma_f32 v[14:15], v[28:29], v[18:19], v[8:9] neg_lo:[0,0,1] neg_hi:[0,0,1]
	v_pk_fma_f32 v[8:9], v[28:29], v[18:19], v[8:9] op_sel_hi:[1,0,1]
	v_mov_b32_e32 v13, v5
	v_mov_b32_e32 v15, v9
	v_add_u32_e32 v0, 0x800, v10
	ds_write_b128 v7, v[30:33]
	ds_write_b128 v7, v[12:15] offset:16
	v_add_u32_e32 v7, 0x4000, v7
	v_mov_b32_e32 v10, v0
	s_andn2_b64 exec, exec, s[0:1]
	s_cbranch_execnz .LBB0_1042

.LBB0_1088:
	s_andn2_b64 vcc, exec, s[0:1]
	s_cbranch_vccnz .LBB0_1077
	v_add_co_u32_e32 v6, vcc, 0x16a20000, v36
	global_store_dwordx4 v[38:39], v[14:17], off sc1
	s_nop 0
	v_addc_co_u32_e32 v7, vcc, 0, v37, vcc
	global_store_dwordx4 v[6:7], v[2:5], off offset:16 sc1
	s_branch .LBB0_1077

.LBB0_1422:
	v_add_u32_e32 v0, 0x200, v0
	s_movk_i32 s4, 0x5dff
	v_cmp_lt_i32_e32 vcc, s4, v0
	global_store_dwordx4 v[26:27], v[2:5], off sc1
	s_or_b64 s[2:3], vcc, s[2:3]
	v_lshl_add_u64 v[26:27], v[26:27], 0, s[68:69]
	s_andn2_b64 exec, exec, s[2:3]
	s_cbranch_execnz .LBB0_1422

.LBB0_1425:
	s_andn2_b64 vcc, exec, s[0:1]
	s_cbranch_vccnz .LBB0_1366
	s_cmpk_gt_i32 s16, 0x3ff
	s_mov_b64 s[0:1], -1
	s_cbranch_scc0 .LBB0_1436
	s_cmpk_gt_u32 s16, 0x4ff
	s_cbranch_scc0 .LBB0_1433
	s_cmpk_gt_u32 s16, 0xb0f
	s_cbranch_scc0 .LBB0_1430
	s_lshl_b32 s0, s16, 2
	v_mov_b32_e32 v0, v179
	s_and_b32 s0, s0, 0x7fffffc0
	s_addk_i32 s0, 0xd3c0
	v_ashrrev_i32_e32 v7, 3, v0
	v_add_u32_e32 v2, s0, v7
	v_ashrrev_i32_e32 v3, 31, v2
	s_lshl_b32 s1, s16, 6
	v_lshlrev_b32_e32 v0, 3, v0
	v_lshlrev_b64 v[2:3], 12, v[2:3]
	s_and_b32 s2, s1, 0x3c0
	v_and_b32_e32 v46, 56, v0
	v_lshl_add_u64 v[2:3], s[44:45], 0, v[2:3]
	s_mov_b32 s5, s27
	s_lshl_b32 s4, s2, 2
	v_lshl_add_u64 v[2:3], v[2:3], 0, s[4:5]
	v_lshlrev_b32_e32 v0, 2, v46
	v_lshl_add_u64 v[26:27], v[2:3], 0, v[0:1]
	global_load_dwordx4 v[2:5], v[26:27], off
	global_load_dwordx4 v[42:45], v[26:27], off offset:16
	v_mul_lo_u32 v47, v7, s17
	v_lshlrev_b32_e32 v48, 2, v7
	v_add_u32_e32 v26, s2, v7
	v_mul_u32_u24_e32 v7, 0x104, v46
	v_add3_u32 v47, 32, v47, v0
	v_add3_u32 v7, 32, v7, v48
	v_add_u32_e32 v48, 0x400, v7
	v_ashrrev_i32_e32 v27, 31, v26
	v_readlane_b32 s2, v251, 22
	v_lshlrev_b64 v[26:27], 12, v[26:27]
	v_readlane_b32 s3, v251, 23
	s_mov_b32 s1, s27
	v_lshlrev_b32_e32 v0, 1, v46
	v_lshl_add_u64 v[26:27], s[2:3], 0, v[26:27]
	v_lshl_add_u64 v[26:27], s[0:1], 1, v[26:27]
	v_lshl_add_u64 v[26:27], v[26:27], 0, v[0:1]
	s_mov_b64 s[0:1], 0
	s_waitcnt vmcnt(1)
	ds_write2_b32 v47, v2, v3 offset1:1
	ds_write2_b32 v47, v4, v5 offset0:2 offset1:3
	s_waitcnt vmcnt(0)
	ds_write2_b32 v47, v42, v43 offset0:4 offset1:5
	ds_write2_b32 v47, v44, v45 offset0:6 offset1:7
	s_waitcnt lgkmcnt(0)
	s_barrier
	ds_read2_b32 v[2:3], v7 offset1:65
	ds_read2_b32 v[4:5], v7 offset0:130 offset1:195
	ds_read2_b32 v[42:43], v48 offset0:4 offset1:69
	ds_read2_b32 v[44:45], v48 offset0:134 offset1:199
	s_waitcnt lgkmcnt(3)
	v_cvt_pk_bf16_f32 v2, v2, v3
	s_waitcnt lgkmcnt(2)
	v_cvt_pk_bf16_f32 v3, v4, v5
	s_waitcnt lgkmcnt(1)
	v_cvt_pk_bf16_f32 v4, v42, v43
	s_waitcnt lgkmcnt(0)
	v_cvt_pk_bf16_f32 v5, v44, v45
	global_store_dwordx4 v[26:27], v[2:5], off sc1
	s_barrier
.LBB0_1430:
	s_andn2_b64 vcc, exec, s[0:1]
	s_cbranch_vccnz .LBB0_1432
	s_add_i32 s0, s16, 0xfb00
	s_and_b32 s1, s0, 0xffff
	s_mulk_i32 s1, 0x51d1
	s_lshr_b32 s1, s1, 16
	s_sub_i32 s2, s0, s1
	s_bfe_u32 s2, s2, 0xf0001
	s_add_i32 s2, s2, s1
	v_mov_b32_e32 v0, v179
	s_bfe_u32 s1, s2, 0xa0006
	v_readlane_b32 s52, v254, 39
	s_mulk_i32 s1, 0x61
	v_ashrrev_i32_e32 v7, 3, v0
	v_lshlrev_b32_e32 v0, 3, v0
	s_and_b32 s2, s2, 0xffc0
	v_readlane_b32 s62, v254, 49
	v_readlane_b32 s63, v254, 50
	s_sub_i32 s3, s0, s1
	v_and_b32_e32 v46, 56, v0
	v_add_u32_e32 v0, s2, v7
	v_mov_b64_e32 v[2:3], s[62:63]
	s_movk_i32 s0, 0x6100
	v_mad_i64_i32 v[2:3], s[0:1], v0, s0, v[2:3]
	s_lshl_b32 s0, s3, 6
	s_and_b32 s0, s0, 0xffc0
	s_mov_b32 s5, s27
	s_lshl_b32 s4, s0, 2
	v_lshl_add_u64 v[2:3], v[2:3], 0, s[4:5]
	v_lshlrev_b32_e32 v0, 2, v46
	v_lshl_add_u64 v[26:27], v[2:3], 0, v[0:1]
	global_load_dwordx4 v[2:5], v[26:27], off
	global_load_dwordx4 v[42:45], v[26:27], off offset:16
	v_mul_lo_u32 v26, v7, s17
	v_lshlrev_b32_e32 v27, 2, v7
	v_mul_u32_u24_e32 v47, 0x104, v46
	v_add3_u32 v48, 32, v26, v0
	v_add3_u32 v47, 32, v47, v27
	v_add_u32_e32 v49, 0x400, v47
	v_add_u32_e32 v26, s0, v7
	v_ashrrev_i32_e32 v27, 31, v26
	v_readlane_b32 s0, v251, 42
	v_lshlrev_b64 v[26:27], 11, v[26:27]
	v_readlane_b32 s1, v251, 43
	s_lshl_b32 s4, s2, 1
	v_lshlrev_b32_e32 v0, 1, v46
	v_lshl_add_u64 v[26:27], s[0:1], 0, v[26:27]
	v_lshl_add_u64 v[26:27], v[26:27], 0, s[4:5]
	v_lshl_add_u64 v[26:27], v[26:27], 0, v[0:1]
	v_readlane_b32 s53, v254, 40
	v_readlane_b32 s54, v254, 41
	v_readlane_b32 s55, v254, 42
	v_readlane_b32 s56, v254, 43
	v_readlane_b32 s57, v254, 44
	v_readlane_b32 s58, v254, 45
	v_readlane_b32 s59, v254, 46
	v_readlane_b32 s60, v254, 47
	v_readlane_b32 s61, v254, 48
	v_readlane_b32 s64, v254, 51
	v_readlane_b32 s65, v254, 52
	v_readlane_b32 s66, v254, 53
	v_readlane_b32 s67, v254, 54
	s_waitcnt vmcnt(1)
	ds_write2_b32 v48, v2, v3 offset1:1
	ds_write2_b32 v48, v4, v5 offset0:2 offset1:3
	s_waitcnt vmcnt(0)
	ds_write2_b32 v48, v42, v43 offset0:4 offset1:5
	ds_write2_b32 v48, v44, v45 offset0:6 offset1:7
	s_waitcnt lgkmcnt(0)
	s_barrier
	ds_read2_b32 v[2:3], v47 offset1:65
	ds_read2_b32 v[4:5], v47 offset0:130 offset1:195
	ds_read2_b32 v[42:43], v49 offset0:4 offset1:69
	ds_read2_b32 v[44:45], v49 offset0:134 offset1:199
	s_waitcnt lgkmcnt(3)
	v_cvt_pk_bf16_f32 v2, v2, v3
	s_waitcnt lgkmcnt(2)
	v_cvt_pk_bf16_f32 v3, v4, v5
	s_waitcnt lgkmcnt(1)
	v_cvt_pk_bf16_f32 v4, v42, v43
	s_waitcnt lgkmcnt(0)
	v_cvt_pk_bf16_f32 v5, v44, v45
	global_store_dwordx4 v[26:27], v[2:5], off sc1
	s_barrier

.LBB0_1433:
	s_andn2_b64 vcc, exec, s[0:1]
	s_cbranch_vccnz .LBB0_1435
	s_lshl_b32 s0, s16, 2
	v_mov_b32_e32 v0, v179
	s_and_b32 s0, s0, 0x1fc0
	s_addk_i32 s0, 0xf000
	v_ashrrev_i32_e32 v7, 3, v0
	v_add_u32_e32 v2, s0, v7
	v_ashrrev_i32_e32 v3, 31, v2
	v_readlane_b32 s52, v254, 23
	s_lshl_b32 s1, s16, 6
	v_lshlrev_b32_e32 v0, 3, v0
	v_lshlrev_b64 v[2:3], 12, v[2:3]
	v_readlane_b32 s53, v254, 24
	s_and_b32 s2, s1, 0x3c0
	v_and_b32_e32 v46, 56, v0
	v_lshl_add_u64 v[2:3], s[52:53], 0, v[2:3]
	s_mov_b32 s5, s27
	s_lshl_b32 s4, s2, 2
	v_lshl_add_u64 v[2:3], v[2:3], 0, s[4:5]
	v_lshlrev_b32_e32 v0, 2, v46
	v_lshl_add_u64 v[26:27], v[2:3], 0, v[0:1]
	global_load_dwordx4 v[2:5], v[26:27], off
	global_load_dwordx4 v[42:45], v[26:27], off offset:16
	v_mul_lo_u32 v47, v7, s17
	v_lshlrev_b32_e32 v48, 2, v7
	v_add_u32_e32 v26, s2, v7
	v_mul_u32_u24_e32 v7, 0x104, v46
	v_add3_u32 v47, 32, v47, v0
	v_add3_u32 v7, 32, v7, v48
	v_add_u32_e32 v48, 0x400, v7
	v_ashrrev_i32_e32 v27, 31, v26
	v_readlane_b32 s2, v251, 50
	v_lshlrev_b64 v[26:27], 11, v[26:27]
	v_readlane_b32 s3, v251, 51
	s_mov_b32 s1, s27
	v_lshlrev_b32_e32 v0, 1, v46
	v_lshl_add_u64 v[26:27], s[2:3], 0, v[26:27]
	v_lshl_add_u64 v[26:27], s[0:1], 1, v[26:27]
	v_lshl_add_u64 v[26:27], v[26:27], 0, v[0:1]
	v_readlane_b32 s54, v254, 25
	v_readlane_b32 s55, v254, 26
	v_readlane_b32 s56, v254, 27
	v_readlane_b32 s57, v254, 28
	v_readlane_b32 s58, v254, 29
	v_readlane_b32 s59, v254, 30
	v_readlane_b32 s60, v254, 31
	v_readlane_b32 s61, v254, 32
	v_readlane_b32 s62, v254, 33
	v_readlane_b32 s63, v254, 34
	v_readlane_b32 s64, v254, 35
	v_readlane_b32 s65, v254, 36
	v_readlane_b32 s66, v254, 37
	v_readlane_b32 s67, v254, 38
	s_waitcnt vmcnt(1)
	ds_write2_b32 v47, v2, v3 offset1:1
	ds_write2_b32 v47, v4, v5 offset0:2 offset1:3
	s_waitcnt vmcnt(0)
	ds_write2_b32 v47, v42, v43 offset0:4 offset1:5
	ds_write2_b32 v47, v44, v45 offset0:6 offset1:7
	s_waitcnt lgkmcnt(0)
	s_barrier
	ds_read2_b32 v[2:3], v7 offset1:65
	ds_read2_b32 v[4:5], v7 offset0:130 offset1:195
	ds_read2_b32 v[42:43], v48 offset0:4 offset1:69
	ds_read2_b32 v[44:45], v48 offset0:134 offset1:199
	s_waitcnt lgkmcnt(3)
	v_cvt_pk_bf16_f32 v2, v2, v3
	s_waitcnt lgkmcnt(2)
	v_cvt_pk_bf16_f32 v3, v4, v5
	s_waitcnt lgkmcnt(1)
	v_cvt_pk_bf16_f32 v4, v42, v43
	s_waitcnt lgkmcnt(0)
	v_cvt_pk_bf16_f32 v5, v44, v45
	global_store_dwordx4 v[26:27], v[2:5], off sc1
	s_barrier

.LBB0_1436:
	s_andn2_b64 vcc, exec, s[0:1]
	s_cbranch_vccnz .LBB0_1366
	s_ashr_i32 s0, s16, 31
	s_lshr_b32 s0, s0, 26
	s_add_i32 s0, s16, s0
	v_mov_b32_e32 v0, v179
	s_andn2_b32 s0, s0, 63
	s_sub_i32 s1, s16, s0
	v_ashrrev_i32_e32 v7, 3, v0
	v_add_u32_e32 v2, s0, v7
	v_ashrrev_i32_e32 v3, 31, v2
	v_readlane_b32 s68, v253, 47
	v_lshlrev_b32_e32 v0, 3, v0
	v_lshlrev_b64 v[2:3], 14, v[2:3]
	v_readlane_b32 s82, v253, 61
	v_readlane_b32 s83, v253, 62
	s_lshl_b32 s2, s1, 6
	v_and_b32_e32 v46, 56, v0
	v_lshl_add_u64 v[2:3], s[82:83], 0, v[2:3]
	s_ashr_i32 s3, s2, 31
	v_lshl_add_u64 v[2:3], s[2:3], 2, v[2:3]
	v_lshlrev_b32_e32 v0, 2, v46
	v_lshl_add_u64 v[26:27], v[2:3], 0, v[0:1]
	global_load_dwordx4 v[2:5], v[26:27], off
	global_load_dwordx4 v[42:45], v[26:27], off offset:16
	v_mul_lo_u32 v26, v7, s17
	v_lshlrev_b32_e32 v27, 2, v7
	v_mul_u32_u24_e32 v47, 0x104, v46
	v_add3_u32 v48, 32, v26, v0
	v_add3_u32 v47, 32, v47, v27
	v_add_u32_e32 v49, 0x400, v47
	v_add_u32_e32 v26, s2, v7
	v_ashrrev_i32_e32 v27, 31, v26
	v_lshlrev_b64 v[26:27], 11, v[26:27]
	s_ashr_i32 s1, s0, 31
	v_lshl_add_u64 v[26:27], s[50:51], 0, v[26:27]
	v_readlane_b32 s69, v253, 48
	v_readlane_b32 s80, v253, 59
	v_lshlrev_b32_e32 v0, 1, v46
	v_lshl_add_u64 v[26:27], s[0:1], 1, v[26:27]
	s_mov_b32 s80, 0x40234736
	s_mov_b64 s[68:69], 0x2000
	s_mov_b32 s82, 0xc0a55e0e
	v_lshl_add_u64 v[26:27], v[26:27], 0, v[0:1]
	v_readlane_b32 s70, v253, 49
	v_readlane_b32 s71, v253, 50
	v_readlane_b32 s72, v253, 51
	v_readlane_b32 s73, v253, 52
	v_readlane_b32 s74, v253, 53
	v_readlane_b32 s75, v253, 54
	v_readlane_b32 s76, v253, 55
	v_readlane_b32 s77, v253, 56
	v_readlane_b32 s78, v253, 57
	v_readlane_b32 s79, v253, 58
	v_readlane_b32 s81, v253, 60
	s_waitcnt vmcnt(1)
	ds_write2_b32 v48, v2, v3 offset1:1
	ds_write2_b32 v48, v4, v5 offset0:2 offset1:3
	s_waitcnt vmcnt(0)
	ds_write2_b32 v48, v42, v43 offset0:4 offset1:5
	ds_write2_b32 v48, v44, v45 offset0:6 offset1:7
	s_waitcnt lgkmcnt(0)
	s_barrier
	ds_read2_b32 v[2:3], v47 offset1:65
	ds_read2_b32 v[4:5], v47 offset0:130 offset1:195
	ds_read2_b32 v[42:43], v49 offset0:4 offset1:69
	ds_read2_b32 v[44:45], v49 offset0:134 offset1:199
	s_waitcnt lgkmcnt(3)
	v_cvt_pk_bf16_f32 v2, v2, v3
	s_waitcnt lgkmcnt(2)
	v_cvt_pk_bf16_f32 v3, v4, v5
	s_waitcnt lgkmcnt(1)
	v_cvt_pk_bf16_f32 v4, v42, v43
	s_waitcnt lgkmcnt(0)
	v_cvt_pk_bf16_f32 v5, v44, v45
	global_store_dwordx4 v[26:27], v[2:5], off sc1
	s_barrier
	s_branch .LBB0_1366
